# HGRN: ln(x) = log2(x)*ln2 with one multiply instead of the error-compensated product + infinity select (33 sites)
# speedup vs baseline: 1.0053x; 1.0053x over previous
; __device__ __forceinline__ bf16_t f2bf(float f) { return (bf16_t)(cvt_pk_bf16(f, 0.f) & 0xffffu); }
; __device__ __forceinline__ float bf2f(bf16_t b) { return __uint_as_float(((unsigned)b) << 16); }
; __device__ __forceinline__ float sigmoidf_(float x) { return 1.0f / (1.0f + __expf(-x)); }
; template <int MODE>
; __device__ __forceinline__ void hgrn_mfma(const Ctx& C, int l, int z, int b, int hd, int c, f32x4 (&Sacc)[4][4], float& dectot, unsigned char* wl, float lb) {
;     ...
;     for (int sc = 0; sc < 4; ++sc) {
;         float bacc = 0.f;
; #pragma unroll 1
;         for (int g8 = 0; g8 < 2; ++g8) {
;             bf16_t fv[16], qv[16], vv[16];
;             const int st0 = c * 128 + sc * 32 + g8 * 16; const int tq0 = z ? 4095 - st0 : st0;
;             const bf16_t* row0 = pa + (size_t)(b * SEQ + tq0) * 1280; const ptrdiff_t rstep = z ? -1280 : 1280;
; #pragma unroll
;             for (int t = 0; t < 16; ++t) { const bf16_t* row = row0 + rstep * t; fv[t] = row[fcol]; vv[t] = row[vcol]; if (MODE != 0) qv[t] = row[qcol]; }
; #pragma unroll
;             for (int t = 0; t < 16; ++t) {
;                 const float fl = bf2f(fv[t]);
;                 const float sg = sigmoidf_(fl);
;                 const float f = lb + (1.0f - lb) * sg, kk = (1.0f - lb) * (1.0f - sg);
;                 bacc += __logf(fmaxf(f, 1e-30f));
;                 Kb[(g8 * 16 + t) * HPT + lane] = f2bf(kk * __expf(fminf(-bacc, 80.f)));
;                 if (MODE != 0) Qt[(g8 * 16 + t) * HPT + lane] = f2bf(bf2f(qv[t]) * __expf(fmaxf(bacc, -80.f)));
;                 Vv[(g8 * 16 + t) * HPT + lane] = vv[t];
;             }
.LBB0_476:
	s_lshl_b32 s0, s70, 4
	s_or_b32 s6, s0, s67
	v_cndmask_b32_e64 v67, 0, 1, s[44:45]
	s_mul_i32 s1, s70, 0x480
	s_sub_i32 s7, 0xfff, s6
	v_cmp_ne_u32_e64 s[4:5], 1, v67
	v_or_b32_e32 v67, s1, v64
	s_and_b64 s[0:1], s[38:39], exec
	s_cselect_b32 s0, s6, s7
	s_add_i32 s0, s0, s68
	s_mul_i32 s36, s0, 0x500
	s_lshl_b64 s[0:1], s[36:37], 1
	s_add_u32 s0, s47, s0
	s_addc_u32 s1, s48, s1
	global_load_ushort v68, v132, s[0:1]
	global_load_ushort v69, v133, s[0:1] offset:1536
	s_add_u32 s0, s0, s42
	s_addc_u32 s1, s1, s43
	global_load_ushort v70, v132, s[0:1]
	global_load_ushort v71, v133, s[0:1] offset:1536
	s_add_u32 s0, s0, s42
	s_addc_u32 s1, s1, s43
	global_load_ushort v72, v132, s[0:1]
	global_load_ushort v73, v133, s[0:1] offset:1536
	s_add_u32 s0, s0, s42
	s_addc_u32 s1, s1, s43
	global_load_ushort v74, v132, s[0:1]
	global_load_ushort v75, v133, s[0:1] offset:1536
	s_add_u32 s0, s0, s42
	s_addc_u32 s1, s1, s43
	global_load_ushort v76, v132, s[0:1]
	global_load_ushort v77, v133, s[0:1] offset:1536
	s_add_u32 s0, s0, s42
	s_addc_u32 s1, s1, s43
	global_load_ushort v78, v132, s[0:1]
	global_load_ushort v79, v133, s[0:1] offset:1536
	s_add_u32 s0, s0, s42
	s_addc_u32 s1, s1, s43
	s_add_u32 s6, s0, s42
	s_addc_u32 s7, s1, s43
	global_load_ushort v80, v133, s[0:1] offset:1536
	global_load_ushort v81, v132, s[0:1]
	global_load_ushort v134, v133, s[6:7] offset:1536
	global_load_ushort v135, v132, s[6:7]
	s_add_u32 s0, s6, s42
	s_addc_u32 s1, s7, s43
	s_add_u32 s6, s0, s42
	global_load_ushort v136, v133, s[0:1] offset:1536
	global_load_ushort v137, v132, s[0:1]
	s_addc_u32 s7, s1, s43
	global_load_ushort v138, v133, s[6:7] offset:1536
	global_load_ushort v139, v132, s[6:7]
	s_add_u32 s0, s6, s42
	s_addc_u32 s1, s7, s43
	global_load_ushort v140, v133, s[0:1] offset:1536
	global_load_ushort v141, v132, s[0:1]
	s_add_u32 s6, s0, s42
	s_addc_u32 s7, s1, s43
	s_add_u32 s0, s6, s42
	global_load_ushort v142, v133, s[6:7] offset:1536
	global_load_ushort v143, v132, s[6:7]
	s_addc_u32 s1, s7, s43
	global_load_ushort v144, v133, s[0:1] offset:1536
	global_load_ushort v145, v132, s[0:1]
	s_add_u32 s6, s0, s42
	s_addc_u32 s7, s1, s43
	global_load_ushort v146, v133, s[6:7] offset:1536
	global_load_ushort v147, v132, s[6:7]
	s_add_u32 s0, s6, s42
	s_addc_u32 s1, s7, s43
	global_load_ushort v148, v133, s[0:1] offset:1536
	global_load_ushort v149, v132, s[0:1]
	s_add_u32 s6, s0, s42
	s_addc_u32 s7, s1, s43
	global_load_ushort v150, v133, s[6:7] offset:1536
	global_load_ushort v151, v132, s[6:7]
	v_lshl_add_u32 v67, v67, 1, s46
	s_mov_b64 s[44:45], 0
	s_mov_b32 s70, 1
	s_waitcnt vmcnt(31)
	v_lshlrev_b32_e32 v68, 16, v68
	v_mul_f32_e32 v68, 0xbfb8aa3b, v68
	v_exp_f32_e32 v68, v68
	s_waitcnt vmcnt(30)
	ds_write_b16 v67, v69 offset:9216
	s_waitcnt vmcnt(29)
	v_lshlrev_b32_e32 v69, 16, v70
	v_mul_f32_e32 v69, 0xbfb8aa3b, v69
	v_exp_f32_e32 v69, v69
	s_waitcnt vmcnt(27)
	v_lshlrev_b32_e32 v70, 16, v72
	v_mul_f32_e32 v70, 0xbfb8aa3b, v70
	v_add_f32_e32 v68, 1.0, v68
	ds_write_b16 v67, v71 offset:9360
	v_exp_f32_e32 v70, v70
	s_waitcnt vmcnt(25)
	v_lshlrev_b32_e32 v71, 16, v74
	v_mul_f32_e32 v71, 0xbfb8aa3b, v71
	v_add_f32_e32 v69, 1.0, v69
	v_exp_f32_e32 v71, v71
	s_waitcnt vmcnt(24)
	ds_write_b16 v67, v75 offset:9648
	s_waitcnt vmcnt(23)
	v_lshlrev_b32_e32 v75, 16, v76
	v_mul_f32_e32 v75, 0xbfb8aa3b, v75
	v_add_f32_e32 v70, 1.0, v70
	s_waitcnt vmcnt(21)
	v_lshlrev_b32_e32 v78, 16, v78
	v_exp_f32_e32 v75, v75
	s_waitcnt vmcnt(20)
	ds_write_b16 v67, v79 offset:9936
	v_mul_f32_e32 v78, 0xbfb8aa3b, v78
	ds_write_b16 v67, v73 offset:9504
	v_add_f32_e32 v71, 1.0, v71
	v_exp_f32_e32 v78, v78
	s_waitcnt vmcnt(19)
	ds_write_b16 v67, v80 offset:10080
	s_waitcnt vmcnt(16)
	v_lshlrev_b32_e32 v135, 16, v135
	ds_write_b16 v67, v134 offset:10224
	v_mul_f32_e32 v135, 0xbfb8aa3b, v135
	ds_write_b16 v67, v77 offset:9792
	v_lshlrev_b32_e32 v81, 16, v81
	v_add_f32_e32 v75, 1.0, v75
	v_exp_f32_e32 v135, v135
	v_mul_f32_e32 v81, 0xbfb8aa3b, v81
	v_add_f32_e32 v78, 1.0, v78
	s_waitcnt vmcnt(14)
	v_lshlrev_b32_e32 v137, 16, v137
	v_exp_f32_e32 v81, v81
	ds_write_b16 v67, v136 offset:10368
	v_mul_f32_e32 v137, 0xbfb8aa3b, v137
	v_exp_f32_e32 v137, v137
	s_waitcnt vmcnt(12)
	v_lshlrev_b32_e32 v139, 16, v139
	v_rcp_f32_e32 v68, v68
	v_mul_f32_e32 v74, 0xbfb8aa3b, v139
	v_fma_f32 v139, v131, v68, v130
	v_sub_f32_e32 v68, 1.0, v68
	v_add_f32_e32 v135, 1.0, v135
	v_mul_f32_e32 v76, v131, v68
	v_max_f32_e32 v68, 0xda24260, v139
	v_add_f32_e32 v81, 1.0, v81
	v_exp_f32_e32 v163, v74
	s_waitcnt vmcnt(10)
	v_lshlrev_b32_e32 v74, 16, v141
	v_rcp_f32_e32 v69, v69
	v_cmp_gt_f32_e64 s[0:1], s54, v68
	v_mul_f32_e32 v74, 0xbfb8aa3b, v74
	s_nop 0
	v_cndmask_b32_e64 v141, 0, 32, s[0:1]
	v_fma_f32 v152, v131, v69, v130
	v_sub_f32_e32 v69, 1.0, v69
	v_add_f32_e32 v137, 1.0, v137
	v_exp_f32_e32 v155, v74
	v_ldexp_f32 v68, v68, v141
	v_cndmask_b32_e64 v141, 0, v225, s[0:1]
	v_mul_f32_e32 v74, v131, v69
	v_max_f32_e32 v69, 0xda24260, v152
	v_rcp_f32_e32 v70, v70
	v_cmp_gt_f32_e64 s[0:1], s54, v69
	s_waitcnt vmcnt(8)
	v_lshlrev_b32_e32 v143, 16, v143
	v_log_f32_e32 v152, v68
	v_cndmask_b32_e64 v68, 0, 32, s[0:1]
	v_fma_f32 v154, v131, v70, v130
	v_add_f32_e32 v163, 1.0, v163
	v_mul_f32_e32 v143, 0xbfb8aa3b, v143
	v_sub_f32_e32 v70, 1.0, v70
	s_waitcnt vmcnt(7)
	ds_write_b16 v67, v144 offset:10944
	v_ldexp_f32 v68, v69, v68
	v_cndmask_b32_e64 v144, 0, v225, s[0:1]
	v_max_f32_e32 v69, 0xda24260, v154
	v_exp_f32_e32 v143, v143
	v_mul_f32_e32 v72, v131, v70
	v_rcp_f32_e32 v70, v71
	v_cmp_gt_f32_e64 s[0:1], s54, v69
	ds_write_b16 v67, v138 offset:10512
	s_waitcnt vmcnt(6)
; __device__ __forceinline__ bf16_t f2bf(float f) { return (bf16_t)(cvt_pk_bf16(f, 0.f) & 0xffffu); }
; __device__ __forceinline__ float bf2f(bf16_t b) { return __uint_as_float(((unsigned)b) << 16); }
; __device__ __forceinline__ float sigmoidf_(float x) { return 1.0f / (1.0f + __expf(-x)); }
; template <int MODE>
; __device__ __forceinline__ void hgrn_mfma(const Ctx& C, int l, int z, int b, int hd, int c, f32x4 (&Sacc)[4][4], float& dectot, unsigned char* wl, float lb) {
;     ...
;             for (int t = 0; t < 16; ++t) {
;                 const float fl = bf2f(fv[t]);
;                 const float sg = sigmoidf_(fl);
;                 const float f = lb + (1.0f - lb) * sg, kk = (1.0f - lb) * (1.0f - sg);
;                 bacc += __logf(fmaxf(f, 1e-30f));
;                 Kb[(g8 * 16 + t) * HPT + lane] = f2bf(kk * __expf(fminf(-bacc, 80.f)));
;                 if (MODE != 0) Qt[(g8 * 16 + t) * HPT + lane] = f2bf(bf2f(qv[t]) * __expf(fmaxf(bacc, -80.f)));
;                 Vv[(g8 * 16 + t) * HPT + lane] = vv[t];
;             }
	v_lshlrev_b32_e32 v145, 16, v145
	v_log_f32_e32 v158, v68
	v_cndmask_b32_e64 v68, 0, 32, s[0:1]
	v_fma_f32 v159, v131, v70, v130
	v_sub_f32_e32 v70, 1.0, v70
	v_add_f32_e32 v155, 1.0, v155
	v_mul_f32_e32 v145, 0xbfb8aa3b, v145
	s_waitcnt vmcnt(5)
	ds_write_b16 v67, v146 offset:11088
	v_ldexp_f32 v68, v69, v68
	v_cndmask_b32_e64 v146, 0, v225, s[0:1]
	v_mul_f32_e32 v71, v131, v70
	v_max_f32_e32 v69, 0xda24260, v159
	v_rcp_f32_e32 v70, v75
	v_exp_f32_e32 v145, v145
	s_waitcnt vmcnt(4)
	v_lshlrev_b32_e32 v147, 16, v147
	v_cmp_gt_f32_e64 s[0:1], s54, v69
	ds_write_b16 v67, v140 offset:10656
	v_mul_f32_e32 v147, 0xbfb8aa3b, v147
	v_log_f32_e32 v161, v68
	v_cndmask_b32_e64 v68, 0, 32, s[0:1]
	v_fma_f32 v166, v131, v70, v130
	v_sub_f32_e32 v70, 1.0, v70
	v_add_f32_e32 v143, 1.0, v143
	v_exp_f32_e32 v147, v147
	s_waitcnt vmcnt(3)
	ds_write_b16 v67, v148 offset:11232
	v_ldexp_f32 v68, v69, v68
	v_cndmask_b32_e64 v160, 0, v225, s[0:1]
	v_mul_f32_e32 v69, v131, v70
	v_max_f32_e32 v70, 0xda24260, v166
	ds_write_b16 v67, v142 offset:10800
	s_waitcnt vmcnt(2)
	v_lshlrev_b32_e32 v149, 16, v149
	v_rcp_f32_e32 v73, v78
	v_cmp_gt_f32_e64 s[0:1], s54, v70
	v_mul_f32_e32 v80, 0xbfb8aa3b, v149
	v_log_f32_e32 v167, v68
	v_cndmask_b32_e64 v68, 0, 32, s[0:1]
	v_fma_f32 v168, v131, v73, v130
	v_sub_f32_e32 v73, 1.0, v73
	v_add_f32_e32 v78, 1.0, v145
	v_exp_f32_e32 v80, v80
	s_waitcnt vmcnt(1)
	ds_write_b16 v67, v150 offset:11376
	v_ldexp_f32 v70, v70, v68
	v_cndmask_b32_e64 v150, 0, v225, s[0:1]
	v_mul_f32_e32 v68, v131, v73
	v_max_f32_e32 v73, 0xda24260, v168
	v_rcp_f32_e32 v77, v81
	s_waitcnt vmcnt(0)
	v_lshlrev_b32_e32 v145, 16, v151
	v_mul_f32_e32 v148, 0x3f317218, v152
	v_cmp_gt_f32_e64 s[0:1], s54, v73
	v_fma_f32 v168, v131, v77, v130
	v_sub_f32_e32 v170, 1.0, v77
	v_add_f32_e32 v77, 1.0, v147
	v_mul_f32_e32 v145, 0xbfb8aa3b, v145
	v_log_f32_e32 v162, v70
	v_cndmask_b32_e64 v70, 0, 32, s[0:1]
	v_sub_f32_e32 v141, v148, v141
	v_cndmask_b32_e64 v148, 0, v225, s[0:1]
	v_max_f32_e32 v152, 0xda24260, v168
	v_exp_f32_e32 v145, v145
	v_ldexp_f32 v73, v73, v70
	v_rcp_f32_e32 v75, v135
	v_add_f32_e32 v141, v66, v141
	v_mul_f32_e32 v66, 0x3f317218, v158
	v_cmp_gt_f32_e64 s[0:1], s54, v152
	v_log_f32_e32 v158, v73
	s_nop 0
	v_cndmask_b32_e64 v73, 0, 32, s[0:1]
	v_fma_f32 v168, v131, v75, v130
	v_sub_f32_e32 v75, 1.0, v75
	v_add_f32_e32 v79, 1.0, v80
	v_sub_f32_e32 v144, v66, v144
	v_ldexp_f32 v73, v152, v73
	v_cndmask_b32_e64 v152, 0, v225, s[0:1]
	v_mul_f32_e32 v66, v131, v75
	v_max_f32_e32 v75, 0xda24260, v168
	v_rcp_f32_e32 v134, v137
	v_min_f32_e64 v80, -v141, s60
	v_cmp_gt_f32_e64 s[0:1], s54, v75
	v_mul_f32_e32 v70, v131, v170
	v_mul_f32_e32 v168, 0x3fb8aa3b, v80
	v_add_f32_e32 v141, v141, v144
	v_mul_f32_e32 v144, 0x3f317218, v161
	v_log_f32_e32 v161, v73
	v_cndmask_b32_e64 v73, 0, 32, s[0:1]
	v_fma_f32 v171, v131, v134, v130
	v_sub_f32_e32 v134, 1.0, v134
	v_add_f32_e32 v80, 1.0, v145
	v_sub_f32_e32 v144, v144, v146
	v_ldexp_f32 v75, v75, v73
	v_cndmask_b32_e64 v147, 0, v225, s[0:1]
	v_mul_f32_e32 v73, v131, v134
	v_max_f32_e32 v134, 0xda24260, v171
	v_exp_f32_e32 v145, v168
	v_min_f32_e64 v168, -v141, s60
	v_rcp_f32_e32 v81, v163
	v_add_f32_e32 v141, v141, v144
	v_mul_f32_e32 v144, 0x3f317218, v167
	v_cmp_gt_f32_e64 s[0:1], s54, v134
	v_mul_f32_e32 v168, 0x3fb8aa3b, v168
	v_log_f32_e32 v167, v75
	v_cndmask_b32_e64 v75, 0, 32, s[0:1]
	v_fma_f32 v171, v131, v81, v130
	v_sub_f32_e32 v81, 1.0, v81
	v_sub_f32_e32 v144, v144, v160
	v_exp_f32_e32 v168, v168
	v_min_f32_e64 v172, -v141, s60
	v_ldexp_f32 v134, v134, v75
	v_mul_f32_e32 v75, v131, v81
	v_max_f32_e32 v81, 0xda24260, v171
	v_add_f32_e32 v141, v141, v144
	v_mul_f32_e32 v144, 0x3f317218, v162
	v_cndmask_b32_e64 v160, 0, v225, s[0:1]
	v_rcp_f32_e32 v135, v155
	v_cmp_gt_f32_e64 s[0:1], s54, v81
	v_mul_f32_e32 v156, 0x3fb8aa3b, v172
	v_log_f32_e32 v134, v134
	v_cndmask_b32_e64 v162, 0, 32, s[0:1]
	v_fma_f32 v166, v131, v135, v130
	v_sub_f32_e32 v135, 1.0, v135
	v_mul_f32_e32 v145, v76, v145
	v_sub_f32_e32 v144, v144, v150
	v_rcp_f32_e32 v137, v143
	v_exp_f32_e32 v156, v156
	v_min_f32_e64 v169, -v141, s60
	v_ldexp_f32 v81, v81, v162
	v_mul_f32_e32 v76, v131, v135
	v_max_f32_e32 v135, 0xda24260, v166
	v_cvt_pk_bf16_f32 v145, v145, s0
	v_add_f32_e32 v141, v141, v144
	v_mul_f32_e32 v144, 0x3f317218, v158
	v_fma_f32 v158, v131, v137, v130
	v_sub_f32_e32 v137, 1.0, v137
	v_cndmask_b32_e64 v150, 0, v225, s[0:1]
	v_mul_f32_e32 v151, 0x3fb8aa3b, v169
	v_log_f32_e32 v81, v81
	v_cmp_gt_f32_e64 s[0:1], s54, v135
	ds_write_b16 v67, v145 offset:4608
	v_mul_f32_e32 v145, v74, v168
	v_sub_f32_e32 v144, v144, v148
	v_mul_f32_e32 v74, v131, v137
	v_max_f32_e32 v137, 0xda24260, v158
	v_cndmask_b32_e64 v155, 0, 32, s[0:1]
	v_exp_f32_e32 v151, v151
	v_min_f32_e64 v153, -v141, s60
	v_cndmask_b32_e64 v149, 0, v225, s[0:1]
	v_rcp_f32_e32 v78, v78
	v_cvt_pk_bf16_f32 v142, v145, s0
	v_add_f32_e32 v141, v141, v144
	v_mul_f32_e32 v144, 0x3f317218, v161
	v_cmp_gt_f32_e64 s[0:1], s54, v137
	v_mul_f32_e32 v143, 0x3fb8aa3b, v153
	s_nop 0
	v_cndmask_b32_e64 v146, 0, 32, s[0:1]
	v_fma_f32 v153, v131, v78, v130
	v_ldexp_f32 v135, v135, v155
	ds_write_b16 v67, v142 offset:4752
	v_mul_f32_e32 v72, v72, v156
	v_exp_f32_e32 v139, v143
	v_min_f32_e64 v142, -v141, s60
	v_sub_f32_e32 v143, v144, v152
	v_ldexp_f32 v137, v137, v146
	v_max_f32_e32 v146, 0xda24260, v153
	v_rcp_f32_e32 v77, v77
	v_log_f32_e32 v135, v135
	v_cndmask_b32_e64 v145, 0, v225, s[0:1]
	v_cvt_pk_bf16_f32 v72, v72, s0
	v_mul_f32_e32 v142, 0x3fb8aa3b, v142
	v_add_f32_e32 v141, v141, v143
	v_mul_f32_e32 v143, 0x3f317218, v167
	v_cmp_gt_f32_e64 s[0:1], s54, v146
	v_fma_f32 v155, v131, v77, v130
; __device__ __forceinline__ bf16_t f2bf(float f) { return (bf16_t)(cvt_pk_bf16(f, 0.f) & 0xffffu); }
; __device__ __forceinline__ float bf2f(bf16_t b) { return __uint_as_float(((unsigned)b) << 16); }
; __device__ __forceinline__ float sigmoidf_(float x) { return 1.0f / (1.0f + __expf(-x)); }
; template <int MODE>
; __device__ __forceinline__ void hgrn_mfma(const Ctx& C, int l, int z, int b, int hd, int c, f32x4 (&Sacc)[4][4], float& dectot, unsigned char* wl, float lb) {
;     ...
;             for (int t = 0; t < 16; ++t) {
;                 const float fl = bf2f(fv[t]);
;                 const float sg = sigmoidf_(fl);
;                 const float f = lb + (1.0f - lb) * sg, kk = (1.0f - lb) * (1.0f - sg);
;                 bacc += __logf(fmaxf(f, 1e-30f));
;                 Kb[(g8 * 16 + t) * HPT + lane] = f2bf(kk * __expf(fminf(-bacc, 80.f)));
;                 if (MODE != 0) Qt[(g8 * 16 + t) * HPT + lane] = f2bf(bf2f(qv[t]) * __expf(fmaxf(bacc, -80.f)));
;                 Vv[(g8 * 16 + t) * HPT + lane] = vv[t];
;             }
;         }
;         { const float eb = __expf(bacc); dl[lane] = eb; dectot *= eb; }
	s_nop 0
	v_cndmask_b32_e64 v153, 0, 32, s[0:1]
	ds_write_b16 v67, v72 offset:4896
	v_mul_f32_e32 v71, v71, v151
	v_exp_f32_e32 v72, v142
	v_sub_f32_e32 v142, v143, v147
	v_max_f32_e32 v148, 0xda24260, v155
	v_log_f32_e32 v137, v137
	v_min_f32_e64 v140, -v141, s60
	v_ldexp_f32 v146, v146, v153
	v_cndmask_b32_e64 v147, 0, v225, s[0:1]
	v_rcp_f32_e32 v79, v79
	v_cvt_pk_bf16_f32 v71, v71, s0
	v_mul_f32_e32 v134, 0x3f317218, v134
	v_cmp_gt_f32_e64 s[0:1], s54, v148
	v_mul_f32_e32 v140, 0x3fb8aa3b, v140
	v_log_f32_e32 v144, v146
	v_cndmask_b32_e64 v146, 0, 32, s[0:1]
	v_fma_f32 v151, v131, v79, v130
	v_add_f32_e32 v141, v141, v142
	s_and_b64 vcc, exec, s[4:5]
	ds_write_b16 v67, v71 offset:5040
	v_mul_f32_e32 v69, v69, v139
	v_exp_f32_e32 v71, v140
	v_ldexp_f32 v140, v148, v146
	v_max_f32_e32 v146, 0xda24260, v151
	v_rcp_f32_e32 v80, v80
	v_min_f32_e64 v138, -v141, s60
	v_sub_f32_e32 v134, v134, v160
	v_cndmask_b32_e64 v142, 0, v225, s[0:1]
	v_cvt_pk_bf16_f32 v69, v69, s0
	v_mul_f32_e32 v81, 0x3f317218, v81
	v_cmp_gt_f32_e64 s[0:1], s54, v146
	v_fma_f32 v143, v131, v80, v130
	v_mul_f32_e32 v136, 0x3fb8aa3b, v138
	v_add_f32_e32 v134, v141, v134
	v_log_f32_e32 v140, v140
	v_cndmask_b32_e64 v141, 0, 32, s[0:1]
	v_mul_f32_e32 v68, v68, v72
	v_max_f32_e32 v143, 0xda24260, v143
	ds_write_b16 v67, v69 offset:5184
	v_exp_f32_e32 v69, v136
	v_min_f32_e64 v72, -v134, s60
	v_sub_f32_e32 v81, v81, v150
	v_ldexp_f32 v138, v146, v141
	v_cndmask_b32_e64 v141, 0, v225, s[0:1]
	v_cvt_pk_bf16_f32 v68, v68, s0
	v_cmp_gt_f32_e64 s[0:1], s54, v143
	v_mul_f32_e32 v72, 0x3fb8aa3b, v72
	v_add_f32_e32 v81, v134, v81
	v_mul_f32_e32 v134, 0x3f317218, v135
	v_mul_f32_e32 v135, 0x3f317217, v144
	v_log_f32_e32 v138, v138
	v_cndmask_b32_e64 v139, 0, 32, s[0:1]
	ds_write_b16 v67, v68 offset:5328
	v_mul_f32_e32 v68, v70, v71
	v_exp_f32_e32 v70, v72
	v_min_f32_e64 v71, -v81, s60
	v_sub_f32_e32 v72, v134, v149
	v_fma_f32 v134, v144, s56, -v135
	v_ldexp_f32 v135, v143, v139
	v_cvt_pk_bf16_f32 v68, v68, s0
	v_mul_f32_e32 v71, 0x3fb8aa3b, v71
	v_add_f32_e32 v72, v81, v72
	v_mul_f32_e32 v81, 0x3f317218, v137
	v_fmac_f32_e32 v134, 0x3377d1cf, v144
	v_mul_f32_e32 v136, 0x3f317217, v140
	v_log_f32_e32 v135, v135
	v_cndmask_b32_e64 v139, 0, v225, s[0:1]
	ds_write_b16 v67, v68 offset:5472
	v_mul_f32_e32 v66, v66, v69
	v_exp_f32_e32 v68, v71
	v_min_f32_e64 v69, -v72, s60
	v_sub_f32_e32 v71, v81, v145
	v_fmac_f32_e32 v134, 0x3f317217, v144
	v_cmp_lt_f32_e64 s[0:1], |v144|, s57
	v_fma_f32 v81, v140, s56, -v136
	v_mul_f32_e32 v69, 0x3fb8aa3b, v69
	v_cvt_pk_bf16_f32 v66, v66, s0
	v_add_f32_e32 v71, v72, v71
	v_cndmask_b32_e64 v72, v144, v134, s[0:1]
	v_fmac_f32_e32 v81, 0x3377d1cf, v140
	v_mul_f32_e32 v134, 0x3f317217, v138
	ds_write_b16 v67, v66 offset:5616
	v_mul_f32_e32 v66, v73, v70
	v_exp_f32_e32 v69, v69
	v_min_f32_e64 v70, -v71, s60
	v_sub_f32_e32 v72, v72, v147
	v_fmac_f32_e32 v81, 0x3f317217, v140
	v_cmp_lt_f32_e64 s[0:1], |v140|, s57
	v_fma_f32 v73, v138, s56, -v134
	v_mul_f32_e32 v70, 0x3fb8aa3b, v70
	v_cvt_pk_bf16_f32 v66, v66, s0
	v_add_f32_e32 v71, v71, v72
	v_cndmask_b32_e64 v72, v140, v81, s[0:1]
	v_fmac_f32_e32 v73, 0x3377d1cf, v138
	v_mul_f32_e32 v81, 0x3f317217, v135
	ds_write_b16 v67, v66 offset:5760
	v_mul_f32_e32 v66, v75, v68
	v_exp_f32_e32 v68, v70
	v_min_f32_e64 v70, -v71, s60
	v_sub_f32_e32 v72, v72, v142
	v_fmac_f32_e32 v73, 0x3f317217, v138
	v_cmp_lt_f32_e64 s[0:1], |v138|, s57
	v_fma_f32 v75, v135, s56, -v81
	v_mul_f32_e32 v70, 0x3fb8aa3b, v70
	v_cvt_pk_bf16_f32 v66, v66, s0
	v_add_f32_e32 v71, v71, v72
	v_cndmask_b32_e64 v72, v138, v73, s[0:1]
	v_fmac_f32_e32 v75, 0x3377d1cf, v135
	ds_write_b16 v67, v66 offset:5904
	v_mul_f32_e32 v66, v76, v69
	v_exp_f32_e32 v69, v70
	v_min_f32_e64 v70, -v71, s60
	v_sub_f32_e32 v72, v72, v141
	v_fmac_f32_e32 v75, 0x3f317217, v135
	v_cmp_lt_f32_e64 s[0:1], |v135|, s57
	v_mul_f32_e32 v70, 0x3fb8aa3b, v70
	v_add_f32_e32 v71, v71, v72
	v_cvt_pk_bf16_f32 v66, v66, s0
	v_cndmask_b32_e64 v72, v135, v75, s[0:1]
	v_sub_f32_e32 v78, 1.0, v78
	ds_write_b16 v67, v66 offset:6048
	v_mul_f32_e32 v66, v74, v68
	v_exp_f32_e32 v68, v70
	v_min_f32_e64 v70, -v71, s60
	v_sub_f32_e32 v72, v72, v139
	v_mul_f32_e32 v78, v131, v78
	v_cvt_pk_bf16_f32 v73, v66, s0
	v_mul_f32_e32 v70, 0x3fb8aa3b, v70
	v_add_f32_e32 v66, v71, v72
	v_sub_f32_e32 v77, 1.0, v77
	v_mul_f32_e32 v69, v78, v69
	v_exp_f32_e32 v70, v70
	v_min_f32_e64 v71, -v66, s60
	v_mul_f32_e32 v77, v131, v77
	v_cvt_pk_bf16_f32 v69, v69, s0
	v_mul_f32_e32 v71, 0x3fb8aa3b, v71
	v_sub_f32_e32 v79, 1.0, v79
	ds_write_b16 v67, v69 offset:6336
	v_mul_f32_e32 v68, v77, v68
	v_exp_f32_e32 v69, v71
	v_mul_f32_e32 v79, v131, v79
	v_cvt_pk_bf16_f32 v68, v68, s0
	v_sub_f32_e32 v80, 1.0, v80
	ds_write_b16 v67, v68 offset:6480
	v_mul_f32_e32 v68, v79, v70
	v_mul_f32_e32 v80, v131, v80
	v_cvt_pk_bf16_f32 v68, v68, s0
	ds_write_b16 v67, v68 offset:6624
	v_mul_f32_e32 v68, v80, v69
	v_cvt_pk_bf16_f32 v68, v68, s0
	ds_write_b16 v67, v73 offset:6192
	ds_write_b16 v67, v68 offset:6768
	s_cbranch_vccz .LBB0_476
; template <int MODE>
; __device__ __forceinline__ void hgrn_mfma(const Ctx& C, int l, int z, int b, int hd, int c, f32x4 (&Sacc)[4][4], float& dectot, unsigned char* wl, float lb) {
;     ...
;         { const float eb = __expf(bacc); dl[lane] = eb; dectot *= eb; }
;         wave_lds_fence();
;         f32x4 Oacc[2][4];
;         if (MODE != 0) {
;             bf16x8 Sb[2][4];
; #pragma unroll
;             for (int ks = 0; ks < 2; ++ks)
; #pragma unroll
;                 for (int vt = 0; vt < 4; ++vt) { union { bf16x8 v; unsigned u[4]; } t_;
;                     t_.u[0] = cvt_pk_bf16(Sacc[2 * ks][vt][0], Sacc[2 * ks][vt][1]); t_.u[1] = cvt_pk_bf16(Sacc[2 * ks][vt][2], Sacc[2 * ks][vt][3]);
;                     t_.u[2] = cvt_pk_bf16(Sacc[2 * ks + 1][vt][0], Sacc[2 * ks + 1][vt][1]); t_.u[3] = cvt_pk_bf16(Sacc[2 * ks + 1][vt][2], Sacc[2 * ks + 1][vt][3]); Sb[ks][vt] = t_.v; }
;             float zz = 0.f; asm volatile("" : "+v"(zz));
; #pragma unroll
;             for (int tt = 0; tt < 2; ++tt)
; #pragma unroll
;                 for (int vt = 0; vt < 4; ++vt) Oacc[tt][vt] = (f32x4){zz, zz, zz, zz};
; #pragma unroll
;             for (int tt = 0; tt < 2; ++tt)
; #pragma unroll
;                 for (int ks = 0; ks < 2; ++ks) { const bf16_t* qp = Qt + (16 * tt + fr) * HPT + 32 * ks + 4 * quad;
;                     union { bf16x8 v; u32x2 h[2]; } a_; a_.h[0] = *(const u32x2*)qp; a_.h[1] = *(const u32x2*)(qp + 16);
; #pragma unroll
;                     for (int vt = 0; vt < 4; ++vt) Oacc[tt][vt] = __builtin_amdgcn_mfma_f32_16x16x32_bf16(a_.v, Sb[ks][vt], Oacc[tt][vt], 0, 0, 0); }
;             f32x4 P00 = {zz, zz, zz, zz}, P01 = {zz, zz, zz, zz}, P11 = {zz, zz, zz, zz};
; #pragma unroll
;             for (int ks = 0; ks < 2; ++ks) {
;                 const bf16x8 kA0 = *(const bf16x8*)(Kb + fr * HPT + 32 * ks + 8 * quad), kA1 = *(const bf16x8*)(Kb + (16 + fr) * HPT + 32 * ks + 8 * quad);
;                 const bf16x8 qB0 = *(const bf16x8*)(Qt + fr * HPT + 32 * ks + 8 * quad), qB1 = *(const bf16x8*)(Qt + (16 + fr) * HPT + 32 * ks + 8 * quad);
;                 P00 = __builtin_amdgcn_mfma_f32_16x16x32_bf16(kA0, qB0, P00, 0, 0, 0);
;                 P01 = __builtin_amdgcn_mfma_f32_16x16x32_bf16(kA0, qB1, P01, 0, 0, 0);
;                 P11 = __builtin_amdgcn_mfma_f32_16x16x32_bf16(kA1, qB1, P11, 0, 0, 0);
;             }
; #pragma unroll
	v_mul_f32_e32 v66, 0x3fb8aa3b, v66
	v_exp_f32_e32 v66, v66
	s_add_i32 s69, s69, 1
	s_cmp_eq_u32 s69, 4
	ds_write_b32 v82, v66 offset:13824
	v_mul_f32_e32 v129, v129, v66
	s_waitcnt lgkmcnt(0)
	ds_read_b64_tr_b16 v[78:79], v83 offset:9216
	ds_read_b64_tr_b16 v[80:81], v83 offset:9792
	ds_read_b64_tr_b16 v[74:75], v83 offset:9248
	ds_read_b64_tr_b16 v[76:77], v83 offset:9824
	ds_read_b64_tr_b16 v[70:71], v83 offset:9280
	ds_read_b64_tr_b16 v[72:73], v83 offset:9856
	ds_read_b64_tr_b16 v[66:67], v83 offset:9312
	ds_read_b64_tr_b16 v[68:69], v83 offset:9888
	ds_read_b64_tr_b16 v[136:137], v83 offset:5184
	ds_read_b64_tr_b16 v[134:135], v83 offset:4608
	ds_read_b64_tr_b16 v[138:139], v83 offset:4640
	ds_read_b128 v[140:143], v84 offset:13824
	s_waitcnt lgkmcnt(2)
	v_mfma_f32_16x16x32_bf16 v[60:63], v[134:137], v[78:81], v[60:63]
	v_mfma_f32_16x16x32_bf16 v[56:59], v[134:137], v[74:77], v[56:59]
	s_waitcnt lgkmcnt(0)
	s_nop 5
	v_pk_mul_f32 v[60:61], v[140:141], v[60:61]
	v_pk_mul_f32 v[62:63], v[142:143], v[62:63]
	v_mfma_f32_16x16x32_bf16 v[52:55], v[134:137], v[70:73], v[52:55]
	v_mfma_f32_16x16x32_bf16 v[48:51], v[134:137], v[66:69], v[48:51]
	v_mul_f32_e64 v56, v140, v56
	v_mul_f32_e64 v57, v141, v57
	s_nop 4
	v_pk_mul_f32 v[52:53], v[140:141], v[52:53]
	v_pk_mul_f32 v[58:59], v[142:143], v[58:59]
	v_pk_mul_f32 v[54:55], v[142:143], v[54:55]
	v_pk_mul_f32 v[48:49], v[140:141], v[48:49]
	ds_read_b64_tr_b16 v[140:141], v83 offset:5216
	ds_read_b128 v[134:137], v84 offset:13888
	s_waitcnt lgkmcnt(1)
	v_mfma_f32_16x16x32_bf16 v[44:47], v[138:141], v[78:81], v[44:47]
	v_mul_f32_e64 v50, v142, v50
	v_mul_f32_e64 v51, v143, v51
	v_mfma_f32_16x16x32_bf16 v[40:43], v[138:141], v[74:77], v[40:43]
	s_waitcnt lgkmcnt(0)
	s_nop 3
	v_pk_mul_f32 v[46:47], v[136:137], v[46:47]
	v_pk_mul_f32 v[44:45], v[134:135], v[44:45]
	v_mfma_f32_16x16x32_bf16 v[36:39], v[138:141], v[70:73], v[36:39]
	v_mfma_f32_16x16x32_bf16 v[32:35], v[138:141], v[66:69], v[32:35]
	v_mul_f32_e64 v42, v136, v42
	v_mul_f32_e64 v43, v137, v43
	v_pk_mul_f32 v[40:41], v[134:135], v[40:41]
	s_nop 3
	v_pk_mul_f32 v[38:39], v[136:137], v[38:39]
	v_pk_mul_f32 v[36:37], v[134:135], v[36:37]
	v_pk_mul_f32 v[34:35], v[136:137], v[34:35]
	v_pk_mul_f32 v[32:33], v[134:135], v[32:33]
	ds_read_b64_tr_b16 v[134:135], v83 offset:4672
	ds_read_b64_tr_b16 v[136:137], v83 offset:5248
	ds_read_b128 v[138:141], v84 offset:13952
	s_waitcnt lgkmcnt(1)
	v_mfma_f32_16x16x32_bf16 v[28:31], v[134:137], v[78:81], v[28:31]
	v_mfma_f32_16x16x32_bf16 v[24:27], v[134:137], v[74:77], v[24:27]
	s_waitcnt lgkmcnt(0)
	s_nop 5
	v_pk_mul_f32 v[30:31], v[140:141], v[30:31]
	v_pk_mul_f32 v[28:29], v[138:139], v[28:29]
	v_mfma_f32_16x16x32_bf16 v[20:23], v[134:137], v[70:73], v[20:23]
	v_mfma_f32_16x16x32_bf16 v[16:19], v[134:137], v[66:69], v[16:19]
	v_mul_f32_e64 v26, v140, v26
	v_mul_f32_e64 v27, v141, v27
	v_pk_mul_f32 v[24:25], v[138:139], v[24:25]
	s_nop 3
	v_pk_mul_f32 v[22:23], v[140:141], v[22:23]
	v_pk_mul_f32 v[20:21], v[138:139], v[20:21]
	v_pk_mul_f32 v[18:19], v[140:141], v[18:19]
	v_pk_mul_f32 v[16:17], v[138:139], v[16:17]
	ds_read_b64_tr_b16 v[134:135], v83 offset:4704
	ds_read_b64_tr_b16 v[136:137], v83 offset:5280
	ds_read_b128 v[138:141], v84 offset:14016
	s_waitcnt lgkmcnt(1)
	v_mfma_f32_16x16x32_bf16 v[8:11], v[134:137], v[78:81], v[8:11]
	s_waitcnt lgkmcnt(0)
	v_mfma_f32_16x16x32_bf16 v[12:15], v[134:137], v[74:77], v[12:15]
	s_waitcnt lgkmcnt(0)
	s_nop 5
	v_pk_mul_f32 v[10:11], v[140:141], v[10:11]
	v_pk_mul_f32 v[8:9], v[138:139], v[8:9]
	v_mfma_f32_16x16x32_bf16 v[4:7], v[134:137], v[70:73], v[4:7]
	v_mfma_f32_16x16x32_bf16 v[0:3], v[134:137], v[66:69], v[0:3]
	v_mul_f32_e64 v14, v140, v14
	v_mul_f32_e64 v15, v141, v15
	v_pk_mul_f32 v[12:13], v[138:139], v[12:13]
	s_nop 3
	v_pk_mul_f32 v[6:7], v[140:141], v[6:7]
	v_pk_mul_f32 v[4:5], v[138:139], v[4:5]
	v_pk_mul_f32 v[2:3], v[140:141], v[2:3]
	v_pk_mul_f32 v[0:1], v[138:139], v[0:1]
	s_cbranch_scc0 .LBB0_475
	s_ashr_i32 s19, s18, 31
	s_lshl_b64 s[0:1], s[18:19], 14
	s_add_u32 s0, s49, s0
	s_addc_u32 s1, s53, s1
	global_store_dword v85, v60, s[0:1]
	global_store_dword v85, v61, s[0:1] offset:256
	global_store_dword v85, v62, s[0:1] offset:512
	global_store_dword v86, v63, s[0:1]
	global_store_dword v85, v56, s[0:1] offset:64
	global_store_dword v87, v57, s[0:1] offset:256
	global_store_dword v87, v58, s[0:1] offset:512
	global_store_dword v86, v59, s[0:1] offset:64
	global_store_dword v85, v52, s[0:1] offset:128
	global_store_dword v88, v53, s[0:1] offset:256
	global_store_dword v88, v54, s[0:1] offset:512
	global_store_dword v86, v55, s[0:1] offset:128
	global_store_dword v85, v48, s[0:1] offset:192
	global_store_dword v89, v49, s[0:1] offset:256
	global_store_dword v89, v50, s[0:1] offset:512
	global_store_dword v86, v51, s[0:1] offset:192
	global_store_dword v90, v44, s[0:1]
	global_store_dword v91, v45, s[0:1]
	global_store_dword v92, v46, s[0:1]
	global_store_dword v93, v47, s[0:1]
	global_store_dword v94, v40, s[0:1]
	global_store_dword v95, v41, s[0:1]
	global_store_dword v96, v42, s[0:1]
	global_store_dword v93, v43, s[0:1] offset:64
	global_store_dword v97, v36, s[0:1]
	global_store_dword v98, v37, s[0:1]
	global_store_dword v99, v38, s[0:1]
	global_store_dword v93, v39, s[0:1] offset:128
	global_store_dword v100, v32, s[0:1]
	global_store_dword v101, v33, s[0:1]
	global_store_dword v102, v34, s[0:1]
	global_store_dword v93, v35, s[0:1] offset:192
	global_store_dword v103, v28, s[0:1]
	global_store_dword v104, v29, s[0:1]
	global_store_dword v105, v30, s[0:1]
	global_store_dword v106, v31, s[0:1]
	global_store_dword v107, v24, s[0:1]
	global_store_dword v108, v25, s[0:1]
	global_store_dword v109, v26, s[0:1]
	global_store_dword v106, v27, s[0:1] offset:64
	global_store_dword v110, v20, s[0:1]
	global_store_dword v111, v21, s[0:1]
	global_store_dword v112, v22, s[0:1]
	global_store_dword v106, v23, s[0:1] offset:128
	global_store_dword v113, v16, s[0:1]
	global_store_dword v114, v17, s[0:1]
	global_store_dword v115, v18, s[0:1]
	global_store_dword v106, v19, s[0:1] offset:192
	global_store_dword v116, v8, s[0:1]
	global_store_dword v117, v9, s[0:1]
	global_store_dword v118, v10, s[0:1]
	global_store_dword v119, v11, s[0:1]
	global_store_dword v120, v12, s[0:1]
	global_store_dword v121, v13, s[0:1]
	global_store_dword v122, v14, s[0:1]
	global_store_dword v119, v15, s[0:1] offset:64
	global_store_dword v123, v4, s[0:1]
	global_store_dword v124, v5, s[0:1]
	global_store_dword v125, v6, s[0:1]
	global_store_dword v119, v7, s[0:1] offset:128
	global_store_dword v126, v0, s[0:1]
	global_store_dword v127, v1, s[0:1]
	global_store_dword v128, v2, s[0:1]
	global_store_dword v119, v3, s[0:1] offset:192
	v_lshl_or_b32 v0, s18, 6, v64
	v_readlane_b32 s0, v254, 20
	v_ashrrev_i32_e32 v1, 31, v0
	s_add_i32 s18, s18, s0
	v_lshl_add_u64 v[0:1], v[0:1], 2, s[20:21]
	s_cmpk_gt_i32 s18, 0x7ff
	v_readlane_b32 s1, v254, 21
	global_store_dword v[0:1], v129, off
	s_cbranch_scc0 .LBB0_470

; __device__ __forceinline__ bf16_t f2bf(float f) { return (bf16_t)(cvt_pk_bf16(f, 0.f) & 0xffffu); }
; __device__ __forceinline__ float bf2f(bf16_t b) { return __uint_as_float(((unsigned)b) << 16); }
; __device__ __forceinline__ float sigmoidf_(float x) { return 1.0f / (1.0f + __expf(-x)); }
; template <int MODE>
; __device__ __forceinline__ void hgrn_mfma(const Ctx& C, int l, int z, int b, int hd, int c, f32x4 (&Sacc)[4][4], float& dectot, unsigned char* wl, float lb) {
;     ...
;             bf16_t fv[16], qv[16], vv[16];
;             const int st0 = c * 128 + sc * 32 + g8 * 16; const int tq0 = z ? 4095 - st0 : st0;
;             const bf16_t* row0 = pa + (size_t)(b * SEQ + tq0) * 1280; const ptrdiff_t rstep = z ? -1280 : 1280;
; #pragma unroll
;             for (int t = 0; t < 16; ++t) { const bf16_t* row = row0 + rstep * t; fv[t] = row[fcol]; vv[t] = row[vcol]; if (MODE != 0) qv[t] = row[qcol]; }
; #pragma unroll
;             for (int t = 0; t < 16; ++t) {
;                 const float fl = bf2f(fv[t]);
;                 const float sg = sigmoidf_(fl);
;                 const float f = lb + (1.0f - lb) * sg, kk = (1.0f - lb) * (1.0f - sg);
;                 bacc += __logf(fmaxf(f, 1e-30f));
;                 Kb[(g8 * 16 + t) * HPT + lane] = f2bf(kk * __expf(fminf(-bacc, 80.f)));
;                 if (MODE != 0) Qt[(g8 * 16 + t) * HPT + lane] = f2bf(bf2f(qv[t]) * __expf(fmaxf(bacc, -80.f)));
;                 Vv[(g8 * 16 + t) * HPT + lane] = vv[t];
;             }
.LBB0_645:
	s_lshl_b32 s0, s67, 4
	v_cndmask_b32_e64 v60, 0, 1, s[46:47]
	s_mul_i32 s1, s67, 0x480
	s_sub_i32 s0, s74, s0
	v_cmp_ne_u32_e64 s[4:5], 1, v60
	v_or_b32_e32 v60, s1, v118
	s_mul_hi_i32 s1, s0, 0xa00
	s_mulk_i32 s0, 0xa00
	s_add_u32 s0, s69, s0
	v_lshlrev_b32_e32 v64, 1, v192
	s_addc_u32 s1, s70, s1
	global_load_ushort v70, v64, s[0:1] offset:1536
	global_load_ushort v71, v64, s[0:1] offset:1024
	global_load_ushort v72, v64, s[0:1]
	global_load_ushort v73, v64, s[0:1] offset:-1024
	global_load_ushort v74, v64, s[0:1] offset:-1536
	global_load_ushort v75, v64, s[0:1] offset:-2560
	global_load_ushort v76, v64, s[0:1] offset:-3584
	global_load_ushort v77, v64, s[0:1] offset:-4096
	s_add_u32 s6, s0, 0xffffe200
	s_addc_u32 s7, s1, -1
	global_load_ushort v78, v203, s[6:7]
	global_load_ushort v82, v64, s[6:7]
	global_load_ushort v83, v204, s[6:7]
	s_add_u32 s6, s0, 0xffffd800
	s_addc_u32 s7, s1, -1
	global_load_ushort v84, v203, s[6:7]
	global_load_ushort v85, v64, s[6:7]
	global_load_ushort v86, v204, s[6:7]
	s_add_u32 s6, s0, 0xffffce00
	v_lshl_add_u64 v[62:63], s[0:1], 0, v[64:65]
	s_movk_i32 s8, 0xf000
	s_addc_u32 s7, s1, -1
	v_add_co_u32_e32 v62, vcc, s8, v62
	s_add_u32 s8, s0, 0xffffc400
	global_load_ushort v89, v203, s[6:7]
	global_load_ushort v90, v64, s[6:7]
	global_load_ushort v91, v204, s[6:7]
	s_addc_u32 s9, s1, -1
	s_add_u32 s6, s0, 0xffffba00
	global_load_ushort v92, v204, s[8:9]
	global_load_ushort v93, v203, s[8:9]
	global_load_ushort v94, v64, s[8:9]
	s_addc_u32 s7, s1, -1
	s_add_u32 s8, s0, 0xffffb000
	global_load_ushort v95, v204, s[6:7]
	global_load_ushort v96, v203, s[6:7]
	global_load_ushort v97, v64, s[6:7]
	s_addc_u32 s9, s1, -1
	s_add_u32 s6, s0, 0xffffa600
	global_load_ushort v98, v204, s[8:9]
	global_load_ushort v99, v203, s[8:9]
	global_load_ushort v100, v64, s[8:9]
	s_addc_u32 s7, s1, -1
	s_add_u32 s8, s0, 0xffff9c00
	global_load_ushort v101, v204, s[6:7]
	global_load_ushort v102, v203, s[6:7]
	global_load_ushort v103, v64, s[6:7]
	s_addc_u32 s9, s1, -1
	global_load_ushort v104, v204, s[8:9]
	global_load_ushort v105, v203, s[8:9]
	global_load_ushort v106, v64, s[8:9]
	s_add_u32 s6, s0, 0xffff9200
	s_addc_u32 s7, s1, -1
	s_add_u32 s8, s0, 0xffff8800
	global_load_ushort v108, v204, s[6:7]
	global_load_ushort v109, v203, s[6:7]
	global_load_ushort v110, v64, s[6:7]
	s_addc_u32 s9, s1, -1
	s_add_u32 s6, s0, 0xffff7e00
	global_load_ushort v111, v204, s[8:9]
	global_load_ushort v178, v203, s[8:9]
	global_load_ushort v179, v64, s[8:9]
	s_addc_u32 s7, s1, -1
	s_add_u32 s8, s0, 0xffff7400
	global_load_ushort v180, v204, s[6:7]
	global_load_ushort v181, v203, s[6:7]
	global_load_ushort v188, v64, s[6:7]
	s_addc_u32 s9, s1, -1
	global_load_ushort v189, v204, s[8:9]
	global_load_ushort v190, v203, s[8:9]
	global_load_ushort v191, v64, s[8:9]
	s_add_u32 s0, s0, 0xffff6a00
	s_addc_u32 s1, s1, -1
	v_addc_co_u32_e32 v63, vcc, -1, v63, vcc
	global_load_ushort v87, v204, s[0:1]
	global_load_ushort v208, v[62:63], off offset:-1024
	global_load_ushort v79, v203, s[0:1]
	global_load_ushort v88, v64, s[0:1]
	v_lshl_add_u32 v60, v60, 1, s49
	s_mov_b64 s[46:47], 0
	s_mov_b32 s67, 1
	s_waitcnt vmcnt(47)
	ds_write_b16 v60, v70 offset:9216
	s_waitcnt vmcnt(46)
	v_lshlrev_b32_e32 v62, 16, v71
	v_mul_f32_e32 v62, 0xbfb8aa3b, v62
	v_exp_f32_e32 v62, v62
	s_waitcnt vmcnt(43)
	v_lshlrev_b32_e32 v63, 16, v74
	v_mul_f32_e32 v63, 0xbfb8aa3b, v63
	v_exp_f32_e32 v63, v63
	s_waitcnt vmcnt(40)
	v_lshlrev_b32_e32 v64, 16, v77
	v_mul_f32_e32 v64, 0xbfb8aa3b, v64
	v_exp_f32_e32 v64, v64
	s_waitcnt vmcnt(39)
	v_lshlrev_b32_e32 v70, 16, v78
	v_mul_f32_e32 v70, 0xbfb8aa3b, v70
	v_exp_f32_e32 v70, v70
	s_waitcnt vmcnt(36)
	v_lshlrev_b32_e32 v71, 16, v84
	v_lshlrev_b32_e32 v78, 16, v82
	v_mul_f32_e32 v71, 0xbfb8aa3b, v71
	v_add_f32_e32 v82, 1.0, v62
	v_add_f32_e32 v63, 1.0, v63
	v_add_f32_e32 v64, 1.0, v64
	ds_write_b16 v60, v83 offset:9648
	s_waitcnt vmcnt(35)
	v_lshlrev_b32_e32 v77, 16, v85
	v_exp_f32_e32 v62, v71
	s_waitcnt vmcnt(33)
	v_lshlrev_b32_e32 v71, 16, v89
	s_waitcnt vmcnt(31)
	ds_write_b16 v60, v91 offset:9936
	v_mul_f32_e32 v71, 0xbfb8aa3b, v71
	v_lshlrev_b32_e32 v81, 16, v72
	v_add_f32_e32 v70, 1.0, v70
	v_exp_f32_e32 v71, v71
	s_waitcnt vmcnt(29)
	v_lshlrev_b32_e32 v72, 16, v93
	v_mul_f32_e32 v72, 0xbfb8aa3b, v72
	v_add_f32_e32 v211, 1.0, v62
	v_exp_f32_e32 v62, v72
	s_waitcnt vmcnt(26)
	v_lshlrev_b32_e32 v72, 16, v96
	ds_write_b16 v60, v92 offset:10080
	ds_write_b16 v60, v95 offset:10224
	v_mul_f32_e32 v72, 0xbfb8aa3b, v72
	ds_write_b16 v60, v76 offset:9504
	ds_write_b16 v60, v86 offset:9792
	v_lshlrev_b32_e32 v76, 16, v90
	v_add_f32_e32 v213, 1.0, v71
	v_exp_f32_e32 v71, v72
	s_waitcnt vmcnt(23)
	v_lshlrev_b32_e32 v72, 16, v99
	ds_write_b16 v60, v98 offset:10368
	v_mul_f32_e32 v72, 0xbfb8aa3b, v72
	s_waitcnt vmcnt(20)
	v_lshlrev_b32_e32 v99, 16, v102
	v_add_f32_e32 v107, 1.0, v62
	v_exp_f32_e32 v62, v72
	s_waitcnt vmcnt(19)
	v_lshlrev_b32_e32 v72, 16, v103
	ds_write_b16 v60, v101 offset:10512
	v_mul_f32_e32 v99, 0xbfb8aa3b, v99
	v_lshlrev_b32_e32 v80, 16, v75
	v_lshlrev_b32_e32 v75, 16, v94
	v_exp_f32_e32 v229, v99
	s_waitcnt vmcnt(17)
	v_lshlrev_b32_e32 v99, 16, v105
	v_mul_f32_e32 v89, 0xbfb8aa3b, v99
	v_lshlrev_b32_e32 v74, 16, v97
	v_add_f32_e32 v103, 1.0, v71
	v_exp_f32_e32 v89, v89
	s_waitcnt vmcnt(14)
	v_lshlrev_b32_e32 v91, 16, v109
	v_rcp_f32_e32 v82, v82
	ds_write_b16 v60, v73 offset:9360
	v_lshlrev_b32_e32 v73, 16, v100
	v_add_f32_e32 v99, 1.0, v62
	v_mul_f32_e32 v86, 0xbfb8aa3b, v91
	v_fma_f32 v91, v194, v82, v193
	v_sub_f32_e32 v82, 1.0, v82
	v_rcp_f32_e32 v83, v63
	v_add_f32_e32 v96, 1.0, v229
	ds_write_b16 v60, v104 offset:10656
	v_exp_f32_e32 v104, v86
	s_waitcnt vmcnt(11)
; __device__ __forceinline__ bf16_t f2bf(float f) { return (bf16_t)(cvt_pk_bf16(f, 0.f) & 0xffffu); }
; __device__ __forceinline__ float bf2f(bf16_t b) { return __uint_as_float(((unsigned)b) << 16); }
; __device__ __forceinline__ float sigmoidf_(float x) { return 1.0f / (1.0f + __expf(-x)); }
; template <int MODE>
; __device__ __forceinline__ void hgrn_mfma(const Ctx& C, int l, int z, int b, int hd, int c, f32x4 (&Sacc)[4][4], float& dectot, unsigned char* wl, float lb) {
;     ...
;             for (int t = 0; t < 16; ++t) {
;                 const float fl = bf2f(fv[t]);
;                 const float sg = sigmoidf_(fl);
;                 const float f = lb + (1.0f - lb) * sg, kk = (1.0f - lb) * (1.0f - sg);
;                 bacc += __logf(fmaxf(f, 1e-30f));
;                 Kb[(g8 * 16 + t) * HPT + lane] = f2bf(kk * __expf(fminf(-bacc, 80.f)));
;                 if (MODE != 0) Qt[(g8 * 16 + t) * HPT + lane] = f2bf(bf2f(qv[t]) * __expf(fmaxf(bacc, -80.f)));
;                 Vv[(g8 * 16 + t) * HPT + lane] = vv[t];
;             }
	v_lshlrev_b32_e32 v102, 16, v178
	v_mul_f32_e32 v86, v194, v82
	v_max_f32_e32 v82, 0xda24260, v91
	v_fma_f32 v91, v194, v83, v193
	v_sub_f32_e32 v83, 1.0, v83
	v_rcp_f32_e32 v64, v64
	v_lshlrev_b32_e32 v71, 16, v106
	ds_write_b16 v60, v108 offset:10800
	v_mul_f32_e32 v101, 0xbfb8aa3b, v102
	v_cmp_gt_f32_e64 s[0:1], s54, v82
	v_mul_f32_e32 v84, v194, v83
	v_max_f32_e32 v83, 0xda24260, v91
	v_fma_f32 v106, v194, v64, v193
	v_rcp_f32_e32 v70, v70
	v_add_f32_e32 v93, 1.0, v89
	s_waitcnt vmcnt(10)
	v_lshlrev_b32_e32 v63, 16, v179
	v_cndmask_b32_e64 v102, 0, 32, s[0:1]
	v_exp_f32_e32 v179, v101
	s_waitcnt vmcnt(9)
	ds_write_b16 v60, v180 offset:11088
	v_cndmask_b32_e64 v105, 0, v225, s[0:1]
	v_cmp_gt_f32_e32 vcc, s54, v83
	v_max_f32_e32 v180, 0xda24260, v106
	v_fma_f32 v106, v194, v70, v193
	v_lshlrev_b32_e32 v62, 16, v110
	v_sub_f32_e32 v110, 1.0, v64
	s_waitcnt vmcnt(8)
	v_lshlrev_b32_e32 v89, 16, v181
	s_waitcnt vmcnt(7)
	v_lshlrev_b32_e32 v64, 16, v188
	v_cndmask_b32_e64 v97, 0, 32, vcc
	v_rcp_f32_e32 v90, v211
	v_cndmask_b32_e32 v100, 0, v225, vcc
	v_cmp_gt_f32_e64 s[0:1], s54, v180
	v_max_f32_e32 v188, 0xda24260, v106
	v_ldexp_f32 v82, v82, v102
	v_sub_f32_e32 v70, 1.0, v70
	v_mul_f32_e32 v95, 0xbfb8aa3b, v89
	v_ldexp_f32 v83, v83, v97
	v_cndmask_b32_e64 v97, 0, 32, s[0:1]
	v_fma_f32 v209, v194, v90, v193
	v_add_f32_e32 v89, 1.0, v104
	v_cmp_gt_f32_e32 vcc, s54, v188
	v_mul_f32_e32 v85, v194, v110
	v_log_f32_e32 v110, v82
	v_mul_f32_e32 v82, v194, v70
	v_exp_f32_e32 v211, v95
	s_waitcnt vmcnt(5)
	v_lshlrev_b32_e32 v104, 16, v190
	s_waitcnt vmcnt(4)
	v_lshlrev_b32_e32 v70, 16, v191
	ds_write_b16 v60, v189 offset:11232
	v_ldexp_f32 v180, v180, v97
	v_cndmask_b32_e64 v97, 0, v225, s[0:1]
	v_cndmask_b32_e64 v189, 0, 32, vcc
	v_max_f32_e32 v190, 0xda24260, v209
	v_rcp_f32_e32 v191, v213
	v_sub_f32_e32 v90, 1.0, v90
	v_log_f32_e32 v106, v83
	v_mul_f32_e32 v210, 0xbfb8aa3b, v104
	v_log_f32_e32 v104, v180
	v_ldexp_f32 v180, v188, v189
	v_cndmask_b32_e32 v188, 0, v225, vcc
	v_cmp_gt_f32_e64 s[0:1], s54, v190
	v_mul_f32_e32 v83, v194, v90
	s_waitcnt vmcnt(2)
	v_lshlrev_b32_e32 v90, 16, v208
	v_cndmask_b32_e64 v189, 0, 32, s[0:1]
	v_fma_f32 v213, v194, v191, v193
	v_sub_f32_e32 v191, 1.0, v191
	v_add_f32_e32 v208, 1.0, v179
	v_exp_f32_e32 v179, v210
	s_waitcnt vmcnt(1)
	v_lshlrev_b32_e32 v210, 16, v79
	s_waitcnt vmcnt(0)
	v_lshlrev_b32_e32 v79, 16, v88
	ds_write_b16 v60, v87 offset:11376
	v_ldexp_f32 v87, v190, v189
	v_cndmask_b32_e64 v189, 0, v225, s[0:1]
	v_mul_f32_e32 v92, v194, v191
	v_max_f32_e32 v88, 0xda24260, v213
	v_rcp_f32_e32 v107, v107
	ds_write_b16 v60, v111 offset:10944
	v_log_f32_e32 v180, v180
	v_mul_f32_e32 v207, 0xbfb8aa3b, v210
	v_cmp_gt_f32_e64 s[0:1], s54, v88
	v_fma_f32 v213, v194, v107, v193
	v_sub_f32_e32 v215, 1.0, v107
	v_add_f32_e32 v107, 1.0, v211
	v_log_f32_e32 v212, v87
	v_cndmask_b32_e64 v87, 0, 32, s[0:1]
	v_exp_f32_e32 v207, v207
	v_cndmask_b32_e64 v223, 0, v225, s[0:1]
	v_max_f32_e32 v213, 0xda24260, v213
	v_rcp_f32_e32 v103, v103
	v_ldexp_f32 v87, v88, v87
	v_cmp_gt_f32_e64 s[0:1], s54, v213
	v_fma_f32 v229, v194, v103, v193
	v_sub_f32_e32 v230, 1.0, v103
	v_add_f32_e32 v103, 1.0, v179
	v_mul_f32_e32 v88, v194, v215
	v_log_f32_e32 v228, v87
	v_cndmask_b32_e64 v87, 0, 32, s[0:1]
	v_cndmask_b32_e64 v231, 0, v225, s[0:1]
	v_max_f32_e32 v229, 0xda24260, v229
	v_rcp_f32_e32 v99, v99
	v_ldexp_f32 v213, v213, v87
	v_mul_f32_e32 v110, 0x3f317218, v110
	v_cmp_gt_f32_e64 s[18:19], s54, v229
	v_fma_f32 v232, v194, v99, v193
	v_mul_f32_e32 v87, v194, v230
	v_log_f32_e32 v213, v213
	v_cndmask_b32_e64 v215, 0, 32, s[18:19]
	v_sub_f32_e32 v233, 1.0, v99
	v_add_f32_e32 v99, 1.0, v207
	v_mul_f32_e32 v106, 0x3f317218, v106
	v_max_f32_e32 v211, 0xda24260, v232
	v_sub_f32_e32 v105, v110, v105
	v_ldexp_f32 v207, v229, v215
	v_cndmask_b32_e64 v210, 0, v225, s[18:19]
	v_rcp_f32_e32 v111, v96
	v_cmp_gt_f32_e64 s[18:19], s54, v211
	v_add_f32_e32 v61, v61, v105
	v_sub_f32_e32 v100, v106, v100
	v_mul_f32_e32 v104, 0x3f317218, v104
	v_log_f32_e32 v106, v207
	v_cndmask_b32_e64 v179, 0, 32, s[18:19]
	v_fma_f32 v207, v194, v111, v193
	v_sub_f32_e32 v111, 1.0, v111
	v_min_f32_e64 v229, -v61, s60
	v_max_f32_e32 v230, 0xc2a00000, v61
	v_add_f32_e32 v100, v61, v100
	v_sub_f32_e32 v97, v104, v97
	v_mul_f32_e32 v104, 0x3f317218, v180
	v_ldexp_f32 v113, v211, v179
	v_mul_f32_e32 v61, v194, v111
	v_max_f32_e32 v111, 0xda24260, v207
	v_rcp_f32_e32 v93, v93
	v_min_f32_e64 v180, -v100, s60
	v_max_f32_e32 v207, 0xc2a00000, v100
	v_add_f32_e32 v97, v100, v97
	v_sub_f32_e32 v100, v104, v188
	v_mul_f32_e32 v104, 0x3f317218, v212
	v_log_f32_e32 v113, v113
	v_cmp_gt_f32_e64 s[0:1], s54, v111
	v_mul_f32_e32 v98, 0x3fb8aa3b, v229
	v_mul_f32_e32 v112, 0x3fb8aa3b, v230
	v_cndmask_b32_e64 v188, 0, 32, s[0:1]
	v_fma_f32 v211, v194, v93, v193
	v_mul_f32_e32 v207, 0x3fb8aa3b, v207
	v_min_f32_e64 v212, -v97, s60
	v_max_f32_e32 v214, 0xc2a00000, v97
	v_add_f32_e32 v97, v97, v100
	v_sub_f32_e32 v100, v104, v189
	v_exp_f32_e32 v98, v98
	v_exp_f32_e32 v112, v112
	v_mul_f32_e32 v180, 0x3fb8aa3b, v180
	v_ldexp_f32 v110, v111, v188
	v_max_f32_e32 v188, 0xda24260, v211
	v_rcp_f32_e32 v89, v89
	v_exp_f32_e32 v181, v207
	v_min_f32_e64 v207, -v97, s60
	v_max_f32_e32 v211, 0xc2a00000, v97
	v_add_f32_e32 v97, v97, v100
	v_mul_f32_e32 v100, 0x3f317218, v228
	v_cndmask_b32_e64 v111, 0, v225, s[0:1]
	v_exp_f32_e32 v180, v180
	v_mul_f32_e32 v191, 0x3fb8aa3b, v212
	v_mul_f32_e32 v206, 0x3fb8aa3b, v214
	v_cmp_gt_f32_e64 s[0:1], s54, v188
	v_fma_f32 v214, v194, v89, v193
	v_sub_f32_e32 v100, v100, v223
	v_log_f32_e32 v110, v110
	v_cndmask_b32_e64 v212, 0, 32, s[0:1]
	v_exp_f32_e32 v191, v191
; __device__ __forceinline__ bf16_t f2bf(float f) { return (bf16_t)(cvt_pk_bf16(f, 0.f) & 0xffffu); }
; __device__ __forceinline__ float bf2f(bf16_t b) { return __uint_as_float(((unsigned)b) << 16); }
; __device__ __forceinline__ float sigmoidf_(float x) { return 1.0f / (1.0f + __expf(-x)); }
; template <int MODE>
; __device__ __forceinline__ void hgrn_mfma(const Ctx& C, int l, int z, int b, int hd, int c, f32x4 (&Sacc)[4][4], float& dectot, unsigned char* wl, float lb) {
;     ...
;             for (int t = 0; t < 16; ++t) {
;                 const float fl = bf2f(fv[t]);
;                 const float sg = sigmoidf_(fl);
;                 const float f = lb + (1.0f - lb) * sg, kk = (1.0f - lb) * (1.0f - sg);
;                 bacc += __logf(fmaxf(f, 1e-30f));
;                 Kb[(g8 * 16 + t) * HPT + lane] = f2bf(kk * __expf(fminf(-bacc, 80.f)));
;                 if (MODE != 0) Qt[(g8 * 16 + t) * HPT + lane] = f2bf(bf2f(qv[t]) * __expf(fmaxf(bacc, -80.f)));
;                 Vv[(g8 * 16 + t) * HPT + lane] = vv[t];
;             }
	v_exp_f32_e32 v205, v206
	v_mul_f32_e32 v206, 0x3fb8aa3b, v207
	v_mul_f32_e32 v207, 0x3fb8aa3b, v211
	v_min_f32_e64 v211, -v97, s60
	v_max_f32_e32 v228, 0xc2a00000, v97
	v_max_f32_e32 v214, 0xda24260, v214
	v_rcp_f32_e32 v94, v208
	v_add_f32_e32 v97, v97, v100
	v_mul_f32_e32 v100, 0x3f317218, v213
	v_ldexp_f32 v188, v188, v212
	v_cndmask_b32_e64 v212, 0, v225, s[0:1]
	v_exp_f32_e32 v189, v206
	v_exp_f32_e32 v206, v207
	v_mul_f32_e32 v207, 0x3fb8aa3b, v211
	v_mul_f32_e32 v208, 0x3fb8aa3b, v228
	v_cmp_gt_f32_e64 s[0:1], s54, v214
	v_fma_f32 v213, v194, v94, v193
	v_sub_f32_e32 v94, 1.0, v94
	v_sub_f32_e32 v100, v100, v231
	v_log_f32_e32 v188, v188
	v_cndmask_b32_e64 v211, 0, 32, s[0:1]
	v_mul_f32_e32 v86, v86, v98
	v_mul_f32_e32 v98, v112, v81
	v_exp_f32_e32 v112, v207
	v_exp_f32_e32 v190, v208
	v_min_f32_e64 v207, -v97, s60
	v_max_f32_e32 v208, 0xc2a00000, v97
	v_mul_f32_e32 v81, v194, v94
	v_max_f32_e32 v94, 0xda24260, v213
	v_rcp_f32_e32 v95, v107
	v_add_f32_e32 v97, v97, v100
	v_mul_f32_e32 v100, 0x3f317218, v106
	v_ldexp_f32 v209, v214, v211
	v_cndmask_b32_e64 v211, 0, v225, s[0:1]
	v_cvt_pk_bf16_f32 v86, v86, s0
	v_cvt_pk_bf16_f32 v98, v98, s0
	v_mul_f32_e32 v84, v84, v180
	v_mul_f32_e32 v80, v181, v80
	v_mul_f32_e32 v109, 0x3fb8aa3b, v207
	v_mul_f32_e32 v180, 0x3fb8aa3b, v208
	v_cmp_gt_f32_e64 s[0:1], s54, v94
	v_fma_f32 v207, v194, v95, v193
	v_sub_f32_e32 v95, 1.0, v95
	v_sub_f32_e32 v100, v100, v210
	v_log_f32_e32 v106, v209
	v_cndmask_b32_e64 v181, 0, 32, s[0:1]
	ds_write_b16 v60, v86 offset:4608
	ds_write_b16 v60, v98
	v_cvt_pk_bf16_f32 v84, v84, s0
	v_cvt_pk_bf16_f32 v86, v80, s0
	v_mul_f32_e32 v85, v85, v191
	v_mul_f32_e32 v90, v205, v90
	v_exp_f32_e32 v98, v109
	v_exp_f32_e32 v107, v180
	v_min_f32_e64 v108, -v97, s60
	v_max_f32_e32 v109, 0xc2a00000, v97
	v_mul_f32_e32 v80, v194, v95
	v_max_f32_e32 v95, 0xda24260, v207
	v_rcp_f32_e32 v102, v103
	v_add_f32_e32 v97, v97, v100
	v_mul_f32_e32 v100, 0x3f317218, v113
	v_cndmask_b32_e64 v179, 0, v225, s[18:19]
	v_ldexp_f32 v94, v94, v181
	v_cndmask_b32_e64 v180, 0, v225, s[0:1]
	ds_write_b16 v60, v84 offset:4752
	ds_write_b16 v60, v86 offset:144
	v_cvt_pk_bf16_f32 v84, v85, s0
	v_cvt_pk_bf16_f32 v85, v90, s0
	v_mul_f32_e32 v82, v82, v189
	v_mul_f32_e32 v78, v206, v78
	v_mul_f32_e32 v86, 0x3fb8aa3b, v108
	v_cmp_gt_f32_e64 s[0:1], s54, v95
	v_fma_f32 v104, v194, v102, v193
	v_mul_f32_e32 v90, 0x3fb8aa3b, v109
	v_log_f32_e32 v94, v94
	v_cndmask_b32_e64 v103, 0, 32, s[0:1]
	ds_write_b16 v60, v84 offset:4896
	ds_write_b16 v60, v85 offset:288
	v_cvt_pk_bf16_f32 v82, v82, s0
	v_cvt_pk_bf16_f32 v78, v78, s0
	v_mul_f32_e32 v83, v83, v112
	v_mul_f32_e32 v77, v190, v77
	v_exp_f32_e32 v84, v86
	v_min_f32_e64 v86, -v97, s60
	v_sub_f32_e32 v100, v100, v179
	v_max_f32_e32 v104, 0xda24260, v104
	v_rcp_f32_e32 v96, v99
	s_and_b64 vcc, exec, s[4:5]
	v_exp_f32_e32 v85, v90
	v_max_f32_e32 v90, 0xc2a00000, v97
	v_ldexp_f32 v95, v95, v103
	v_cndmask_b32_e64 v103, 0, v225, s[0:1]
	ds_write_b16 v60, v82 offset:5040
	ds_write_b16 v60, v78 offset:432
	v_cvt_pk_bf16_f32 v78, v83, s0
	v_cvt_pk_bf16_f32 v77, v77, s0
	v_mul_f32_e32 v82, 0x3fb8aa3b, v86
	v_add_f32_e32 v86, v97, v100
	v_cmp_gt_f32_e64 s[0:1], s54, v104
	v_fma_f32 v100, v194, v96, v193
	v_mul_f32_e32 v83, 0x3fb8aa3b, v90
	v_mul_f32_e32 v90, 0x3f317218, v110
	v_log_f32_e32 v95, v95
	v_cndmask_b32_e64 v99, 0, 32, s[0:1]
	ds_write_b16 v60, v78 offset:5184
	ds_write_b16 v60, v77 offset:576
	v_mul_f32_e32 v77, v92, v98
	v_mul_f32_e32 v76, v107, v76
	v_max_f32_e32 v100, 0xda24260, v100
	v_exp_f32_e32 v78, v82
	v_exp_f32_e32 v82, v83
	v_min_f32_e64 v83, -v86, s60
	v_max_f32_e32 v92, 0xc2a00000, v86
	v_sub_f32_e32 v90, v90, v111
	v_ldexp_f32 v98, v104, v99
	v_cndmask_b32_e64 v99, 0, v225, s[0:1]
	v_cvt_pk_bf16_f32 v77, v77, s0
	v_cvt_pk_bf16_f32 v76, v76, s0
	v_cmp_gt_f32_e64 s[0:1], s54, v100
	v_mul_f32_e32 v83, 0x3fb8aa3b, v83
	v_mul_f32_e32 v92, 0x3fb8aa3b, v92
	v_add_f32_e32 v86, v86, v90
	v_mul_f32_e32 v90, 0x3f317218, v188
	v_mul_f32_e32 v101, 0x3f317217, v94
	v_log_f32_e32 v98, v98
	v_cndmask_b32_e64 v104, 0, 32, s[0:1]
	ds_write_b16 v60, v77 offset:5328
	ds_write_b16 v60, v76 offset:720
	v_mul_f32_e32 v76, v88, v84
	v_mul_f32_e32 v75, v85, v75
	v_exp_f32_e32 v77, v83
	v_exp_f32_e32 v83, v92
	v_min_f32_e64 v84, -v86, s60
	v_max_f32_e32 v85, 0xc2a00000, v86
	v_sub_f32_e32 v88, v90, v212
	v_fma_f32 v90, v94, s56, -v101
	v_ldexp_f32 v92, v100, v104
	v_cvt_pk_bf16_f32 v76, v76, s0
	v_cvt_pk_bf16_f32 v75, v75, s0
	v_mul_f32_e32 v84, 0x3fb8aa3b, v84
	v_mul_f32_e32 v85, 0x3fb8aa3b, v85
	v_add_f32_e32 v86, v86, v88
	v_mul_f32_e32 v88, 0x3f317218, v106
	v_fmac_f32_e32 v90, 0x3377d1cf, v94
	v_mul_f32_e32 v97, 0x3f317217, v95
	v_log_f32_e32 v92, v92
	v_cndmask_b32_e64 v100, 0, v225, s[0:1]
	ds_write_b16 v60, v76 offset:5472
	ds_write_b16 v60, v75 offset:864
	v_mul_f32_e32 v75, v87, v78
	v_mul_f32_e32 v74, v82, v74
	v_exp_f32_e32 v76, v84
	v_exp_f32_e32 v78, v85
	v_min_f32_e64 v82, -v86, s60
	v_max_f32_e32 v84, 0xc2a00000, v86
	v_sub_f32_e32 v85, v88, v211
	v_fmac_f32_e32 v90, 0x3f317217, v94
	v_cmp_lt_f32_e64 s[0:1], |v94|, s57
	v_fma_f32 v87, v95, s56, -v97
	v_mul_f32_e32 v91, v194, v233
	v_cvt_pk_bf16_f32 v75, v75, s0
	v_cvt_pk_bf16_f32 v74, v74, s0
	v_mul_f32_e32 v82, 0x3fb8aa3b, v82
	v_mul_f32_e32 v84, 0x3fb8aa3b, v84
	v_add_f32_e32 v85, v86, v85
	v_cndmask_b32_e64 v86, v94, v90, s[0:1]
	v_fmac_f32_e32 v87, 0x3377d1cf, v95
	v_mul_f32_e32 v88, 0x3f317217, v98
	ds_write_b16 v60, v75 offset:5616
	ds_write_b16 v60, v74 offset:1008
	v_mul_f32_e32 v74, v91, v77
	v_mul_f32_e32 v73, v83, v73
	v_exp_f32_e32 v75, v82
	v_exp_f32_e32 v77, v84
	v_min_f32_e64 v82, -v85, s60
; __device__ __forceinline__ unsigned cvt_pk_bf16(float lo, float hi) { f32x2_t v = {lo, hi}; bf2_t r = __builtin_convertvector(v, bf2_t); return __builtin_bit_cast(unsigned, r); }
; template <int MODE>
; __device__ __forceinline__ void hgrn_mfma(const Ctx& C, int l, int z, int b, int hd, int c, f32x4 (&Sacc)[4][4], float& dectot, unsigned char* wl, float lb) {
;     ...
;             for (int t = 0; t < 16; ++t) {
;                 const float fl = bf2f(fv[t]);
;                 const float sg = sigmoidf_(fl);
;                 const float f = lb + (1.0f - lb) * sg, kk = (1.0f - lb) * (1.0f - sg);
;                 bacc += __logf(fmaxf(f, 1e-30f));
;                 Kb[(g8 * 16 + t) * HPT + lane] = f2bf(kk * __expf(fminf(-bacc, 80.f)));
;                 if (MODE != 0) Qt[(g8 * 16 + t) * HPT + lane] = f2bf(bf2f(qv[t]) * __expf(fmaxf(bacc, -80.f)));
;                 Vv[(g8 * 16 + t) * HPT + lane] = vv[t];
;             }
;         }
;         { const float eb = __expf(bacc); dl[lane] = eb; dectot *= eb; }
;         wave_lds_fence();
;         f32x4 Oacc[2][4];
;         if (MODE != 0) {
;             bf16x8 Sb[2][4];
; #pragma unroll
;             for (int ks = 0; ks < 2; ++ks)
; #pragma unroll
;                 for (int vt = 0; vt < 4; ++vt) { union { bf16x8 v; unsigned u[4]; } t_;
;                     t_.u[0] = cvt_pk_bf16(Sacc[2 * ks][vt][0], Sacc[2 * ks][vt][1]); t_.u[1] = cvt_pk_bf16(Sacc[2 * ks][vt][2], Sacc[2 * ks][vt][3]);
;                     t_.u[2] = cvt_pk_bf16(Sacc[2 * ks + 1][vt][0], Sacc[2 * ks + 1][vt][1]); t_.u[3] = cvt_pk_bf16(Sacc[2 * ks + 1][vt][2], Sacc[2 * ks + 1][vt][3]); Sb[ks][vt] = t_.v; }
;             float zz = 0.f; asm volatile("" : "+v"(zz));
; #pragma unroll
;             for (int tt = 0; tt < 2; ++tt)
; #pragma unroll
;                 for (int vt = 0; vt < 4; ++vt) Oacc[tt][vt] = (f32x4){zz, zz, zz, zz};
; #pragma unroll
;             for (int tt = 0; tt < 2; ++tt)
; #pragma unroll
;                 for (int ks = 0; ks < 2; ++ks) { const bf16_t* qp = Qt + (16 * tt + fr) * HPT + 32 * ks + 4 * quad;
;                     union { bf16x8 v; u32x2 h[2]; } a_; a_.h[0] = *(const u32x2*)qp; a_.h[1] = *(const u32x2*)(qp + 16);
; #pragma unroll
;                     for (int vt = 0; vt < 4; ++vt) Oacc[tt][vt] = __builtin_amdgcn_mfma_f32_16x16x32_bf16(a_.v, Sb[ks][vt], Oacc[tt][vt], 0, 0, 0); }
	v_max_f32_e32 v83, 0xc2a00000, v85
	v_sub_f32_e32 v84, v86, v180
	v_fmac_f32_e32 v87, 0x3f317217, v95
	v_cmp_lt_f32_e64 s[0:1], |v95|, s57
	v_fma_f32 v86, v98, s56, -v88
	v_mul_f32_e32 v82, 0x3fb8aa3b, v82
	v_cvt_pk_bf16_f32 v74, v74, s0
	v_cvt_pk_bf16_f32 v73, v73, s0
	v_mul_f32_e32 v83, 0x3fb8aa3b, v83
	v_add_f32_e32 v84, v85, v84
	v_cndmask_b32_e64 v85, v95, v87, s[0:1]
	v_fmac_f32_e32 v86, 0x3377d1cf, v98
	v_mul_f32_e32 v87, 0x3f317217, v92
	v_sub_f32_e32 v93, 1.0, v93
	ds_write_b16 v60, v74 offset:5760
	ds_write_b16 v60, v73 offset:1152
	v_mul_f32_e32 v61, v61, v76
	v_mul_f32_e32 v72, v78, v72
	v_exp_f32_e32 v73, v82
	v_exp_f32_e32 v74, v83
	v_min_f32_e64 v76, -v84, s60
	v_max_f32_e32 v78, 0xc2a00000, v84
	v_sub_f32_e32 v82, v85, v103
	v_fmac_f32_e32 v86, 0x3f317217, v98
	v_cmp_lt_f32_e64 s[0:1], |v98|, s57
	v_fma_f32 v83, v92, s56, -v87
	v_mul_f32_e32 v93, v194, v93
	v_cvt_pk_bf16_f32 v61, v61, s0
	v_cvt_pk_bf16_f32 v72, v72, s0
	v_mul_f32_e32 v76, 0x3fb8aa3b, v76
	v_mul_f32_e32 v78, 0x3fb8aa3b, v78
	v_add_f32_e32 v82, v84, v82
	v_cndmask_b32_e64 v84, v98, v86, s[0:1]
	v_fmac_f32_e32 v83, 0x3377d1cf, v92
	v_sub_f32_e32 v89, 1.0, v89
	ds_write_b16 v60, v61 offset:5904
	ds_write_b16 v60, v72 offset:1296
	v_mul_f32_e32 v61, v93, v75
	v_mul_f32_e32 v71, v77, v71
	v_exp_f32_e32 v72, v76
	v_exp_f32_e32 v75, v78
	v_min_f32_e64 v76, -v82, s60
	v_max_f32_e32 v77, 0xc2a00000, v82
	v_sub_f32_e32 v78, v84, v99
	v_fmac_f32_e32 v83, 0x3f317217, v92
	v_cmp_lt_f32_e64 s[0:1], |v92|, s57
	v_mul_f32_e32 v89, v194, v89
	v_mul_f32_e32 v76, 0x3fb8aa3b, v76
	v_cvt_pk_bf16_f32 v61, v61, s0
	v_cvt_pk_bf16_f32 v71, v71, s0
	v_mul_f32_e32 v77, 0x3fb8aa3b, v77
	v_add_f32_e32 v78, v82, v78
	v_cndmask_b32_e64 v82, v92, v83, s[0:1]
	ds_write_b16 v60, v61 offset:6048
	ds_write_b16 v60, v71 offset:1440
	v_mul_f32_e32 v61, v89, v73
	v_mul_f32_e32 v62, v74, v62
	v_exp_f32_e32 v71, v76
	v_exp_f32_e32 v73, v77
	v_min_f32_e64 v74, -v78, s60
	v_sub_f32_e32 v77, v82, v100
	v_max_f32_e32 v76, 0xc2a00000, v78
	v_cvt_pk_bf16_f32 v82, v61, s0
	v_cvt_pk_bf16_f32 v62, v62, s0
	v_mul_f32_e32 v74, 0x3fb8aa3b, v74
	v_add_f32_e32 v61, v78, v77
	v_mul_f32_e32 v76, 0x3fb8aa3b, v76
	ds_write_b16 v60, v82 offset:6192
	ds_write_b16 v60, v62 offset:1584
	v_mul_f32_e32 v62, v81, v72
	v_mul_f32_e32 v63, v75, v63
	v_exp_f32_e32 v72, v74
	v_min_f32_e64 v75, -v61, s60
	v_exp_f32_e32 v74, v76
	v_max_f32_e32 v76, 0xc2a00000, v61
	v_cvt_pk_bf16_f32 v62, v62, s0
	v_cvt_pk_bf16_f32 v63, v63, s0
	v_mul_f32_e32 v75, 0x3fb8aa3b, v75
	v_sub_f32_e32 v102, 1.0, v102
	v_mul_f32_e32 v76, 0x3fb8aa3b, v76
	ds_write_b16 v60, v62 offset:6336
	ds_write_b16 v60, v63 offset:1728
	v_mul_f32_e32 v62, v80, v71
	v_mul_f32_e32 v63, v73, v64
	v_exp_f32_e32 v64, v75
	v_mul_f32_e32 v102, v194, v102
	v_exp_f32_e32 v71, v76
	v_cvt_pk_bf16_f32 v62, v62, s0
	v_sub_f32_e32 v96, 1.0, v96
	v_cvt_pk_bf16_f32 v63, v63, s0
	ds_write_b16 v60, v62 offset:6480
	ds_write_b16 v60, v63 offset:1872
	v_mul_f32_e32 v62, v102, v72
	v_mul_f32_e32 v96, v194, v96
	v_mul_f32_e32 v63, v74, v70
	v_cvt_pk_bf16_f32 v62, v62, s0
	v_cvt_pk_bf16_f32 v63, v63, s0
	ds_write_b16 v60, v62 offset:6624
	ds_write_b16 v60, v63 offset:2016
	v_mul_f32_e32 v62, v96, v64
	v_mul_f32_e32 v63, v71, v79
	v_cvt_pk_bf16_f32 v62, v62, s0
	v_cvt_pk_bf16_f32 v63, v63, s0
	ds_write_b16 v60, v62 offset:6768
	ds_write_b16 v60, v63 offset:2160
	s_cbranch_vccz .LBB0_645
	v_mul_f32_e32 v60, 0x3fb8aa3b, v61
	v_exp_f32_e32 v60, v60
	v_mov_b32_e32 v98, v65
	v_cvt_pk_bf16_f32 v61, v2, v3
	v_cvt_pk_bf16_f32 v62, v16, v17
	ds_write_b32 v119, v60 offset:13824
	s_waitcnt lgkmcnt(0)
	ds_read2_b64 v[102:105], v126 offset1:4
	ds_read2_b64 v[188:191], v126 offset0:8 offset1:12
	v_cvt_pk_bf16_f32 v60, v0, v1
	v_cvt_pk_bf16_f32 v63, v18, v19
	v_cvt_pk_bf16_f32 v70, v4, v5
	v_cvt_pk_bf16_f32 v71, v6, v7
	v_cvt_pk_bf16_f32 v72, v20, v21
	v_cvt_pk_bf16_f32 v73, v22, v23
	v_cvt_pk_bf16_f32 v78, v8, v9
	v_cvt_pk_bf16_f32 v79, v10, v11
	v_cvt_pk_bf16_f32 v80, v24, v25
	v_cvt_pk_bf16_f32 v81, v26, v27
	v_cvt_pk_bf16_f32 v86, v12, v13
	v_cvt_pk_bf16_f32 v87, v14, v15
	v_cvt_pk_bf16_f32 v88, v28, v29
	v_cvt_pk_bf16_f32 v89, v30, v31
	v_mov_b32_e32 v99, v98
	v_mov_b32_e32 v100, v98
	v_mov_b32_e32 v101, v98
	v_cvt_pk_bf16_f32 v74, v32, v33
	v_cvt_pk_bf16_f32 v75, v34, v35
	s_waitcnt lgkmcnt(1)
	v_mfma_f32_16x16x32_bf16 v[106:109], v[102:105], v[60:63], v[98:101]
	v_cvt_pk_bf16_f32 v76, v48, v49
	v_cvt_pk_bf16_f32 v77, v50, v51
	v_cvt_pk_bf16_f32 v82, v36, v37
	v_mfma_f32_16x16x32_bf16 v[110:113], v[102:105], v[70:73], v[98:101]
	v_cvt_pk_bf16_f32 v83, v38, v39
	v_cvt_pk_bf16_f32 v84, v66, v67
	v_cvt_pk_bf16_f32 v85, v68, v69
	v_mfma_f32_16x16x32_bf16 v[178:181], v[102:105], v[78:81], v[98:101]
	v_cvt_pk_bf16_f32 v90, v40, v41
	v_cvt_pk_bf16_f32 v91, v42, v43
	v_cvt_pk_bf16_f32 v92, v56, v57
	v_mfma_f32_16x16x32_bf16 v[102:105], v[102:105], v[86:89], v[98:101]
	v_cvt_pk_bf16_f32 v93, v58, v59
	v_cvt_pk_bf16_f32 v94, v44, v45
	v_cvt_pk_bf16_f32 v95, v46, v47
	v_cvt_pk_bf16_f32 v96, v52, v53
	v_cvt_pk_bf16_f32 v97, v54, v55
	v_add_u32_e32 v64, 0x800, v126
	s_waitcnt lgkmcnt(0)
	v_mfma_f32_16x16x32_bf16 v[106:109], v[188:191], v[74:77], v[106:109]
	s_add_i32 s72, s72, 1
	s_cmp_eq_u32 s72, 4
	v_mfma_f32_16x16x32_bf16 v[110:113], v[188:191], v[82:85], v[110:113]
	v_mfma_f32_16x16x32_bf16 v[178:181], v[188:191], v[90:93], v[178:181]
	v_mfma_f32_16x16x32_bf16 v[102:105], v[188:191], v[94:97], v[102:105]
	ds_read2_b64 v[188:191], v64 offset0:32 offset1:36
	s_waitcnt lgkmcnt(0)
; template <int MODE>
; __device__ __forceinline__ void hgrn_mfma(const Ctx& C, int l, int z, int b, int hd, int c, f32x4 (&Sacc)[4][4], float& dectot, unsigned char* wl, float lb) {
;     ...
;             f32x4 P00 = {zz, zz, zz, zz}, P01 = {zz, zz, zz, zz}, P11 = {zz, zz, zz, zz};
; #pragma unroll
;             for (int ks = 0; ks < 2; ++ks) {
;                 const bf16x8 kA0 = *(const bf16x8*)(Kb + fr * HPT + 32 * ks + 8 * quad), kA1 = *(const bf16x8*)(Kb + (16 + fr) * HPT + 32 * ks + 8 * quad);
;                 const bf16x8 qB0 = *(const bf16x8*)(Qt + fr * HPT + 32 * ks + 8 * quad), qB1 = *(const bf16x8*)(Qt + (16 + fr) * HPT + 32 * ks + 8 * quad);
;                 P00 = __builtin_amdgcn_mfma_f32_16x16x32_bf16(kA0, qB0, P00, 0, 0, 0);
;                 P01 = __builtin_amdgcn_mfma_f32_16x16x32_bf16(kA0, qB1, P01, 0, 0, 0);
;                 P11 = __builtin_amdgcn_mfma_f32_16x16x32_bf16(kA1, qB1, P11, 0, 0, 0);
;             }
; #pragma unroll
;             for (int r = 0; r < 4; ++r) if (4 * quad + r > fr) { P00[r] = 0.f; P11[r] = 0.f; }
;             union { bf16x8 v; unsigned u[4]; } pa0, pa1;
;             pa0.u[0] = cvt_pk_bf16(P00[0], P00[1]); pa0.u[1] = cvt_pk_bf16(P00[2], P00[3]); pa0.u[2] = 0u; pa0.u[3] = 0u;
;             pa1.u[0] = cvt_pk_bf16(P01[0], P01[1]); pa1.u[1] = cvt_pk_bf16(P01[2], P01[3]); pa1.u[2] = cvt_pk_bf16(P11[0], P11[1]); pa1.u[3] = cvt_pk_bf16(P11[2], P11[3]);
; #pragma unroll
;             for (int vt = 0; vt < 4; ++vt) { const bf16_t* vp = Vv + (4 * quad + (fr >> 2)) * HPT + 16 * vt + 4 * (fr & 3);
;                 union { bf16x8 v; s16x4 h[2]; } vb; vb.h[0] = lds_tr(vp); vb.h[1] = lds_tr(vp + 16 * HPT);
;                 Oacc[0][vt] = __builtin_amdgcn_mfma_f32_16x16x32_bf16(pa0.v, vb.v, Oacc[0][vt], 0, 0, 0);
;                 Oacc[1][vt] = __builtin_amdgcn_mfma_f32_16x16x32_bf16(pa1.v, vb.v, Oacc[1][vt], 0, 0, 0); }
;         }
;         {
;             bf16x8 vB[4];
; #pragma unroll
;             for (int vt = 0; vt < 4; ++vt) { const bf16_t* vp = Vv + (8 * quad + (fr >> 2)) * HPT + 16 * vt + 4 * (fr & 3);
;                 union { bf16x8 v; s16x4 h[2]; } vb; vb.h[0] = lds_tr(vp); vb.h[1] = lds_tr(vp + 4 * HPT); vB[vt] = vb.v; }
; #pragma unroll
;             for (int kt = 0; kt < 4; ++kt) { const bf16_t* kp = Kb + (8 * quad + (fr >> 2)) * HPT + 16 * kt + 4 * (fr & 3);
	v_mfma_f32_16x16x32_bf16 v[60:63], v[188:191], v[60:63], v[98:101]
	v_mfma_f32_16x16x32_bf16 v[70:73], v[188:191], v[70:73], v[98:101]
	v_mfma_f32_16x16x32_bf16 v[78:81], v[188:191], v[78:81], v[98:101]
	v_mfma_f32_16x16x32_bf16 v[86:89], v[188:191], v[86:89], v[98:101]
	ds_read2_b64 v[188:191], v64 offset0:40 offset1:44
	s_waitcnt lgkmcnt(0)
	v_mfma_f32_16x16x32_bf16 v[74:77], v[188:191], v[74:77], v[60:63]
	v_mfma_f32_16x16x32_bf16 v[206:209], v[188:191], v[82:85], v[70:73]
	v_mfma_f32_16x16x32_bf16 v[78:81], v[188:191], v[90:93], v[78:81]
	v_mfma_f32_16x16x32_bf16 v[188:191], v[188:191], v[94:97], v[86:89]
	ds_read_b128 v[60:63], v123 offset:4608
	ds_read_b128 v[70:73], v123 offset:6912
	ds_read_b128 v[82:85], v123
	ds_read_b128 v[86:89], v123 offset:2304
	ds_read_b128 v[90:93], v123 offset:4672
	ds_read_b128 v[94:97], v123 offset:6976
	ds_read_b128 v[210:213], v123 offset:64
	ds_read_b128 v[228:231], v123 offset:2368
	s_waitcnt lgkmcnt(5)
	v_mfma_f32_16x16x32_bf16 v[82:85], v[60:63], v[82:85], v[98:101]
	s_waitcnt lgkmcnt(4)
	v_mfma_f32_16x16x32_bf16 v[70:73], v[70:73], v[86:89], v[98:101]
	s_waitcnt lgkmcnt(1)
	v_mfma_f32_16x16x32_bf16 v[82:85], v[90:93], v[210:213], v[82:85]
	s_waitcnt lgkmcnt(0)
	v_mfma_f32_16x16x32_bf16 v[70:73], v[94:97], v[228:231], v[70:73]
	v_mfma_f32_16x16x32_bf16 v[60:63], v[60:63], v[86:89], v[98:101]
	s_nop 4
	v_cndmask_b32_e64 v64, v85, 0, s[42:43]
	s_nop 0
	v_cndmask_b32_e64 v85, v73, 0, s[42:43]
	v_cndmask_b32_e64 v94, v72, 0, s[20:21]
	v_cndmask_b32_e64 v95, v71, 0, s[38:39]
	v_cndmask_b32_e64 v96, v70, 0, s[44:45]
	v_mfma_f32_16x16x32_bf16 v[70:73], v[90:93], v[228:231], v[60:63]
	v_cndmask_b32_e64 v84, v84, 0, s[20:21]
	v_cndmask_b32_e64 v83, v83, 0, s[38:39]
	v_cndmask_b32_e64 v82, v82, 0, s[44:45]
	v_cvt_pk_bf16_f32 v62, v82, v83
	v_cvt_pk_bf16_f32 v63, v84, v64
	v_mov_b32_e32 v64, v65
	s_nop 1
	v_cvt_pk_bf16_f32 v98, v70, v71
	v_cvt_pk_bf16_f32 v99, v72, v73
	ds_read_b64_tr_b16 v[72:73], v124 offset:11520
	ds_read_b64_tr_b16 v[70:71], v124 offset:9216
	ds_read_b64_tr_b16 v[90:91], v124 offset:9248
	v_cvt_pk_bf16_f32 v100, v96, v95
	v_cvt_pk_bf16_f32 v101, v94, v85
	s_waitcnt lgkmcnt(1)
	v_mfma_f32_16x16x32_bf16 v[82:85], v[62:65], v[70:73], v[106:109]
	ds_read_b64_tr_b16 v[92:93], v124 offset:11552
	ds_read_b64_tr_b16 v[94:95], v124 offset:9280
	ds_read_b64_tr_b16 v[96:97], v124 offset:11584
	ds_read_b64_tr_b16 v[106:107], v124 offset:9312
	ds_read_b64_tr_b16 v[108:109], v124 offset:11616
	v_mfma_f32_16x16x32_bf16 v[70:73], v[98:101], v[70:73], v[74:77]
	s_waitcnt lgkmcnt(4)
	v_mfma_f32_16x16x32_bf16 v[86:89], v[62:65], v[90:93], v[110:113]
	v_mfma_f32_16x16x32_bf16 v[74:77], v[98:101], v[90:93], v[206:209]
	s_waitcnt lgkmcnt(2)
	v_mfma_f32_16x16x32_bf16 v[90:93], v[62:65], v[94:97], v[178:181]
	v_mfma_f32_16x16x32_bf16 v[78:81], v[98:101], v[94:97], v[78:81]
	s_waitcnt lgkmcnt(0)
	v_mfma_f32_16x16x32_bf16 v[94:97], v[62:65], v[106:109], v[102:105]
	v_add_u32_e32 v64, v122, v121
	v_mfma_f32_16x16x32_bf16 v[60:63], v[98:101], v[106:109], v[188:191]
	ds_read_b64_tr_b16 v[110:111], v125 offset:9216
	ds_read_b64_tr_b16 v[112:113], v125 offset:9792
	ds_read_b64_tr_b16 v[106:107], v125 offset:9248
	ds_read_b64_tr_b16 v[108:109], v125 offset:9824
	ds_read_b64_tr_b16 v[102:103], v125 offset:9280
	ds_read_b64_tr_b16 v[104:105], v125 offset:9856
	ds_read_b64_tr_b16 v[98:99], v125 offset:9312
	ds_read_b64_tr_b16 v[100:101], v125 offset:9888
	ds_read_b64_tr_b16 v[180:181], v125 offset:5184
	ds_read_b64_tr_b16 v[178:179], v125 offset:4608
	ds_read_b64_tr_b16 v[188:189], v125 offset:4640
	ds_read_b128 v[206:209], v64 offset:13824
	v_cvt_pk_bf16_f32 v60, v60, s0
	s_waitcnt lgkmcnt(2)
	v_mfma_f32_16x16x32_bf16 v[0:3], v[178:181], v[110:113], v[0:3]
	v_cvt_pk_bf16_f32 v62, v62, s0
	v_mfma_f32_16x16x32_bf16 v[4:7], v[178:181], v[106:109], v[4:7]
	v_mfma_f32_16x16x32_bf16 v[8:11], v[178:181], v[102:105], v[8:11]
	s_waitcnt lgkmcnt(0)
	s_nop 3
	v_pk_mul_f32 v[2:3], v[208:209], v[2:3]
	v_pk_mul_f32 v[0:1], v[206:207], v[0:1]
	v_pk_mul_f32 v[6:7], v[208:209], v[6:7]
	v_mfma_f32_16x16x32_bf16 v[12:15], v[178:181], v[98:101], v[12:15]
	ds_read_b64_tr_b16 v[190:191], v125 offset:5216
	ds_read_b128 v[178:181], v64 offset:13888
	v_pk_mul_f32 v[4:5], v[206:207], v[4:5]
	v_pk_mul_f32 v[10:11], v[208:209], v[10:11]
	s_waitcnt lgkmcnt(1)
	v_mfma_f32_16x16x32_bf16 v[16:19], v[188:191], v[110:113], v[16:19]
	v_mul_f32_e64 v8, v206, v8
	v_mul_f32_e64 v9, v207, v9
	v_pk_mul_f32 v[14:15], v[208:209], v[14:15]
	v_pk_mul_f32 v[12:13], v[206:207], v[12:13]
	v_mfma_f32_16x16x32_bf16 v[20:23], v[188:191], v[106:109], v[20:23]
	s_waitcnt lgkmcnt(0)
	s_nop 1
	v_pk_mul_f32 v[18:19], v[180:181], v[18:19]
	v_pk_mul_f32 v[16:17], v[178:179], v[16:17]
	v_mfma_f32_16x16x32_bf16 v[24:27], v[188:191], v[102:105], v[24:27]
	v_mfma_f32_16x16x32_bf16 v[28:31], v[188:191], v[98:101], v[28:31]
	s_nop 0
	v_mul_f32_e64 v22, v180, v22
	v_mul_f32_e64 v23, v181, v23
	v_pk_mul_f32 v[20:21], v[178:179], v[20:21]
	s_nop 2
	v_pk_mul_f32 v[26:27], v[180:181], v[26:27]
	v_pk_mul_f32 v[24:25], v[178:179], v[24:25]
	v_pk_mul_f32 v[30:31], v[180:181], v[30:31]
	v_pk_mul_f32 v[28:29], v[178:179], v[28:29]
	ds_read_b64_tr_b16 v[178:179], v125 offset:4672
	ds_read_b64_tr_b16 v[180:181], v125 offset:5248
	ds_read_b128 v[188:191], v64 offset:13952
	s_waitcnt lgkmcnt(1)
; __device__ __forceinline__ bf16_t f2bf(float f) { return (bf16_t)(cvt_pk_bf16(f, 0.f) & 0xffffu); }
; template <int MODE>
; __device__ __forceinline__ void hgrn_mfma(const Ctx& C, int l, int z, int b, int hd, int c, f32x4 (&Sacc)[4][4], float& dectot, unsigned char* wl, float lb) {
;     ...
;             for (int kt = 0; kt < 4; ++kt) { const bf16_t* kp = Kb + (8 * quad + (fr >> 2)) * HPT + 16 * kt + 4 * (fr & 3);
;                 union { bf16x8 v; s16x4 h[2]; } ka; ka.h[0] = lds_tr(kp); ka.h[1] = lds_tr(kp + 4 * HPT);
;                 const f32x4 d4 = *(const f32x4*)(dl + 16 * kt + 4 * quad);
; #pragma unroll
;                 for (int vt = 0; vt < 4; ++vt) { Sacc[kt][vt] = __builtin_amdgcn_mfma_f32_16x16x32_bf16(ka.v, vB[vt], Sacc[kt][vt], 0, 0, 0); Sacc[kt][vt] *= d4; } }
;         }
;         if (MODE == 1) {
; #pragma unroll
;             for (int tt = 0; tt < 2; ++tt)
; #pragma unroll
;                 for (int r = 0; r < 4; ++r) { const int st = c * 128 + sc * 32 + 16 * tt + 4 * quad + r; const int tq = z ? 4095 - st : st;
;                     bf16_t* yp = ya + (size_t)(b * SEQ + tq) * 256 + hd * 64 + fr;
; #pragma unroll
;                     for (int vt = 0; vt < 4; ++vt) yp[16 * vt] = f2bf(Oacc[tt][vt][r]); }
	v_mfma_f32_16x16x32_bf16 v[32:35], v[178:181], v[110:113], v[32:35]
	v_mfma_f32_16x16x32_bf16 v[36:39], v[178:181], v[106:109], v[36:39]
	s_waitcnt lgkmcnt(0)
	s_nop 5
	v_pk_mul_f32 v[34:35], v[190:191], v[34:35]
	v_pk_mul_f32 v[32:33], v[188:189], v[32:33]
	v_mfma_f32_16x16x32_bf16 v[40:43], v[178:181], v[102:105], v[40:43]
	v_mfma_f32_16x16x32_bf16 v[44:47], v[178:181], v[98:101], v[44:47]
	v_mul_f32_e64 v38, v190, v38
	v_mul_f32_e64 v39, v191, v39
	v_pk_mul_f32 v[36:37], v[188:189], v[36:37]
	s_nop 3
	v_pk_mul_f32 v[42:43], v[190:191], v[42:43]
	v_pk_mul_f32 v[40:41], v[188:189], v[40:41]
	v_pk_mul_f32 v[46:47], v[190:191], v[46:47]
	v_pk_mul_f32 v[44:45], v[188:189], v[44:45]
	ds_read_b64_tr_b16 v[178:179], v125 offset:4704
	ds_read_b64_tr_b16 v[180:181], v125 offset:5280
	ds_read_b128 v[188:191], v64 offset:14016
	s_waitcnt lgkmcnt(1)
	v_mfma_f32_16x16x32_bf16 v[52:55], v[178:181], v[98:101], v[52:55]
	v_add_u32_e32 v98, s36, v195
	v_ashrrev_i32_e32 v99, 31, v98
	v_lshlrev_b64 v[98:99], 9, v[98:99]
	v_lshl_add_u64 v[98:99], v[116:117], 0, v[98:99]
	v_cvt_pk_bf16_f32 v64, v82, s0
	global_store_short v[98:99], v64, off
	v_cvt_pk_bf16_f32 v64, v86, s0
	global_store_short v[98:99], v64, off offset:32
	v_cvt_pk_bf16_f32 v64, v90, s0
	global_store_short v[98:99], v64, off offset:64
	v_cvt_pk_bf16_f32 v64, v94, s0
	global_store_short v[98:99], v64, off offset:96
	v_add_u32_e32 v98, s36, v196
	v_ashrrev_i32_e32 v99, 31, v98
	v_lshlrev_b64 v[98:99], 9, v[98:99]
	v_lshl_add_u64 v[98:99], v[116:117], 0, v[98:99]
	v_cvt_pk_bf16_f32 v64, v83, s0
	global_store_short v[98:99], v64, off
	v_cvt_pk_bf16_f32 v64, v87, s0
	v_add_u32_e32 v82, s36, v197
	global_store_short v[98:99], v64, off offset:32
	v_cvt_pk_bf16_f32 v64, v91, s0
	v_ashrrev_i32_e32 v83, 31, v82
	global_store_short v[98:99], v64, off offset:64
	v_cvt_pk_bf16_f32 v64, v95, s0
	v_lshlrev_b64 v[82:83], 9, v[82:83]
	global_store_short v[98:99], v64, off offset:96
	v_lshl_add_u64 v[82:83], v[116:117], 0, v[82:83]
	v_cvt_pk_bf16_f32 v64, v84, s0
	global_store_short v[82:83], v64, off
	v_cvt_pk_bf16_f32 v64, v88, s0
	global_store_short v[82:83], v64, off offset:32
	v_cvt_pk_bf16_f32 v64, v92, s0
	global_store_short v[82:83], v64, off offset:64
	v_cvt_pk_bf16_f32 v64, v96, s0
	global_store_short v[82:83], v64, off offset:96
	v_add_u32_e32 v82, s36, v198
	v_ashrrev_i32_e32 v83, 31, v82
	v_lshlrev_b64 v[82:83], 9, v[82:83]
	v_lshl_add_u64 v[82:83], v[116:117], 0, v[82:83]
	v_cvt_pk_bf16_f32 v64, v85, s0
	global_store_short v[82:83], v64, off
	v_cvt_pk_bf16_f32 v64, v89, s0
	global_store_short v[82:83], v64, off offset:32
	v_cvt_pk_bf16_f32 v64, v93, s0
	global_store_short v[82:83], v64, off offset:64
	v_cvt_pk_bf16_f32 v64, v97, s0
	global_store_short v[82:83], v64, off offset:96
	v_add_u32_e32 v82, s36, v199
	v_ashrrev_i32_e32 v83, 31, v82
	v_lshlrev_b64 v[82:83], 9, v[82:83]
	v_lshl_add_u64 v[82:83], v[116:117], 0, v[82:83]
	v_cvt_pk_bf16_f32 v64, v70, s0
	global_store_short v[82:83], v64, off
	v_cvt_pk_bf16_f32 v64, v74, s0
	global_store_short v[82:83], v64, off offset:32
	v_cvt_pk_bf16_f32 v64, v78, s0
	global_store_short v[82:83], v64, off offset:64
	global_store_short v[82:83], v60, off offset:96
	v_add_u32_e32 v82, s36, v200
	v_ashrrev_i32_e32 v83, 31, v82
	v_lshlrev_b64 v[82:83], 9, v[82:83]
	v_lshl_add_u64 v[82:83], v[116:117], 0, v[82:83]
	v_cvt_pk_bf16_f32 v60, v71, s0
	global_store_short v[82:83], v60, off
	v_cvt_pk_bf16_f32 v60, v75, s0
	global_store_short v[82:83], v60, off offset:32
	v_cvt_pk_bf16_f32 v60, v79, s0
	global_store_short v[82:83], v60, off offset:64
	v_cvt_pk_bf16_f32 v60, v61, s0
	global_store_short v[82:83], v60, off offset:96
	v_add_u32_e32 v60, s36, v201
	v_ashrrev_i32_e32 v61, 31, v60
	v_lshlrev_b64 v[60:61], 9, v[60:61]
	v_lshl_add_u64 v[60:61], v[116:117], 0, v[60:61]
	v_cvt_pk_bf16_f32 v64, v72, s0
	global_store_short v[60:61], v64, off
	v_cvt_pk_bf16_f32 v64, v76, s0
	global_store_short v[60:61], v64, off offset:32
	v_cvt_pk_bf16_f32 v64, v80, s0
	global_store_short v[60:61], v64, off offset:64
	global_store_short v[60:61], v62, off offset:96
	v_add_u32_e32 v60, s36, v202
	v_ashrrev_i32_e32 v61, 31, v60
	v_lshlrev_b64 v[60:61], 9, v[60:61]
	v_lshl_add_u64 v[60:61], v[116:117], 0, v[60:61]
	v_cvt_pk_bf16_f32 v62, v73, s0
	global_store_short v[60:61], v62, off
	v_cvt_pk_bf16_f32 v62, v77, s0
	global_store_short v[60:61], v62, off offset:32
	v_cvt_pk_bf16_f32 v62, v81, s0
	v_mfma_f32_16x16x32_bf16 v[48:51], v[178:181], v[110:113], v[48:51]
	global_store_short v[60:61], v62, off offset:64
	v_cvt_pk_bf16_f32 v62, v63, s0
	global_store_short v[60:61], v62, off offset:96
	v_mfma_f32_16x16x32_bf16 v[66:69], v[178:181], v[106:109], v[66:69]
	s_waitcnt lgkmcnt(0)
	s_waitcnt lgkmcnt(0)
	s_nop 2
	v_pk_mul_f32 v[50:51], v[190:191], v[50:51]
	v_pk_mul_f32 v[48:49], v[188:189], v[48:49]
	v_mfma_f32_16x16x32_bf16 v[56:59], v[178:181], v[102:105], v[56:59]
	v_mul_f32_e64 v54, v190, v54
	v_mul_f32_e64 v55, v191, v55
	v_pk_mul_f32 v[68:69], v[190:191], v[68:69]
	v_pk_mul_f32 v[66:67], v[188:189], v[66:67]
	v_pk_mul_f32 v[52:53], v[188:189], v[52:53]
	s_nop 2
	v_pk_mul_f32 v[58:59], v[190:191], v[58:59]
	v_pk_mul_f32 v[56:57], v[188:189], v[56:57]
	s_cbranch_scc0 .LBB0_644
	v_readlane_b32 s0, v254, 20
	s_add_i32 s48, s48, s0
	s_cmpk_gt_i32 s48, 0x3ff
	v_readlane_b32 s1, v254, 21
	s_cbranch_scc0 .LBB0_641

; __device__ __forceinline__ bf16_t f2bf(float f) { return (bf16_t)(cvt_pk_bf16(f, 0.f) & 0xffffu); }
; __device__ __forceinline__ float bf2f(bf16_t b) { return __uint_as_float(((unsigned)b) << 16); }
; __device__ __forceinline__ float sigmoidf_(float x) { return 1.0f / (1.0f + __expf(-x)); }
; template <int MODE>
; __device__ __forceinline__ void hgrn_mfma(const Ctx& C, int l, int z, int b, int hd, int c, f32x4 (&Sacc)[4][4], float& dectot, unsigned char* wl, float lb) {
;     ...
;             const int st0 = c * 128 + sc * 32 + g8 * 16; const int tq0 = z ? 4095 - st0 : st0;
;             const bf16_t* row0 = pa + (size_t)(b * SEQ + tq0) * 1280; const ptrdiff_t rstep = z ? -1280 : 1280;
; #pragma unroll
;             for (int t = 0; t < 16; ++t) { const bf16_t* row = row0 + rstep * t; fv[t] = row[fcol]; vv[t] = row[vcol]; if (MODE != 0) qv[t] = row[qcol]; }
; #pragma unroll
;             for (int t = 0; t < 16; ++t) {
;                 const float fl = bf2f(fv[t]);
;                 const float sg = sigmoidf_(fl);
;                 const float f = lb + (1.0f - lb) * sg, kk = (1.0f - lb) * (1.0f - sg);
;                 bacc += __logf(fmaxf(f, 1e-30f));
;                 Kb[(g8 * 16 + t) * HPT + lane] = f2bf(kk * __expf(fminf(-bacc, 80.f)));
;                 if (MODE != 0) Qt[(g8 * 16 + t) * HPT + lane] = f2bf(bf2f(qv[t]) * __expf(fmaxf(bacc, -80.f)));
.LBB0_743:
	s_lshl_b32 s0, s67, 4
	v_cndmask_b32_e64 v61, 0, 1, s[52:53]
	s_mul_i32 s1, s67, 0x480
	s_or_b32 s0, s0, s76
	v_cmp_ne_u32_e64 s[4:5], 1, v61
	v_or_b32_e32 v61, s1, v132
	s_mul_hi_i32 s1, s0, 0xa00
	s_mulk_i32 s0, 0xa00
	s_add_u32 s0, s44, s0
	v_lshlrev_b32_e32 v62, 1, v207
	s_addc_u32 s1, s45, s1
	global_load_ushort v63, v62, s[0:1] offset:512
	global_load_ushort v64, v62, s[0:1] offset:1536
	global_load_ushort v70, v62, s[0:1] offset:3072
	global_load_ushort v71, v215, s[0:1] offset:2560
	s_add_u32 s6, s0, 0x1400
	s_addc_u32 s7, s1, 0
	global_load_ushort v72, v228, s[6:7]
	global_load_ushort v73, v62, s[6:7]
	global_load_ushort v74, v215, s[6:7]
	s_add_u32 s6, s0, 0x1e00
	s_addc_u32 s7, s1, 0
	global_load_ushort v75, v228, s[6:7]
	global_load_ushort v76, v62, s[6:7]
	global_load_ushort v77, v215, s[6:7]
	s_add_u32 s6, s0, 0x2800
	s_addc_u32 s7, s1, 0
	global_load_ushort v78, v62, s[6:7]
	global_load_ushort v81, v62, s[0:1] offset:2560
	global_load_ushort v82, v62, s[0:1]
	global_load_ushort v83, v228, s[6:7]
	global_load_ushort v84, v215, s[6:7]
	s_add_u32 s6, s0, 0x3200
	s_addc_u32 s7, s1, 0
	s_add_u32 s8, s0, 0x3c00
	global_load_ushort v85, v215, s[6:7]
	global_load_ushort v86, v228, s[6:7]
	global_load_ushort v87, v62, s[6:7]
	s_addc_u32 s9, s1, 0
	s_add_u32 s6, s0, 0x4600
	global_load_ushort v88, v215, s[8:9]
	global_load_ushort v89, v228, s[8:9]
	global_load_ushort v90, v62, s[8:9]
	s_addc_u32 s7, s1, 0
	s_add_u32 s8, s0, 0x5000
	global_load_ushort v91, v215, s[6:7]
	global_load_ushort v92, v228, s[6:7]
	global_load_ushort v93, v62, s[6:7]
	s_addc_u32 s9, s1, 0
	s_add_u32 s6, s0, 0x5a00
	global_load_ushort v94, v215, s[8:9]
	global_load_ushort v95, v228, s[8:9]
	global_load_ushort v96, v62, s[8:9]
	s_addc_u32 s7, s1, 0
	s_add_u32 s8, s0, 0x6400
	global_load_ushort v97, v215, s[6:7]
	global_load_ushort v98, v228, s[6:7]
	global_load_ushort v99, v62, s[6:7]
	s_addc_u32 s9, s1, 0
	s_add_u32 s6, s0, 0x6e00
	global_load_ushort v100, v215, s[8:9]
	global_load_ushort v101, v228, s[8:9]
	global_load_ushort v110, v62, s[8:9]
	s_addc_u32 s7, s1, 0
	s_add_u32 s8, s0, 0x7800
	global_load_ushort v111, v215, s[6:7]
	global_load_ushort v112, v228, s[6:7]
	global_load_ushort v113, v62, s[6:7]
	s_addc_u32 s9, s1, 0
	global_load_ushort v114, v215, s[8:9]
	global_load_ushort v115, v228, s[8:9]
	global_load_ushort v116, v62, s[8:9]
	s_add_u32 s6, s0, 0x8200
	s_addc_u32 s7, s1, 0
	s_add_u32 s8, s0, 0x8c00
	global_load_ushort v117, v215, s[6:7]
	global_load_ushort v118, v228, s[6:7]
	global_load_ushort v119, v62, s[6:7]
	s_addc_u32 s9, s1, 0
	s_add_u32 s0, s0, 0x9600
	global_load_ushort v120, v215, s[8:9]
	global_load_ushort v121, v228, s[8:9]
	global_load_ushort v122, v62, s[8:9]
	s_addc_u32 s1, s1, 0
	global_load_ushort v123, v215, s[0:1]
	global_load_ushort v124, v228, s[0:1]
	global_load_ushort v125, v62, s[0:1]
	v_lshl_add_u32 v61, v61, 1, s70
	s_mov_b64 s[52:53], 0
	s_mov_b32 s67, 1
	s_waitcnt vmcnt(47)
	v_lshlrev_b32_e32 v62, 16, v63
	v_mul_f32_e32 v62, 0xbfb8aa3b, v62
	s_waitcnt vmcnt(45)
	v_lshlrev_b32_e32 v63, 16, v70
	v_mul_f32_e32 v63, 0xbfb8aa3b, v63
	ds_write_b16 v61, v64 offset:9216
	v_exp_f32_e32 v62, v62
	v_exp_f32_e32 v63, v63
	s_waitcnt vmcnt(43)
	v_lshlrev_b32_e32 v64, 16, v72
	v_mul_f32_e32 v64, 0xbfb8aa3b, v64
	v_exp_f32_e32 v64, v64
	s_waitcnt vmcnt(40)
	v_lshlrev_b32_e32 v70, 16, v75
	v_mul_f32_e32 v70, 0xbfb8aa3b, v70
	v_lshlrev_b32_e32 v80, 16, v73
	v_add_f32_e32 v73, 1.0, v62
	v_add_f32_e32 v63, 1.0, v63
	v_exp_f32_e32 v62, v70
	s_waitcnt vmcnt(34)
	v_lshlrev_b32_e32 v70, 16, v83
	v_mul_f32_e32 v70, 0xbfb8aa3b, v70
	v_add_f32_e32 v128, 1.0, v64
	v_exp_f32_e32 v64, v70
	s_waitcnt vmcnt(31)
	v_lshlrev_b32_e32 v70, 16, v86
	ds_write_b16 v61, v85 offset:9936
	ds_write_b16 v61, v77 offset:9648
	s_waitcnt vmcnt(30)
	v_lshlrev_b32_e32 v77, 16, v87
	v_mul_f32_e32 v70, 0xbfb8aa3b, v70
	v_add_f32_e32 v129, 1.0, v62
	v_exp_f32_e32 v62, v70
	s_waitcnt vmcnt(28)
	v_lshlrev_b32_e32 v70, 16, v89
	ds_write_b16 v61, v88 offset:10080
	ds_write_b16 v61, v71 offset:9360
	ds_write_b16 v61, v74 offset:9504
	s_waitcnt vmcnt(27)
	v_lshlrev_b32_e32 v74, 16, v90
	v_mul_f32_e32 v70, 0xbfb8aa3b, v70
	v_lshlrev_b32_e32 v79, 16, v76
	ds_write_b16 v61, v84 offset:9792
	v_add_f32_e32 v131, 1.0, v64
	v_exp_f32_e32 v64, v70
	s_waitcnt vmcnt(25)
	v_lshlrev_b32_e32 v70, 16, v92
	s_waitcnt vmcnt(24)
	v_lshlrev_b32_e32 v72, 16, v93
	v_mul_f32_e32 v70, 0xbfb8aa3b, v70
	v_add_f32_e32 v180, 1.0, v62
	v_exp_f32_e32 v62, v70
	s_waitcnt vmcnt(22)
	v_lshlrev_b32_e32 v70, 16, v95
	ds_write_b16 v61, v94 offset:10368
	s_waitcnt vmcnt(21)
	v_lshlrev_b32_e32 v71, 16, v96
	v_mul_f32_e32 v70, 0xbfb8aa3b, v70
	v_add_f32_e32 v188, 1.0, v64
	v_exp_f32_e32 v70, v70
	s_waitcnt vmcnt(19)
	v_lshlrev_b32_e32 v98, 16, v98
	ds_write_b16 v61, v97 offset:10512
	v_mul_f32_e32 v97, 0xbfb8aa3b, v98
	s_waitcnt vmcnt(18)
	v_lshlrev_b32_e32 v64, 16, v99
	v_add_f32_e32 v99, 1.0, v62
	v_exp_f32_e32 v97, v97
	s_waitcnt vmcnt(16)
	v_lshlrev_b32_e32 v101, 16, v101
	v_rcp_f32_e32 v73, v73
	ds_write_b16 v61, v91 offset:10224
	ds_write_b16 v61, v100 offset:10656
	v_mul_f32_e32 v93, 0xbfb8aa3b, v101
	v_fma_f32 v100, v213, v73, v208
	v_sub_f32_e32 v73, 1.0, v73
	v_rcp_f32_e32 v75, v63
	s_waitcnt vmcnt(15)
	v_lshlrev_b32_e32 v62, 16, v110
	v_add_f32_e32 v101, 1.0, v70
	v_exp_f32_e32 v93, v93
	s_waitcnt vmcnt(13)
	v_lshlrev_b32_e32 v70, 16, v112
	v_mul_f32_e32 v110, v213, v73
	v_max_f32_e32 v73, 0xda24260, v100
	v_fma_f32 v100, v213, v75, v208
	v_sub_f32_e32 v75, 1.0, v75
	v_rcp_f32_e32 v76, v128
	v_mul_f32_e32 v70, 0xbfb8aa3b, v70
	v_mul_f32_e32 v112, v213, v75
	v_max_f32_e32 v75, 0xda24260, v100
	v_cmp_gt_f32_e32 vcc, s54, v73
	s_waitcnt vmcnt(12)
; __device__ __forceinline__ bf16_t f2bf(float f) { return (bf16_t)(cvt_pk_bf16(f, 0.f) & 0xffffu); }
; __device__ __forceinline__ float bf2f(bf16_t b) { return __uint_as_float(((unsigned)b) << 16); }
; __device__ __forceinline__ float sigmoidf_(float x) { return 1.0f / (1.0f + __expf(-x)); }
; template <int MODE>
; __device__ __forceinline__ void hgrn_mfma(const Ctx& C, int l, int z, int b, int hd, int c, f32x4 (&Sacc)[4][4], float& dectot, unsigned char* wl, float lb) {
;     ...
;             for (int t = 0; t < 16; ++t) {
;                 const float fl = bf2f(fv[t]);
;                 const float sg = sigmoidf_(fl);
;                 const float f = lb + (1.0f - lb) * sg, kk = (1.0f - lb) * (1.0f - sg);
;                 bacc += __logf(fmaxf(f, 1e-30f));
;                 Kb[(g8 * 16 + t) * HPT + lane] = f2bf(kk * __expf(fminf(-bacc, 80.f)));
;                 if (MODE != 0) Qt[(g8 * 16 + t) * HPT + lane] = f2bf(bf2f(qv[t]) * __expf(fmaxf(bacc, -80.f)));
	v_lshlrev_b32_e32 v63, 16, v113
	v_fma_f32 v100, v213, v76, v208
	v_sub_f32_e32 v76, 1.0, v76
	v_add_f32_e32 v97, 1.0, v97
	v_exp_f32_e32 v126, v70
	s_waitcnt vmcnt(9)
	v_lshlrev_b32_e32 v70, 16, v116
	ds_write_b16 v61, v114 offset:10944
	v_cndmask_b32_e64 v114, 0, 32, vcc
	v_cndmask_b32_e32 v116, 0, v225, vcc
	v_cmp_gt_f32_e32 vcc, s54, v75
	v_lshlrev_b32_e32 v115, 16, v115
	v_mul_f32_e32 v127, v213, v76
	v_max_f32_e32 v76, 0xda24260, v100
	v_rcp_f32_e32 v83, v129
	v_cndmask_b32_e64 v128, 0, 32, vcc
	v_cndmask_b32_e32 v129, 0, v225, vcc
	v_mul_f32_e32 v115, 0xbfb8aa3b, v115
	v_ldexp_f32 v114, v73, v114
	v_fma_f32 v130, v213, v83, v208
	v_add_f32_e32 v93, 1.0, v93
	v_cmp_gt_f32_e32 vcc, s54, v76
	v_exp_f32_e32 v115, v115
	s_waitcnt vmcnt(7)
	v_lshlrev_b32_e32 v118, 16, v118
	s_waitcnt vmcnt(6)
	v_lshlrev_b32_e32 v73, 16, v119
	ds_write_b16 v61, v117 offset:11088
	v_log_f32_e32 v114, v114
	v_ldexp_f32 v75, v75, v128
	v_cndmask_b32_e64 v117, 0, 32, vcc
	v_cndmask_b32_e32 v119, 0, v225, vcc
	v_max_f32_e32 v128, 0xda24260, v130
	v_rcp_f32_e32 v85, v131
	v_mul_f32_e32 v118, 0xbfb8aa3b, v118
	v_log_f32_e32 v178, v75
	v_ldexp_f32 v76, v76, v117
	v_fma_f32 v117, v213, v85, v208
	v_cmp_gt_f32_e32 vcc, s54, v128
	ds_write_b16 v61, v111 offset:10800
	v_add_f32_e32 v126, 1.0, v126
	v_exp_f32_e32 v118, v118
	s_waitcnt vmcnt(4)
	v_lshlrev_b32_e32 v121, 16, v121
	s_waitcnt vmcnt(3)
	v_lshlrev_b32_e32 v75, 16, v122
	ds_write_b16 v61, v120 offset:11232
	v_log_f32_e32 v120, v76
	v_cndmask_b32_e64 v76, 0, 32, vcc
	v_cndmask_b32_e32 v122, 0, v225, vcc
	v_max_f32_e32 v117, 0xda24260, v117
	v_rcp_f32_e32 v88, v180
	v_mul_f32_e32 v121, 0xbfb8aa3b, v121
	v_ldexp_f32 v128, v128, v76
	v_fma_f32 v189, v213, v88, v208
	v_cmp_gt_f32_e32 vcc, s54, v117
	v_add_f32_e32 v115, 1.0, v115
	v_exp_f32_e32 v121, v121
	s_waitcnt vmcnt(1)
	v_lshlrev_b32_e32 v124, 16, v124
	s_waitcnt vmcnt(0)
	v_lshlrev_b32_e32 v76, 16, v125
	ds_write_b16 v61, v123 offset:11376
	v_log_f32_e32 v125, v128
	v_cndmask_b32_e64 v128, 0, 32, vcc
	v_cndmask_b32_e32 v190, 0, v225, vcc
	v_max_f32_e32 v189, 0xda24260, v189
	v_rcp_f32_e32 v84, v188
	v_mul_f32_e32 v124, 0xbfb8aa3b, v124
	v_ldexp_f32 v117, v117, v128
	v_fma_f32 v128, v213, v84, v208
	v_cmp_gt_f32_e32 vcc, s54, v189
	v_add_f32_e32 v118, 1.0, v118
	v_exp_f32_e32 v124, v124
	v_log_f32_e32 v117, v117
	v_cndmask_b32_e64 v229, 0, 32, vcc
	v_cndmask_b32_e32 v230, 0, v225, vcc
	v_max_f32_e32 v128, 0xda24260, v128
	v_rcp_f32_e32 v86, v99
	v_ldexp_f32 v189, v189, v229
	v_fma_f32 v229, v213, v86, v208
	v_cmp_gt_f32_e32 vcc, s54, v128
	v_add_f32_e32 v121, 1.0, v121
	v_mul_f32_e32 v114, 0x3f317218, v114
	v_log_f32_e32 v189, v189
	v_cndmask_b32_e64 v231, 0, 32, vcc
	v_cndmask_b32_e32 v232, 0, v225, vcc
	v_max_f32_e32 v229, 0xda24260, v229
	v_rcp_f32_e32 v87, v101
	v_sub_f32_e32 v114, v114, v116
	v_mul_f32_e32 v116, 0x3f317218, v178
	v_ldexp_f32 v128, v128, v231
	v_fma_f32 v178, v213, v87, v208
	v_cmp_gt_f32_e32 vcc, s54, v229
	v_add_f32_e32 v124, 1.0, v124
	v_add_f32_e32 v60, v60, v114
	v_sub_f32_e32 v114, v116, v129
	v_mul_f32_e32 v116, 0x3f317218, v120
	v_log_f32_e32 v128, v128
	v_cndmask_b32_e64 v129, 0, 32, vcc
	v_cndmask_b32_e32 v191, 0, v225, vcc
	v_max_f32_e32 v178, 0xda24260, v178
	v_rcp_f32_e32 v89, v97
	v_min_f32_e64 v223, -v60, s60
	v_max_f32_e32 v231, 0xc2a00000, v60
	v_add_f32_e32 v60, v60, v114
	v_sub_f32_e32 v114, v116, v119
	v_ldexp_f32 v119, v229, v129
	v_cmp_gt_f32_e32 vcc, s54, v178
	v_fma_f32 v120, v213, v89, v208
	v_mul_f32_e32 v181, 0x3fb8aa3b, v223
	v_mul_f32_e32 v223, 0x3fb8aa3b, v231
	v_min_f32_e64 v229, -v60, s60
	v_max_f32_e32 v231, 0xc2a00000, v60
	v_add_f32_e32 v60, v60, v114
	v_mul_f32_e32 v114, 0x3f317218, v125
	v_log_f32_e32 v119, v119
	v_cndmask_b32_e64 v125, 0, 32, vcc
	v_cndmask_b32_e32 v233, 0, v225, vcc
	v_max_f32_e32 v120, 0xda24260, v120
	v_rcp_f32_e32 v90, v93
	v_exp_f32_e32 v97, v181
	v_exp_f32_e32 v180, v223
	v_mul_f32_e32 v181, 0x3fb8aa3b, v229
	v_mul_f32_e32 v223, 0x3fb8aa3b, v231
	v_min_f32_e64 v229, -v60, s60
	v_max_f32_e32 v231, 0xc2a00000, v60
	v_sub_f32_e32 v114, v114, v122
	v_ldexp_f32 v123, v178, v125
	v_fma_f32 v125, v213, v90, v208
	v_exp_f32_e32 v130, v181
	v_exp_f32_e32 v178, v223
	v_mul_f32_e32 v181, 0x3fb8aa3b, v229
	v_mul_f32_e32 v223, 0x3fb8aa3b, v231
	v_add_f32_e32 v60, v60, v114
	v_mul_f32_e32 v114, 0x3f317218, v117
	v_mul_f32_e32 v116, 0x3f317217, v128
	v_log_f32_e32 v117, v123
	v_cmp_gt_f32_e32 vcc, s54, v120
	s_nop 0
	s_nop 0
	v_cndmask_b32_e64 v123, 0, 32, vcc
	v_cndmask_b32_e32 v229, 0, v225, vcc
	v_max_f32_e32 v125, 0xda24260, v125
	v_rcp_f32_e32 v92, v126
	v_exp_f32_e32 v98, v181
	v_exp_f32_e32 v181, v223
	v_min_f32_e64 v188, -v60, s60
	v_max_f32_e32 v223, 0xc2a00000, v60
	v_sub_f32_e32 v114, v114, v190
	v_fma_f32 v116, v128, s56, -v116
	v_lshlrev_b32_e32 v82, 16, v82
	v_ldexp_f32 v120, v120, v123
	v_fma_f32 v123, v213, v92, v208
	v_mul_f32_e32 v126, 0x3fb8aa3b, v188
	v_mul_f32_e32 v188, 0x3fb8aa3b, v223
	v_add_f32_e32 v60, v60, v114
	v_mul_f32_e32 v114, 0x3f317218, v189
	v_fmac_f32_e32 v116, 0x3377d1cf, v128
	v_mul_f32_e32 v122, 0x3f317217, v119
	v_cmp_gt_f32_e32 vcc, s54, v125
	v_lshlrev_b32_e32 v81, 16, v81
	v_log_f32_e32 v120, v120
	v_cndmask_b32_e64 v189, 0, 32, vcc
	v_fmac_f32_e32 v116, 0x3f317217, v128
	v_cmp_lt_f32_e64 s[0:1], |v128|, s57
	v_cndmask_b32_e32 v190, 0, v225, vcc
	v_max_f32_e32 v123, 0xda24260, v123
	v_rcp_f32_e32 v91, v115
	v_mul_f32_e32 v96, v110, v97
	v_mul_f32_e32 v82, v180, v82
	v_exp_f32_e32 v97, v126
	v_exp_f32_e32 v110, v188
	v_min_f32_e64 v115, -v60, s60
	v_max_f32_e32 v126, 0xc2a00000, v60
	v_sub_f32_e32 v114, v114, v230
	v_fma_f32 v122, v119, s56, -v122
; __device__ __forceinline__ bf16_t f2bf(float f) { return (bf16_t)(cvt_pk_bf16(f, 0.f) & 0xffffu); }
; __device__ __forceinline__ float bf2f(bf16_t b) { return __uint_as_float(((unsigned)b) << 16); }
; __device__ __forceinline__ float sigmoidf_(float x) { return 1.0f / (1.0f + __expf(-x)); }
; template <int MODE>
; __device__ __forceinline__ void hgrn_mfma(const Ctx& C, int l, int z, int b, int hd, int c, f32x4 (&Sacc)[4][4], float& dectot, unsigned char* wl, float lb) {
;     ...
;             for (int t = 0; t < 16; ++t) {
;                 const float fl = bf2f(fv[t]);
;                 const float sg = sigmoidf_(fl);
;                 const float f = lb + (1.0f - lb) * sg, kk = (1.0f - lb) * (1.0f - sg);
;                 bacc += __logf(fmaxf(f, 1e-30f));
;                 Kb[(g8 * 16 + t) * HPT + lane] = f2bf(kk * __expf(fminf(-bacc, 80.f)));
;                 if (MODE != 0) Qt[(g8 * 16 + t) * HPT + lane] = f2bf(bf2f(qv[t]) * __expf(fmaxf(bacc, -80.f)));
	v_ldexp_f32 v125, v125, v189
	v_fma_f32 v180, v213, v91, v208
	v_cvt_pk_bf16_f32 v96, v96, s0
	v_cvt_pk_bf16_f32 v82, v82, s0
	v_mul_f32_e32 v111, v112, v130
	v_mul_f32_e32 v81, v178, v81
	v_mul_f32_e32 v112, 0x3fb8aa3b, v115
	v_mul_f32_e32 v113, 0x3fb8aa3b, v126
	v_add_f32_e32 v60, v60, v114
	v_cndmask_b32_e64 v114, v128, v116, s[0:1]
	v_fmac_f32_e32 v122, 0x3377d1cf, v119
	v_mul_f32_e32 v115, 0x3f317217, v117
	v_cmp_gt_f32_e32 vcc, s54, v123
	v_cmp_lt_f32_e64 s[0:1], |v119|, s57
	v_sub_f32_e32 v83, 1.0, v83
	v_log_f32_e32 v116, v125
	v_cndmask_b32_e64 v125, 0, 32, vcc
	v_fmac_f32_e32 v122, 0x3f317217, v119
	v_cndmask_b32_e32 v126, 0, v225, vcc
	v_max_f32_e32 v128, 0xda24260, v180
	v_rcp_f32_e32 v93, v118
	ds_write_b16 v61, v96 offset:4608
	ds_write_b16 v61, v82
	v_cvt_pk_bf16_f32 v82, v111, s0
	v_cvt_pk_bf16_f32 v81, v81, s0
	v_mul_f32_e32 v96, v127, v98
	v_mul_f32_e32 v80, v181, v80
	v_exp_f32_e32 v98, v112
	v_exp_f32_e32 v111, v113
	v_min_f32_e64 v112, -v60, s60
	v_max_f32_e32 v113, 0xc2a00000, v60
	v_fma_f32 v115, v117, s56, -v115
	v_mul_f32_e32 v83, v213, v83
	v_sub_f32_e32 v114, v114, v232
	v_ldexp_f32 v118, v123, v125
	v_fma_f32 v123, v213, v93, v208
	ds_write_b16 v61, v82 offset:4752
	ds_write_b16 v61, v81 offset:144
	v_cvt_pk_bf16_f32 v81, v96, s0
	v_cvt_pk_bf16_f32 v80, v80, s0
	v_mul_f32_e32 v82, 0x3fb8aa3b, v112
	v_mul_f32_e32 v96, 0x3fb8aa3b, v113
	v_cndmask_b32_e64 v99, v119, v122, s[0:1]
	v_fmac_f32_e32 v115, 0x3377d1cf, v117
	v_cmp_gt_f32_e32 vcc, s54, v128
	v_sub_f32_e32 v85, 1.0, v85
	v_add_f32_e32 v60, v60, v114
	v_log_f32_e32 v112, v118
	v_cndmask_b32_e64 v113, 0, 32, vcc
	v_fmac_f32_e32 v115, 0x3f317217, v117
	v_cmp_lt_f32_e64 s[0:1], |v117|, s57
	v_cndmask_b32_e32 v114, 0, v225, vcc
	v_max_f32_e32 v118, 0xda24260, v123
	v_rcp_f32_e32 v95, v121
	ds_write_b16 v61, v81 offset:4896
	ds_write_b16 v61, v80 offset:288
	v_mul_f32_e32 v80, v83, v97
	v_mul_f32_e32 v79, v110, v79
	v_exp_f32_e32 v81, v82
	v_exp_f32_e32 v82, v96
	v_sub_f32_e32 v97, v99, v191
	v_lshlrev_b32_e32 v78, 16, v78
	v_mul_f32_e32 v85, v213, v85
	v_min_f32_e64 v83, -v60, s60
	v_max_f32_e32 v96, 0xc2a00000, v60
	v_ldexp_f32 v101, v128, v113
	v_fma_f32 v110, v213, v95, v208
	v_cvt_pk_bf16_f32 v80, v80, s0
	v_cvt_pk_bf16_f32 v79, v79, s0
	v_add_f32_e32 v60, v60, v97
	v_cndmask_b32_e64 v97, v117, v115, s[0:1]
	v_cmp_gt_f32_e64 s[0:1], s54, v118
	v_sub_f32_e32 v88, 1.0, v88
	v_mul_f32_e32 v83, 0x3fb8aa3b, v83
	v_mul_f32_e32 v96, 0x3fb8aa3b, v96
	v_log_f32_e32 v101, v101
	v_cndmask_b32_e64 v113, 0, 32, s[0:1]
	v_max_f32_e32 v110, 0xda24260, v110
	v_rcp_f32_e32 v94, v124
	ds_write_b16 v61, v80 offset:5040
	ds_write_b16 v61, v79 offset:432
	v_mul_f32_e32 v79, v85, v98
	v_mul_f32_e32 v78, v111, v78
	v_mul_f32_e32 v88, v213, v88
	s_and_b64 vcc, exec, s[4:5]
	v_cndmask_b32_e64 v115, 0, v225, s[0:1]
	v_exp_f32_e32 v80, v83
	v_exp_f32_e32 v83, v96
	v_min_f32_e64 v85, -v60, s60
	v_max_f32_e32 v96, 0xc2a00000, v60
	v_sub_f32_e32 v97, v97, v233
	v_ldexp_f32 v100, v118, v113
	v_fma_f32 v111, v213, v94, v208
	v_cvt_pk_bf16_f32 v79, v79, s0
	v_cvt_pk_bf16_f32 v78, v78, s0
	v_cmp_gt_f32_e64 s[0:1], s54, v110
	v_mul_f32_e32 v85, 0x3fb8aa3b, v85
	v_mul_f32_e32 v96, 0x3fb8aa3b, v96
	v_add_f32_e32 v60, v60, v97
	v_mul_f32_e32 v97, 0x3f317218, v120
	v_log_f32_e32 v100, v100
	v_cndmask_b32_e64 v113, 0, 32, s[0:1]
	v_max_f32_e32 v111, 0xda24260, v111
	ds_write_b16 v61, v79 offset:5184
	ds_write_b16 v61, v78 offset:576
	v_mul_f32_e32 v78, v88, v81
	v_mul_f32_e32 v77, v82, v77
	v_sub_f32_e32 v84, 1.0, v84
	v_cndmask_b32_e64 v117, 0, v225, s[0:1]
	v_exp_f32_e32 v79, v85
	v_exp_f32_e32 v81, v96
	v_min_f32_e64 v82, -v60, s60
	v_max_f32_e32 v85, 0xc2a00000, v60
	v_sub_f32_e32 v88, v97, v229
	v_ldexp_f32 v97, v110, v113
	v_cvt_pk_bf16_f32 v78, v78, s0
	v_cvt_pk_bf16_f32 v77, v77, s0
	v_cmp_gt_f32_e64 s[0:1], s54, v111
	v_mul_f32_e32 v84, v213, v84
	v_mul_f32_e32 v82, 0x3fb8aa3b, v82
	v_mul_f32_e32 v85, 0x3fb8aa3b, v85
	v_add_f32_e32 v60, v60, v88
	v_mul_f32_e32 v88, 0x3f317218, v116
	v_mul_f32_e32 v98, 0x3f317217, v101
	v_log_f32_e32 v97, v97
	v_cndmask_b32_e64 v99, 0, 32, s[0:1]
	v_sub_f32_e32 v86, 1.0, v86
	ds_write_b16 v61, v78 offset:5328
	ds_write_b16 v61, v77 offset:720
	v_mul_f32_e32 v77, v84, v80
	v_mul_f32_e32 v74, v83, v74
	v_exp_f32_e32 v78, v82
	v_exp_f32_e32 v80, v85
	v_min_f32_e64 v82, -v60, s60
	v_max_f32_e32 v83, 0xc2a00000, v60
	v_sub_f32_e32 v84, v88, v190
	v_fma_f32 v85, v101, s56, -v98
	v_ldexp_f32 v88, v111, v99
	v_mul_f32_e32 v86, v213, v86
	v_cvt_pk_bf16_f32 v77, v77, s0
	v_cvt_pk_bf16_f32 v74, v74, s0
	v_mul_f32_e32 v82, 0x3fb8aa3b, v82
	v_mul_f32_e32 v83, 0x3fb8aa3b, v83
	v_add_f32_e32 v60, v60, v84
	v_mul_f32_e32 v84, 0x3f317218, v112
	v_fmac_f32_e32 v85, 0x3377d1cf, v101
	v_mul_f32_e32 v96, 0x3f317217, v100
	v_log_f32_e32 v88, v88
	v_sub_f32_e32 v87, 1.0, v87
	v_cndmask_b32_e64 v110, 0, v225, s[0:1]
	v_fmac_f32_e32 v85, 0x3f317217, v101
	v_cmp_lt_f32_e64 s[0:1], |v101|, s57
	ds_write_b16 v61, v77 offset:5472
	ds_write_b16 v61, v74 offset:864
	v_mul_f32_e32 v74, v86, v79
	v_mul_f32_e32 v72, v81, v72
	v_exp_f32_e32 v77, v82
	v_exp_f32_e32 v79, v83
	v_min_f32_e64 v81, -v60, s60
	v_max_f32_e32 v82, 0xc2a00000, v60
	v_sub_f32_e32 v83, v84, v126
	v_fma_f32 v84, v100, s56, -v96
	v_mul_f32_e32 v87, v213, v87
	v_cvt_pk_bf16_f32 v74, v74, s0
	v_cvt_pk_bf16_f32 v72, v72, s0
	v_mul_f32_e32 v81, 0x3fb8aa3b, v81
	v_mul_f32_e32 v82, 0x3fb8aa3b, v82
	v_add_f32_e32 v60, v60, v83
	v_cndmask_b32_e64 v83, v101, v85, s[0:1]
	v_fmac_f32_e32 v84, 0x3377d1cf, v100
	v_mul_f32_e32 v85, 0x3f317217, v97
	v_sub_f32_e32 v89, 1.0, v89
	v_fmac_f32_e32 v84, 0x3f317217, v100
; __device__ __forceinline__ unsigned cvt_pk_bf16(float lo, float hi) { f32x2_t v = {lo, hi}; bf2_t r = __builtin_convertvector(v, bf2_t); return __builtin_bit_cast(unsigned, r); }
; template <int MODE>
; __device__ __forceinline__ void hgrn_mfma(const Ctx& C, int l, int z, int b, int hd, int c, f32x4 (&Sacc)[4][4], float& dectot, unsigned char* wl, float lb) {
;     ...
;             for (int t = 0; t < 16; ++t) {
;                 const float fl = bf2f(fv[t]);
;                 const float sg = sigmoidf_(fl);
;                 const float f = lb + (1.0f - lb) * sg, kk = (1.0f - lb) * (1.0f - sg);
;                 bacc += __logf(fmaxf(f, 1e-30f));
;                 Kb[(g8 * 16 + t) * HPT + lane] = f2bf(kk * __expf(fminf(-bacc, 80.f)));
;                 if (MODE != 0) Qt[(g8 * 16 + t) * HPT + lane] = f2bf(bf2f(qv[t]) * __expf(fmaxf(bacc, -80.f)));
;                 Vv[(g8 * 16 + t) * HPT + lane] = vv[t];
;             }
;         }
;         { const float eb = __expf(bacc); dl[lane] = eb; dectot *= eb; }
;         wave_lds_fence();
;         f32x4 Oacc[2][4];
;         if (MODE != 0) {
;             bf16x8 Sb[2][4];
; #pragma unroll
;             for (int ks = 0; ks < 2; ++ks)
; #pragma unroll
;                 for (int vt = 0; vt < 4; ++vt) { union { bf16x8 v; unsigned u[4]; } t_;
;                     t_.u[0] = cvt_pk_bf16(Sacc[2 * ks][vt][0], Sacc[2 * ks][vt][1]); t_.u[1] = cvt_pk_bf16(Sacc[2 * ks][vt][2], Sacc[2 * ks][vt][3]);
;                     t_.u[2] = cvt_pk_bf16(Sacc[2 * ks + 1][vt][0], Sacc[2 * ks + 1][vt][1]); t_.u[3] = cvt_pk_bf16(Sacc[2 * ks + 1][vt][2], Sacc[2 * ks + 1][vt][3]); Sb[ks][vt] = t_.v; }
;             float zz = 0.f; asm volatile("" : "+v"(zz));
; #pragma unroll
;             for (int tt = 0; tt < 2; ++tt)
; #pragma unroll
;                 for (int vt = 0; vt < 4; ++vt) Oacc[tt][vt] = (f32x4){zz, zz, zz, zz};
; #pragma unroll
;             for (int tt = 0; tt < 2; ++tt)
; #pragma unroll
;                 for (int ks = 0; ks < 2; ++ks) { const bf16_t* qp = Qt + (16 * tt + fr) * HPT + 32 * ks + 4 * quad;
;                     union { bf16x8 v; u32x2 h[2]; } a_; a_.h[0] = *(const u32x2*)qp; a_.h[1] = *(const u32x2*)(qp + 16);
; #pragma unroll
;                     for (int vt = 0; vt < 4; ++vt) Oacc[tt][vt] = __builtin_amdgcn_mfma_f32_16x16x32_bf16(a_.v, Sb[ks][vt], Oacc[tt][vt], 0, 0, 0); }
	v_cmp_lt_f32_e64 s[0:1], |v100|, s57
	ds_write_b16 v61, v74 offset:5616
	ds_write_b16 v61, v72 offset:1008
	v_mul_f32_e32 v72, v87, v78
	v_mul_f32_e32 v71, v80, v71
	v_exp_f32_e32 v74, v81
	v_exp_f32_e32 v78, v82
	v_min_f32_e64 v80, -v60, s60
	v_max_f32_e32 v81, 0xc2a00000, v60
	v_sub_f32_e32 v82, v83, v114
	v_fma_f32 v83, v97, s56, -v85
	v_mul_f32_e32 v89, v213, v89
	v_cvt_pk_bf16_f32 v72, v72, s0
	v_cvt_pk_bf16_f32 v71, v71, s0
	v_mul_f32_e32 v80, 0x3fb8aa3b, v80
	v_mul_f32_e32 v81, 0x3fb8aa3b, v81
	v_add_f32_e32 v60, v60, v82
	v_cndmask_b32_e64 v82, v100, v84, s[0:1]
	v_fmac_f32_e32 v83, 0x3377d1cf, v97
	v_mul_f32_e32 v84, 0x3f317217, v88
	v_sub_f32_e32 v90, 1.0, v90
	v_fmac_f32_e32 v83, 0x3f317217, v97
	v_cmp_lt_f32_e64 s[0:1], |v97|, s57
	ds_write_b16 v61, v72 offset:5760
	ds_write_b16 v61, v71 offset:1152
	v_mul_f32_e32 v71, v89, v77
	v_mul_f32_e32 v64, v79, v64
	v_exp_f32_e32 v72, v80
	v_exp_f32_e32 v77, v81
	v_min_f32_e64 v79, -v60, s60
	v_max_f32_e32 v80, 0xc2a00000, v60
	v_sub_f32_e32 v81, v82, v115
	v_fma_f32 v82, v88, s56, -v84
	v_mul_f32_e32 v90, v213, v90
	v_cvt_pk_bf16_f32 v71, v71, s0
	v_cvt_pk_bf16_f32 v64, v64, s0
	v_mul_f32_e32 v79, 0x3fb8aa3b, v79
	v_mul_f32_e32 v80, 0x3fb8aa3b, v80
	v_add_f32_e32 v60, v60, v81
	v_cndmask_b32_e64 v81, v97, v83, s[0:1]
	v_fmac_f32_e32 v82, 0x3377d1cf, v88
	v_sub_f32_e32 v92, 1.0, v92
	v_fmac_f32_e32 v82, 0x3f317217, v88
	v_cmp_lt_f32_e64 s[0:1], |v88|, s57
	ds_write_b16 v61, v71 offset:5904
	ds_write_b16 v61, v64 offset:1296
	v_mul_f32_e32 v64, v90, v74
	v_mul_f32_e32 v62, v78, v62
	v_exp_f32_e32 v71, v79
	v_exp_f32_e32 v74, v80
	v_min_f32_e64 v78, -v60, s60
	v_max_f32_e32 v79, 0xc2a00000, v60
	v_sub_f32_e32 v80, v81, v117
	v_mul_f32_e32 v92, v213, v92
	v_cvt_pk_bf16_f32 v64, v64, s0
	v_cvt_pk_bf16_f32 v62, v62, s0
	v_mul_f32_e32 v78, 0x3fb8aa3b, v78
	v_mul_f32_e32 v79, 0x3fb8aa3b, v79
	v_add_f32_e32 v60, v60, v80
	v_cndmask_b32_e64 v80, v88, v82, s[0:1]
	v_sub_f32_e32 v91, 1.0, v91
	ds_write_b16 v61, v64 offset:6048
	ds_write_b16 v61, v62 offset:1440
	v_mul_f32_e32 v62, v92, v72
	v_mul_f32_e32 v63, v77, v63
	v_exp_f32_e32 v64, v78
	v_exp_f32_e32 v72, v79
	v_min_f32_e64 v77, -v60, s60
	v_sub_f32_e32 v79, v80, v110
	v_mul_f32_e32 v91, v213, v91
	v_max_f32_e32 v78, 0xc2a00000, v60
	v_cvt_pk_bf16_f32 v62, v62, s0
	v_cvt_pk_bf16_f32 v63, v63, s0
	v_mul_f32_e32 v77, 0x3fb8aa3b, v77
	v_add_f32_e32 v60, v60, v79
	v_sub_f32_e32 v93, 1.0, v93
	v_mul_f32_e32 v78, 0x3fb8aa3b, v78
	ds_write_b16 v61, v62 offset:6192
	ds_write_b16 v61, v63 offset:1584
	v_mul_f32_e32 v62, v91, v71
	v_mul_f32_e32 v63, v74, v70
	v_exp_f32_e32 v70, v77
	v_min_f32_e64 v74, -v60, s60
	v_mul_f32_e32 v93, v213, v93
	v_exp_f32_e32 v71, v78
	v_max_f32_e32 v77, 0xc2a00000, v60
	v_cvt_pk_bf16_f32 v62, v62, s0
	v_mul_f32_e32 v74, 0x3fb8aa3b, v74
	v_sub_f32_e32 v95, 1.0, v95
	v_cvt_pk_bf16_f32 v63, v63, s0
	v_mul_f32_e32 v77, 0x3fb8aa3b, v77
	ds_write_b16 v61, v62 offset:6336
	ds_write_b16 v61, v63 offset:1728
	v_mul_f32_e32 v62, v93, v64
	v_exp_f32_e32 v64, v74
	v_mul_f32_e32 v95, v213, v95
	v_mul_f32_e32 v63, v72, v73
	v_exp_f32_e32 v72, v77
	v_cvt_pk_bf16_f32 v62, v62, s0
	v_sub_f32_e32 v94, 1.0, v94
	v_cvt_pk_bf16_f32 v63, v63, s0
	ds_write_b16 v61, v62 offset:6480
	ds_write_b16 v61, v63 offset:1872
	v_mul_f32_e32 v62, v95, v70
	v_mul_f32_e32 v94, v213, v94
	v_mul_f32_e32 v63, v71, v75
	v_cvt_pk_bf16_f32 v62, v62, s0
	v_cvt_pk_bf16_f32 v63, v63, s0
	ds_write_b16 v61, v62 offset:6624
	ds_write_b16 v61, v63 offset:2016
	v_mul_f32_e32 v62, v94, v64
	v_mul_f32_e32 v63, v72, v76
	v_cvt_pk_bf16_f32 v62, v62, s0
	v_cvt_pk_bf16_f32 v63, v63, s0
	ds_write_b16 v61, v62 offset:6768
	ds_write_b16 v61, v63 offset:2160
	s_cbranch_vccz .LBB0_743
	v_mul_f32_e32 v60, 0x3fb8aa3b, v60
	v_exp_f32_e32 v60, v60
	v_mov_b32_e32 v98, v65
	v_cvt_pk_bf16_f32 v61, v2, v3
	v_cvt_pk_bf16_f32 v62, v16, v17
	ds_write_b32 v134, v60 offset:13824
	s_waitcnt lgkmcnt(0)
	ds_read2_b64 v[110:113], v141 offset1:4
	ds_read2_b64 v[126:129], v141 offset0:8 offset1:12
	v_cvt_pk_bf16_f32 v60, v0, v1
	v_cvt_pk_bf16_f32 v63, v18, v19
	v_cvt_pk_bf16_f32 v70, v4, v5
	v_cvt_pk_bf16_f32 v71, v6, v7
	v_cvt_pk_bf16_f32 v72, v20, v21
	v_cvt_pk_bf16_f32 v73, v22, v23
	v_cvt_pk_bf16_f32 v78, v8, v9
	v_cvt_pk_bf16_f32 v79, v10, v11
	v_cvt_pk_bf16_f32 v80, v24, v25
	v_cvt_pk_bf16_f32 v81, v26, v27
	v_cvt_pk_bf16_f32 v86, v12, v13
	v_cvt_pk_bf16_f32 v87, v14, v15
	v_cvt_pk_bf16_f32 v88, v28, v29
	v_cvt_pk_bf16_f32 v89, v30, v31
	v_mov_b32_e32 v99, v98
	v_mov_b32_e32 v100, v98
	v_mov_b32_e32 v101, v98
	v_cvt_pk_bf16_f32 v74, v32, v33
	v_cvt_pk_bf16_f32 v75, v34, v35
	s_waitcnt lgkmcnt(1)
	v_mfma_f32_16x16x32_bf16 v[114:117], v[110:113], v[60:63], v[98:101]
	v_cvt_pk_bf16_f32 v76, v48, v49
	v_cvt_pk_bf16_f32 v77, v50, v51
	v_cvt_pk_bf16_f32 v82, v36, v37
	v_mfma_f32_16x16x32_bf16 v[118:121], v[110:113], v[70:73], v[98:101]
	v_cvt_pk_bf16_f32 v83, v38, v39
	v_cvt_pk_bf16_f32 v84, v52, v53
	v_cvt_pk_bf16_f32 v85, v54, v55
	v_mfma_f32_16x16x32_bf16 v[122:125], v[110:113], v[78:81], v[98:101]
	v_cvt_pk_bf16_f32 v90, v40, v41
	v_cvt_pk_bf16_f32 v91, v42, v43
	v_cvt_pk_bf16_f32 v92, v56, v57
	v_mfma_f32_16x16x32_bf16 v[110:113], v[110:113], v[86:89], v[98:101]
	v_cvt_pk_bf16_f32 v93, v58, v59
	v_cvt_pk_bf16_f32 v94, v44, v45
	v_cvt_pk_bf16_f32 v95, v46, v47
	v_cvt_pk_bf16_f32 v96, v66, v67
	v_cvt_pk_bf16_f32 v97, v68, v69
	v_add_u32_e32 v64, 0x800, v141
	s_waitcnt lgkmcnt(0)
	v_mfma_f32_16x16x32_bf16 v[114:117], v[126:129], v[74:77], v[114:117]
	s_add_i32 s36, s36, 1
	s_cmp_eq_u32 s36, 4
	v_mfma_f32_16x16x32_bf16 v[118:121], v[126:129], v[82:85], v[118:121]
	v_mfma_f32_16x16x32_bf16 v[122:125], v[126:129], v[90:93], v[122:125]
	v_mfma_f32_16x16x32_bf16 v[110:113], v[126:129], v[94:97], v[110:113]
	ds_read2_b64 v[126:129], v64 offset0:32 offset1:36
	s_waitcnt lgkmcnt(0)
; template <int MODE>
; __device__ __forceinline__ void hgrn_mfma(const Ctx& C, int l, int z, int b, int hd, int c, f32x4 (&Sacc)[4][4], float& dectot, unsigned char* wl, float lb) {
;     ...
;             f32x4 P00 = {zz, zz, zz, zz}, P01 = {zz, zz, zz, zz}, P11 = {zz, zz, zz, zz};
; #pragma unroll
;             for (int ks = 0; ks < 2; ++ks) {
;                 const bf16x8 kA0 = *(const bf16x8*)(Kb + fr * HPT + 32 * ks + 8 * quad), kA1 = *(const bf16x8*)(Kb + (16 + fr) * HPT + 32 * ks + 8 * quad);
;                 const bf16x8 qB0 = *(const bf16x8*)(Qt + fr * HPT + 32 * ks + 8 * quad), qB1 = *(const bf16x8*)(Qt + (16 + fr) * HPT + 32 * ks + 8 * quad);
;                 P00 = __builtin_amdgcn_mfma_f32_16x16x32_bf16(kA0, qB0, P00, 0, 0, 0);
;                 P01 = __builtin_amdgcn_mfma_f32_16x16x32_bf16(kA0, qB1, P01, 0, 0, 0);
;                 P11 = __builtin_amdgcn_mfma_f32_16x16x32_bf16(kA1, qB1, P11, 0, 0, 0);
;             }
; #pragma unroll
;             for (int r = 0; r < 4; ++r) if (4 * quad + r > fr) { P00[r] = 0.f; P11[r] = 0.f; }
;             union { bf16x8 v; unsigned u[4]; } pa0, pa1;
;             pa0.u[0] = cvt_pk_bf16(P00[0], P00[1]); pa0.u[1] = cvt_pk_bf16(P00[2], P00[3]); pa0.u[2] = 0u; pa0.u[3] = 0u;
;             pa1.u[0] = cvt_pk_bf16(P01[0], P01[1]); pa1.u[1] = cvt_pk_bf16(P01[2], P01[3]); pa1.u[2] = cvt_pk_bf16(P11[0], P11[1]); pa1.u[3] = cvt_pk_bf16(P11[2], P11[3]);
; #pragma unroll
;             for (int vt = 0; vt < 4; ++vt) { const bf16_t* vp = Vv + (4 * quad + (fr >> 2)) * HPT + 16 * vt + 4 * (fr & 3);
;                 union { bf16x8 v; s16x4 h[2]; } vb; vb.h[0] = lds_tr(vp); vb.h[1] = lds_tr(vp + 16 * HPT);
;                 Oacc[0][vt] = __builtin_amdgcn_mfma_f32_16x16x32_bf16(pa0.v, vb.v, Oacc[0][vt], 0, 0, 0);
;                 Oacc[1][vt] = __builtin_amdgcn_mfma_f32_16x16x32_bf16(pa1.v, vb.v, Oacc[1][vt], 0, 0, 0); }
;         }
;         {
;             bf16x8 vB[4];
; #pragma unroll
;             for (int vt = 0; vt < 4; ++vt) { const bf16_t* vp = Vv + (8 * quad + (fr >> 2)) * HPT + 16 * vt + 4 * (fr & 3);
;                 union { bf16x8 v; s16x4 h[2]; } vb; vb.h[0] = lds_tr(vp); vb.h[1] = lds_tr(vp + 4 * HPT); vB[vt] = vb.v; }
; #pragma unroll
;             for (int kt = 0; kt < 4; ++kt) { const bf16_t* kp = Kb + (8 * quad + (fr >> 2)) * HPT + 16 * kt + 4 * (fr & 3);
	v_mfma_f32_16x16x32_bf16 v[60:63], v[126:129], v[60:63], v[98:101]
	v_mfma_f32_16x16x32_bf16 v[70:73], v[126:129], v[70:73], v[98:101]
	v_mfma_f32_16x16x32_bf16 v[78:81], v[126:129], v[78:81], v[98:101]
	v_mfma_f32_16x16x32_bf16 v[86:89], v[126:129], v[86:89], v[98:101]
	ds_read2_b64 v[126:129], v64 offset0:40 offset1:44
	s_waitcnt lgkmcnt(0)
	v_mfma_f32_16x16x32_bf16 v[74:77], v[126:129], v[74:77], v[60:63]
	v_mfma_f32_16x16x32_bf16 v[178:181], v[126:129], v[82:85], v[70:73]
	v_mfma_f32_16x16x32_bf16 v[78:81], v[126:129], v[90:93], v[78:81]
	v_mfma_f32_16x16x32_bf16 v[126:129], v[126:129], v[94:97], v[86:89]
	ds_read_b128 v[60:63], v138 offset:4608
	ds_read_b128 v[70:73], v138 offset:6912
	ds_read_b128 v[82:85], v138
	ds_read_b128 v[86:89], v138 offset:2304
	ds_read_b128 v[90:93], v138 offset:4672
	ds_read_b128 v[94:97], v138 offset:6976
	ds_read_b128 v[188:191], v138 offset:64
	ds_read_b128 v[230:233], v138 offset:2368
	s_waitcnt lgkmcnt(5)
	v_mfma_f32_16x16x32_bf16 v[82:85], v[60:63], v[82:85], v[98:101]
	s_waitcnt lgkmcnt(4)
	v_mfma_f32_16x16x32_bf16 v[70:73], v[70:73], v[86:89], v[98:101]
	s_waitcnt lgkmcnt(1)
	v_mfma_f32_16x16x32_bf16 v[82:85], v[90:93], v[188:191], v[82:85]
	s_waitcnt lgkmcnt(0)
	v_mfma_f32_16x16x32_bf16 v[70:73], v[94:97], v[230:233], v[70:73]
	v_mfma_f32_16x16x32_bf16 v[60:63], v[60:63], v[86:89], v[98:101]
	s_nop 4
	v_cndmask_b32_e64 v64, v85, 0, s[42:43]
	s_nop 0
	v_cndmask_b32_e64 v85, v73, 0, s[42:43]
	v_cndmask_b32_e64 v94, v72, 0, s[46:47]
	v_cndmask_b32_e64 v95, v71, 0, s[48:49]
	v_cndmask_b32_e64 v96, v70, 0, s[50:51]
	v_mfma_f32_16x16x32_bf16 v[70:73], v[90:93], v[230:233], v[60:63]
	v_cndmask_b32_e64 v84, v84, 0, s[46:47]
	v_cndmask_b32_e64 v83, v83, 0, s[48:49]
	v_cndmask_b32_e64 v82, v82, 0, s[50:51]
	v_cvt_pk_bf16_f32 v62, v82, v83
	v_cvt_pk_bf16_f32 v63, v84, v64
	v_mov_b32_e32 v64, v65
	s_nop 1
	v_cvt_pk_bf16_f32 v98, v70, v71
	v_cvt_pk_bf16_f32 v99, v72, v73
	ds_read_b64_tr_b16 v[72:73], v139 offset:11520
	ds_read_b64_tr_b16 v[70:71], v139 offset:9216
	ds_read_b64_tr_b16 v[90:91], v139 offset:9248
	v_cvt_pk_bf16_f32 v100, v96, v95
	v_cvt_pk_bf16_f32 v101, v94, v85
	s_waitcnt lgkmcnt(1)
	v_mfma_f32_16x16x32_bf16 v[82:85], v[62:65], v[70:73], v[114:117]
	ds_read_b64_tr_b16 v[92:93], v139 offset:11552
	ds_read_b64_tr_b16 v[94:95], v139 offset:9280
	ds_read_b64_tr_b16 v[96:97], v139 offset:11584
	ds_read_b64_tr_b16 v[114:115], v139 offset:9312
	ds_read_b64_tr_b16 v[116:117], v139 offset:11616
	v_mfma_f32_16x16x32_bf16 v[70:73], v[98:101], v[70:73], v[74:77]
	s_waitcnt lgkmcnt(4)
	v_mfma_f32_16x16x32_bf16 v[86:89], v[62:65], v[90:93], v[118:121]
	v_mfma_f32_16x16x32_bf16 v[74:77], v[98:101], v[90:93], v[178:181]
	s_waitcnt lgkmcnt(2)
	v_mfma_f32_16x16x32_bf16 v[90:93], v[62:65], v[94:97], v[122:125]
	v_mfma_f32_16x16x32_bf16 v[78:81], v[98:101], v[94:97], v[78:81]
	s_waitcnt lgkmcnt(0)
	v_mfma_f32_16x16x32_bf16 v[94:97], v[62:65], v[114:117], v[110:113]
	v_add_u32_e32 v64, v137, v136
	v_mfma_f32_16x16x32_bf16 v[60:63], v[98:101], v[114:117], v[126:129]
	ds_read_b64_tr_b16 v[98:99], v140 offset:9216
	ds_read_b64_tr_b16 v[100:101], v140 offset:9792
	ds_read_b64_tr_b16 v[110:111], v140 offset:9248
	ds_read_b64_tr_b16 v[112:113], v140 offset:9824
	ds_read_b64_tr_b16 v[114:115], v140 offset:9280
	ds_read_b64_tr_b16 v[116:117], v140 offset:9856
	ds_read_b64_tr_b16 v[118:119], v140 offset:9312
	ds_read_b64_tr_b16 v[120:121], v140 offset:9888
	ds_read_b64_tr_b16 v[124:125], v140 offset:5184
	ds_read_b64_tr_b16 v[122:123], v140 offset:4608
	ds_read_b64_tr_b16 v[126:127], v140 offset:4640
	ds_read_b128 v[128:131], v64 offset:13824
	s_waitcnt lgkmcnt(2)
	v_mfma_f32_16x16x32_bf16 v[0:3], v[122:125], v[98:101], v[0:3]
	v_mfma_f32_16x16x32_bf16 v[4:7], v[122:125], v[110:113], v[4:7]
	s_waitcnt lgkmcnt(0)
	s_nop 5
	v_pk_mul_f32 v[0:1], v[128:129], v[0:1]
	v_pk_mul_f32 v[2:3], v[130:131], v[2:3]
	v_mfma_f32_16x16x32_bf16 v[8:11], v[122:125], v[114:117], v[8:11]
	v_mfma_f32_16x16x32_bf16 v[12:15], v[122:125], v[118:121], v[12:15]
	v_mul_f32_e64 v4, v128, v4
	v_mul_f32_e64 v5, v129, v5
	s_nop 4
	v_pk_mul_f32 v[8:9], v[128:129], v[8:9]
	v_pk_mul_f32 v[6:7], v[130:131], v[6:7]
	v_pk_mul_f32 v[10:11], v[130:131], v[10:11]
	v_pk_mul_f32 v[12:13], v[128:129], v[12:13]
	ds_read_b64_tr_b16 v[128:129], v140 offset:5216
	ds_read_b128 v[122:125], v64 offset:13888
	s_waitcnt lgkmcnt(1)
	v_mfma_f32_16x16x32_bf16 v[16:19], v[126:129], v[98:101], v[16:19]
	v_mul_f32_e64 v14, v130, v14
	v_mul_f32_e64 v15, v131, v15
	v_mfma_f32_16x16x32_bf16 v[20:23], v[126:129], v[110:113], v[20:23]
	s_waitcnt lgkmcnt(0)
	s_nop 3
	v_pk_mul_f32 v[18:19], v[124:125], v[18:19]
	v_pk_mul_f32 v[16:17], v[122:123], v[16:17]
	v_mfma_f32_16x16x32_bf16 v[24:27], v[126:129], v[114:117], v[24:27]
	v_mfma_f32_16x16x32_bf16 v[28:31], v[126:129], v[118:121], v[28:31]
	v_mul_f32_e64 v22, v124, v22
	v_mul_f32_e64 v23, v125, v23
	v_pk_mul_f32 v[20:21], v[122:123], v[20:21]
	s_nop 3
	v_pk_mul_f32 v[26:27], v[124:125], v[26:27]
	v_pk_mul_f32 v[24:25], v[122:123], v[24:25]
	v_pk_mul_f32 v[30:31], v[124:125], v[30:31]
	v_pk_mul_f32 v[28:29], v[122:123], v[28:29]
	ds_read_b64_tr_b16 v[122:123], v140 offset:4672
	ds_read_b64_tr_b16 v[124:125], v140 offset:5248
	ds_read_b128 v[126:129], v64 offset:13952
	s_waitcnt lgkmcnt(1)
	v_mfma_f32_16x16x32_bf16 v[32:35], v[122:125], v[98:101], v[32:35]
	v_mfma_f32_16x16x32_bf16 v[36:39], v[122:125], v[110:113], v[36:39]
	s_waitcnt lgkmcnt(0)
; template <int MODE>
; __device__ __forceinline__ void hgrn_mfma(const Ctx& C, int l, int z, int b, int hd, int c, f32x4 (&Sacc)[4][4], float& dectot, unsigned char* wl, float lb) {
;     ...
;             for (int kt = 0; kt < 4; ++kt) { const bf16_t* kp = Kb + (8 * quad + (fr >> 2)) * HPT + 16 * kt + 4 * (fr & 3);
;                 union { bf16x8 v; s16x4 h[2]; } ka; ka.h[0] = lds_tr(kp); ka.h[1] = lds_tr(kp + 4 * HPT);
;                 const f32x4 d4 = *(const f32x4*)(dl + 16 * kt + 4 * quad);
; #pragma unroll
;                 for (int vt = 0; vt < 4; ++vt) { Sacc[kt][vt] = __builtin_amdgcn_mfma_f32_16x16x32_bf16(ka.v, vB[vt], Sacc[kt][vt], 0, 0, 0); Sacc[kt][vt] *= d4; } }
;         }
;         if (MODE == 1) {
; #pragma unroll
;             for (int tt = 0; tt < 2; ++tt)
; #pragma unroll
;                 for (int r = 0; r < 4; ++r) { const int st = c * 128 + sc * 32 + 16 * tt + 4 * quad + r; const int tq = z ? 4095 - st : st;
;                     bf16_t* yp = ya + (size_t)(b * SEQ + tq) * 256 + hd * 64 + fr;
; #pragma unroll
;                     for (int vt = 0; vt < 4; ++vt) yp[16 * vt] = f2bf(Oacc[tt][vt][r]); }
;         }
;         if (MODE == 2) {
; #pragma unroll
;             for (int tt = 0; tt < 2; ++tt) {
;                 bf16_t tmpv[4][4], gtv[4][4];
; #pragma unroll
;                 for (int r = 0; r < 4; ++r) { const int st = c * 128 + sc * 32 + 16 * tt + 4 * quad + r; const int tq = z ? 4095 - st : st;
;                     const size_t tok = (size_t)(b * SEQ + tq); const bf16_t* yp = ya + tok * 256 + hd * 64 + fr; const bf16_t* gp = pa + tok * 1280 + 1024 + hd * 64 + fr;
; #pragma unroll
;                     for (int vt = 0; vt < 4; ++vt) { tmpv[r][vt] = yp[16 * vt]; gtv[r][vt] = gp[16 * vt]; } }
; #pragma unroll
;                 for (int r = 0; r < 4; ++r) { const int st = c * 128 + sc * 32 + 16 * tt + 4 * quad + r; const int tq = z ? 4095 - st : st;
;                     bf16_t* yp = ya + (size_t)(b * SEQ + tq) * 256 + hd * 64 + fr;
;                     float o[4]; float ss = 0.f;
; #pragma unroll
;                     for (int vt = 0; vt < 4; ++vt) { o[vt] = Oacc[tt][vt][r] + bf2f(tmpv[r][vt]); ss += o[vt] * o[vt]; }
;                     ss += __shfl_xor(ss, 1); ss += __shfl_xor(ss, 2); ss += __shfl_xor(ss, 4); ss += __shfl_xor(ss, 8);
;                     const float rs = rsqrtf(ss * (1.f / 64.f) + 1e-6f);
; #pragma unroll
	s_nop 5
	v_pk_mul_f32 v[34:35], v[128:129], v[34:35]
	v_pk_mul_f32 v[32:33], v[126:127], v[32:33]
	v_mfma_f32_16x16x32_bf16 v[40:43], v[122:125], v[114:117], v[40:43]
	v_mfma_f32_16x16x32_bf16 v[44:47], v[122:125], v[118:121], v[44:47]
	v_mul_f32_e64 v38, v128, v38
	v_mul_f32_e64 v39, v129, v39
	v_pk_mul_f32 v[36:37], v[126:127], v[36:37]
	s_nop 3
	v_pk_mul_f32 v[42:43], v[128:129], v[42:43]
	v_pk_mul_f32 v[40:41], v[126:127], v[40:41]
	v_pk_mul_f32 v[46:47], v[128:129], v[46:47]
	v_pk_mul_f32 v[44:45], v[126:127], v[44:45]
	ds_read_b64_tr_b16 v[122:123], v140 offset:4704
	ds_read_b64_tr_b16 v[124:125], v140 offset:5280
	ds_read_b128 v[126:129], v64 offset:14016
	s_waitcnt lgkmcnt(1)
	v_mfma_f32_16x16x32_bf16 v[48:51], v[122:125], v[98:101], v[48:51]
	v_and_b32_e32 v99, 64, v221
	v_xor_b32_e32 v64, 1, v221
	v_add_u32_e32 v99, 64, v99
	v_cmp_lt_i32_e32 vcc, v64, v99
	v_add_u32_e32 v98, s75, v214
	v_mfma_f32_16x16x32_bf16 v[56:59], v[122:125], v[114:117], v[56:59]
	v_cndmask_b32_e32 v64, v221, v64, vcc
	v_lshlrev_b32_e32 v231, 2, v64
	v_xor_b32_e32 v64, 2, v221
	v_cmp_lt_i32_e32 vcc, v64, v99
	v_mfma_f32_16x16x32_bf16 v[52:55], v[122:125], v[110:113], v[52:55]
	v_or_b32_e32 v116, 3, v98
	v_cndmask_b32_e32 v64, v221, v64, vcc
	v_lshlrev_b32_e32 v230, 2, v64
	v_xor_b32_e32 v64, 4, v221
	v_cmp_lt_i32_e32 vcc, v64, v99
	v_mfma_f32_16x16x32_bf16 v[66:69], v[122:125], v[118:121], v[66:69]
	v_ashrrev_i32_e32 v117, 31, v116
	v_cndmask_b32_e32 v64, v221, v64, vcc
	v_lshlrev_b32_e32 v229, 2, v64
	v_xor_b32_e32 v64, 8, v221
	v_cmp_lt_i32_e32 vcc, v64, v99
	v_ashrrev_i32_e32 v99, 31, v98
	v_lshlrev_b64 v[100:101], 9, v[98:99]
	v_lshl_add_u64 v[114:115], v[106:107], 0, v[100:101]
	v_or_b32_e32 v100, 1, v98
	v_ashrrev_i32_e32 v101, 31, v100
	v_lshlrev_b64 v[110:111], 9, v[100:101]
	v_mad_i64_i32 v[124:125], s[0:1], v100, s62, v[108:109]
	v_or_b32_e32 v100, 2, v98
	v_ashrrev_i32_e32 v101, 31, v100
	v_lshl_add_u64 v[112:113], v[106:107], 0, v[110:111]
	v_lshlrev_b64 v[110:111], 9, v[100:101]
	v_mad_i64_i32 v[120:121], s[0:1], v100, s62, v[108:109]
	v_lshlrev_b64 v[100:101], 9, v[116:117]
	s_waitcnt lgkmcnt(0)
	v_pk_mul_f32 v[48:49], v[126:127], v[48:49]
	v_pk_mul_f32 v[52:53], v[126:127], v[52:53]
	v_pk_mul_f32 v[56:57], v[126:127], v[56:57]
	v_pk_mul_f32 v[66:67], v[126:127], v[66:67]
	v_mad_i64_i32 v[126:127], s[0:1], v98, s62, v[108:109]
	v_lshl_add_u64 v[110:111], v[106:107], 0, v[110:111]
	v_lshl_add_u64 v[100:101], v[106:107], 0, v[100:101]
	global_load_ushort v118, v[114:115], off
	global_load_ushort v119, v[114:115], off offset:32
	global_load_ushort v130, v[114:115], off offset:64
	global_load_ushort v131, v[114:115], off offset:96
	global_load_ushort v244, v[112:113], off
	global_load_ushort v245, v[112:113], off offset:32
	global_load_ushort v242, v[112:113], off offset:64
	global_load_ushort v243, v[112:113], off offset:96
	global_load_ushort v237, v[110:111], off
	global_load_ushort v238, v[110:111], off offset:32
	global_load_ushort v235, v[110:111], off offset:64
	global_load_ushort v236, v[110:111], off offset:96
	global_load_ushort v233, v[100:101], off
	global_load_ushort v234, v[100:101], off offset:32
	global_load_ushort v99, v[100:101], off offset:64
	global_load_ushort v232, v[100:101], off offset:96
	v_mov_b32_e32 v122, v82
	global_load_ushort v82, v[126:127], off offset:2048
	v_mov_b32_e32 v123, v86
	v_cndmask_b32_e32 v64, v221, v64, vcc
	v_pk_mul_f32 v[50:51], v[128:129], v[50:51]
	v_pk_mul_f32 v[54:55], v[128:129], v[54:55]
	v_pk_mul_f32 v[58:59], v[128:129], v[58:59]
	v_pk_mul_f32 v[68:69], v[128:129], v[68:69]
	v_lshlrev_b32_e32 v64, 2, v64
	v_mad_i64_i32 v[116:117], s[0:1], v116, s62, v[108:109]
	s_waitcnt vmcnt(16)
	v_lshlrev_b32_e32 v118, 16, v118
	s_waitcnt vmcnt(15)
	v_lshlrev_b32_e32 v119, 16, v119
	v_pk_add_f32 v[122:123], v[122:123], v[118:119]
	s_waitcnt vmcnt(14)
	v_lshlrev_b32_e32 v118, 16, v130
	v_mov_b32_e32 v130, v90
	s_waitcnt vmcnt(13)
	v_lshlrev_b32_e32 v119, 16, v131
	v_mov_b32_e32 v131, v94
	v_pk_mul_f32 v[128:129], v[122:123], v[122:123]
	s_waitcnt vmcnt(0)
	v_lshlrev_b32_e32 v82, 16, v82
	v_mul_f32_e32 v86, 0xbfb8aa3b, v82
	v_exp_f32_e32 v86, v86
	v_pk_add_f32 v[118:119], v[130:131], v[118:119]
	v_add_f32_e32 v86, 1.0, v86
	v_pk_mul_f32 v[130:131], v[118:119], v[118:119]
	v_rcp_f32_e32 v86, v86
	s_nop 0
	v_mul_f32_e32 v246, v86, v82
	global_load_ushort v82, v[126:127], off offset:2080
	s_waitcnt vmcnt(0)
	v_lshlrev_b32_e32 v82, 16, v82
	v_mul_f32_e32 v86, 0xbfb8aa3b, v82
	v_exp_f32_e32 v86, v86
	s_nop 0
	v_add_f32_e32 v86, 1.0, v86
	s_nop 0
	v_rcp_f32_e32 v86, v86
	s_nop 0
	v_mul_f32_e32 v239, v86, v82
	global_load_ushort v82, v[126:127], off offset:2112
	s_waitcnt vmcnt(0)
	v_lshlrev_b32_e32 v82, 16, v82
	v_mul_f32_e32 v86, 0xbfb8aa3b, v82
	v_exp_f32_e32 v86, v86
	s_nop 0
	v_add_f32_e32 v86, 1.0, v86
	s_nop 0
	v_rcp_f32_e32 v86, v86
	s_nop 0
	v_mul_f32_e32 v240, v86, v82
	global_load_ushort v82, v[126:127], off offset:2144
	s_waitcnt vmcnt(0)
	v_lshlrev_b32_e32 v82, 16, v82
	v_mul_f32_e32 v86, 0xbfb8aa3b, v82
	v_exp_f32_e32 v86, v86
	s_nop 0
	v_add_f32_e32 v86, 1.0, v86
	s_nop 0
	v_rcp_f32_e32 v86, v86
	s_nop 0
	v_mul_f32_e32 v241, v86, v82
	v_lshlrev_b32_e32 v127, 16, v245
	v_lshlrev_b32_e32 v126, 16, v244
	v_mov_b32_e32 v86, v83
	v_pk_add_f32 v[126:127], v[86:87], v[126:127]
	v_lshlrev_b32_e32 v87, 16, v243
	v_lshlrev_b32_e32 v86, 16, v242
	v_mov_b32_e32 v94, v91
	v_pk_mul_f32 v[82:83], v[126:127], v[126:127]
	v_pk_add_f32 v[86:87], v[94:95], v[86:87]
	v_mov_b32_e32 v94, v82
	v_pk_mul_f32 v[90:91], v[86:87], v[86:87]
	v_mov_b32_e32 v95, v128
	v_mov_b32_e32 v128, v83
	v_pk_add_f32 v[82:83], v[94:95], v[128:129]
	v_mov_b32_e32 v94, v90
	v_mov_b32_e32 v95, v130
	v_pk_add_f32 v[82:83], v[82:83], v[94:95]
	v_mov_b32_e32 v130, v91
	v_pk_add_f32 v[82:83], v[82:83], v[130:131]
	ds_bpermute_b32 v91, v231, v83
	ds_bpermute_b32 v90, v231, v82
	s_waitcnt lgkmcnt(0)
; __device__ __forceinline__ bf16_t f2bf(float f) { return (bf16_t)(cvt_pk_bf16(f, 0.f) & 0xffffu); }
; __device__ __forceinline__ float bf2f(bf16_t b) { return __uint_as_float(((unsigned)b) << 16); }
; __device__ __forceinline__ float siluf_(float x) { return x * sigmoidf_(x); }
; template <int MODE>
; __device__ __forceinline__ void hgrn_mfma(const Ctx& C, int l, int z, int b, int hd, int c, f32x4 (&Sacc)[4][4], float& dectot, unsigned char* wl, float lb) {
;     ...
;                 for (int r = 0; r < 4; ++r) { const int st = c * 128 + sc * 32 + 16 * tt + 4 * quad + r; const int tq = z ? 4095 - st : st;
;                     bf16_t* yp = ya + (size_t)(b * SEQ + tq) * 256 + hd * 64 + fr;
;                     float o[4]; float ss = 0.f;
; #pragma unroll
;                     for (int vt = 0; vt < 4; ++vt) { o[vt] = Oacc[tt][vt][r] + bf2f(tmpv[r][vt]); ss += o[vt] * o[vt]; }
;                     ss += __shfl_xor(ss, 1); ss += __shfl_xor(ss, 2); ss += __shfl_xor(ss, 4); ss += __shfl_xor(ss, 8);
;                     const float rs = rsqrtf(ss * (1.f / 64.f) + 1e-6f);
; #pragma unroll
;                     for (int vt = 0; vt < 4; ++vt) yp[16 * vt] = f2bf(o[vt] * rs * gnv[vt] * siluf_(bf2f(gtv[r][vt]))); }
	v_pk_add_f32 v[82:83], v[82:83], v[90:91]
	ds_bpermute_b32 v91, v230, v83
	ds_bpermute_b32 v90, v230, v82
	s_waitcnt lgkmcnt(0)
	v_pk_add_f32 v[82:83], v[82:83], v[90:91]
	ds_bpermute_b32 v91, v229, v83
	ds_bpermute_b32 v90, v229, v82
	s_waitcnt lgkmcnt(0)
	v_pk_add_f32 v[82:83], v[82:83], v[90:91]
	ds_bpermute_b32 v91, v64, v83
	ds_bpermute_b32 v90, v64, v82
	s_waitcnt lgkmcnt(0)
	v_pk_add_f32 v[90:91], v[82:83], v[90:91]
	v_mov_b64_e32 v[82:83], s[66:67]
	v_pk_fma_f32 v[90:91], v[90:91], s[2:3], v[82:83] op_sel_hi:[1,0,0]
	s_nop 0
	v_mul_f32_e32 v94, 0x4b800000, v91
	v_cmp_gt_f32_e64 s[0:1], s54, v91
	v_cmp_gt_f32_e32 vcc, s54, v90
	s_nop 0
	v_cndmask_b32_e64 v91, v91, v94, s[0:1]
	v_rsq_f32_e32 v91, v91
	s_nop 0
	v_mul_f32_e32 v94, 0x45800000, v91
	v_cndmask_b32_e64 v91, v91, v94, s[0:1]
	v_mul_f32_e32 v94, v122, v91
	global_load_ushort v95, v[124:125], off offset:2048
	global_load_ushort v128, v[124:125], off offset:2080
	global_load_ushort v129, v[124:125], off offset:2112
	global_load_ushort v130, v[124:125], off offset:2144
	global_load_ushort v131, v[120:121], off offset:2048
	global_load_ushort v178, v[120:121], off offset:2080
	s_nop 0
	global_load_ushort v125, v[120:121], off offset:2112
	global_load_ushort v124, v[120:121], off offset:2144
	global_load_ushort v122, v[116:117], off offset:2048
	s_nop 0
	global_load_ushort v121, v[116:117], off offset:2080
	global_load_ushort v120, v[116:117], off offset:2112
	s_nop 0
	global_load_ushort v116, v[116:117], off offset:2144
	v_mul_f32_e32 v94, v209, v94
	v_mul_f32_e32 v94, v246, v94
	v_cvt_pk_bf16_f32 v94, v94, s0
	global_store_short v[114:115], v94, off
	v_mul_f32_e32 v94, v123, v91
	v_mul_f32_e32 v94, v210, v94
	v_mul_f32_e32 v94, v239, v94
	v_cvt_pk_bf16_f32 v94, v94, s0
	global_store_short v[114:115], v94, off offset:32
	v_mul_f32_e32 v94, v118, v91
	v_mul_f32_e32 v94, v211, v94
	v_mul_f32_e32 v94, v240, v94
	v_cvt_pk_bf16_f32 v94, v94, s0
	global_store_short v[114:115], v94, off offset:64
	v_mul_f32_e32 v91, v119, v91
	v_mul_f32_e32 v91, v212, v91
	v_mul_f32_e32 v91, v241, v91
	v_cvt_pk_bf16_f32 v91, v91, s0
	global_store_short v[114:115], v91, off offset:96
	v_mul_f32_e32 v91, 0x4b800000, v90
	v_cndmask_b32_e32 v90, v90, v91, vcc
	v_rsq_f32_e32 v90, v90
	s_waitcnt vmcnt(15)
	v_lshlrev_b32_e32 v94, 16, v95
	v_mul_f32_e32 v95, 0xbfb8aa3b, v94
	v_exp_f32_e32 v95, v95
	v_mul_f32_e32 v91, 0x45800000, v90
	v_cndmask_b32_e32 v90, v90, v91, vcc
	v_mul_f32_e32 v91, v126, v90
	v_add_f32_e32 v95, 1.0, v95
	v_mul_f32_e32 v91, v209, v91
	v_mul_f32_e32 v86, v86, v90
	v_mul_f32_e32 v86, v211, v86
	v_rcp_f32_e32 v95, v95
	s_nop 0
	v_mul_f32_e32 v94, v95, v94
	v_mul_f32_e32 v91, v94, v91
	s_waitcnt vmcnt(14)
	v_lshlrev_b32_e32 v94, 16, v128
	v_mul_f32_e32 v95, 0xbfb8aa3b, v94
	v_exp_f32_e32 v95, v95
	v_cvt_pk_bf16_f32 v91, v91, s0
	global_store_short v[112:113], v91, off
	v_mul_f32_e32 v91, v127, v90
	v_add_f32_e32 v95, 1.0, v95
	v_mul_f32_e32 v91, v210, v91
	v_rcp_f32_e32 v95, v95
	s_nop 0
	v_mul_f32_e32 v94, v95, v94
	v_mul_f32_e32 v91, v94, v91
	v_cvt_pk_bf16_f32 v91, v91, s0
	global_store_short v[112:113], v91, off offset:32
	s_waitcnt vmcnt(15)
	v_lshlrev_b32_e32 v91, 16, v129
	v_mul_f32_e32 v94, 0xbfb8aa3b, v91
	v_exp_f32_e32 v94, v94
	s_nop 0
	v_add_f32_e32 v94, 1.0, v94
	s_nop 0
	v_rcp_f32_e32 v94, v94
	s_nop 0
	v_mul_f32_e32 v91, v94, v91
	v_mul_f32_e32 v86, v91, v86
	v_cvt_pk_bf16_f32 v86, v86, s0
	global_store_short v[112:113], v86, off offset:64
	v_mul_f32_e32 v86, v87, v90
	s_waitcnt vmcnt(15)
	v_lshlrev_b32_e32 v87, 16, v130
	v_mul_f32_e32 v90, 0xbfb8aa3b, v87
	v_exp_f32_e32 v90, v90
	v_mul_f32_e32 v86, v212, v86
	v_add_f32_e32 v90, 1.0, v90
	s_nop 0
	v_rcp_f32_e32 v90, v90
	s_nop 0
	v_mul_f32_e32 v87, v90, v87
	v_mov_b32_e32 v90, v84
	s_waitcnt vmcnt(14)
	v_lshlrev_b32_e32 v84, 16, v131
	v_mov_b32_e32 v91, v88
	v_mul_f32_e32 v88, 0xbfb8aa3b, v84
	v_exp_f32_e32 v88, v88
	v_mul_f32_e32 v86, v87, v86
	v_cvt_pk_bf16_f32 v86, v86, s0
	v_mov_b32_e32 v94, v92
	v_add_f32_e32 v88, 1.0, v88
	v_mov_b32_e32 v95, v96
	global_store_short v[112:113], v86, off offset:96
	v_lshlrev_b32_e32 v87, 16, v238
	v_lshlrev_b32_e32 v86, 16, v237
	v_rcp_f32_e32 v88, v88
	s_nop 0
	v_mul_f32_e32 v117, v88, v84
	s_waitcnt vmcnt(14)
	v_lshlrev_b32_e32 v84, 16, v178
	v_mul_f32_e32 v88, 0xbfb8aa3b, v84
	v_exp_f32_e32 v88, v88
	v_pk_add_f32 v[90:91], v[90:91], v[86:87]
	v_lshlrev_b32_e32 v87, 16, v236
	v_lshlrev_b32_e32 v86, 16, v235
	v_add_f32_e32 v88, 1.0, v88
	v_pk_mul_f32 v[112:113], v[90:91], v[90:91]
	v_pk_add_f32 v[86:87], v[94:95], v[86:87]
	v_rcp_f32_e32 v88, v88
	s_nop 0
	v_mul_f32_e32 v118, v88, v84
	s_waitcnt vmcnt(13)
	v_lshlrev_b32_e32 v84, 16, v125
	v_mul_f32_e32 v88, 0xbfb8aa3b, v84
	v_exp_f32_e32 v88, v88
	v_pk_mul_f32 v[94:95], v[86:87], v[86:87]
	v_add_f32_e32 v88, 1.0, v88
	s_nop 0
	v_rcp_f32_e32 v88, v88
	s_nop 0
	v_mul_f32_e32 v119, v88, v84
	s_waitcnt vmcnt(12)
	v_lshlrev_b32_e32 v84, 16, v124
	v_mul_f32_e32 v88, 0xbfb8aa3b, v84
	v_exp_f32_e32 v88, v88
	s_nop 0
	v_add_f32_e32 v88, 1.0, v88
	s_nop 0
	v_rcp_f32_e32 v88, v88
	s_nop 0
	v_mul_f32_e32 v123, v88, v84
	v_lshlrev_b32_e32 v115, 16, v234
	v_lshlrev_b32_e32 v114, 16, v233
	v_mov_b32_e32 v88, v85
	v_pk_add_f32 v[88:89], v[88:89], v[114:115]
	v_lshlrev_b32_e32 v85, 16, v232
	v_lshlrev_b32_e32 v84, 16, v99
	v_mov_b32_e32 v96, v93
	v_pk_mul_f32 v[114:115], v[88:89], v[88:89]
	v_pk_add_f32 v[84:85], v[96:97], v[84:85]
	v_mov_b32_e32 v96, v114
	v_pk_mul_f32 v[92:93], v[84:85], v[84:85]
	v_mov_b32_e32 v97, v112
	v_mov_b32_e32 v112, v115
	v_pk_add_f32 v[96:97], v[96:97], v[112:113]
	v_mov_b32_e32 v112, v92
	v_mov_b32_e32 v113, v94
	v_pk_add_f32 v[96:97], v[96:97], v[112:113]
	v_mov_b32_e32 v94, v93
	v_pk_add_f32 v[92:93], v[96:97], v[94:95]
	ds_bpermute_b32 v95, v231, v93
	ds_bpermute_b32 v94, v231, v92
	v_mov_b32_e32 v99, v74
	s_waitcnt lgkmcnt(0)
; __device__ __forceinline__ bf16_t f2bf(float f) { return (bf16_t)(cvt_pk_bf16(f, 0.f) & 0xffffu); }
; __device__ __forceinline__ float bf2f(bf16_t b) { return __uint_as_float(((unsigned)b) << 16); }
; __device__ __forceinline__ float siluf_(float x) { return x * sigmoidf_(x); }
; template <int MODE>
; __device__ __forceinline__ void hgrn_mfma(const Ctx& C, int l, int z, int b, int hd, int c, f32x4 (&Sacc)[4][4], float& dectot, unsigned char* wl, float lb) {
;     ...
;                 for (int r = 0; r < 4; ++r) { const int st = c * 128 + sc * 32 + 16 * tt + 4 * quad + r; const int tq = z ? 4095 - st : st;
;                     bf16_t* yp = ya + (size_t)(b * SEQ + tq) * 256 + hd * 64 + fr;
;                     float o[4]; float ss = 0.f;
; #pragma unroll
;                     for (int vt = 0; vt < 4; ++vt) { o[vt] = Oacc[tt][vt][r] + bf2f(tmpv[r][vt]); ss += o[vt] * o[vt]; }
;                     ss += __shfl_xor(ss, 1); ss += __shfl_xor(ss, 2); ss += __shfl_xor(ss, 4); ss += __shfl_xor(ss, 8);
;                     const float rs = rsqrtf(ss * (1.f / 64.f) + 1e-6f);
; #pragma unroll
;                     for (int vt = 0; vt < 4; ++vt) yp[16 * vt] = f2bf(o[vt] * rs * gnv[vt] * siluf_(bf2f(gtv[r][vt]))); }
	v_pk_add_f32 v[92:93], v[92:93], v[94:95]
	ds_bpermute_b32 v95, v230, v93
	ds_bpermute_b32 v94, v230, v92
	s_waitcnt lgkmcnt(0)
	v_pk_add_f32 v[92:93], v[92:93], v[94:95]
	ds_bpermute_b32 v95, v229, v93
	ds_bpermute_b32 v94, v229, v92
	s_waitcnt lgkmcnt(0)
	v_pk_add_f32 v[92:93], v[92:93], v[94:95]
	ds_bpermute_b32 v95, v64, v93
	ds_bpermute_b32 v94, v64, v92
	s_waitcnt lgkmcnt(0)
	v_pk_add_f32 v[92:93], v[92:93], v[94:95]
	s_nop 0
	v_pk_fma_f32 v[92:93], v[92:93], s[2:3], v[82:83] op_sel_hi:[1,0,0]
	s_nop 0
	v_mul_f32_e32 v94, 0x4b800000, v93
	v_cmp_gt_f32_e64 s[0:1], s54, v93
	v_cmp_gt_f32_e32 vcc, s54, v92
	s_nop 0
	v_cndmask_b32_e64 v93, v93, v94, s[0:1]
	v_rsq_f32_e32 v93, v93
	s_nop 0
	v_mul_f32_e32 v94, 0x45800000, v93
	v_cndmask_b32_e64 v93, v93, v94, s[0:1]
	v_mul_f32_e32 v86, v86, v93
	v_mul_f32_e32 v86, v211, v86
	v_mul_f32_e32 v86, v119, v86
	v_cvt_pk_bf16_f32 v86, v86, s0
	global_store_short v[110:111], v86, off offset:64
	v_mul_f32_e32 v86, v87, v93
	v_mul_f32_e32 v86, v212, v86
	v_mul_f32_e32 v86, v123, v86
	v_cvt_pk_bf16_f32 v86, v86, s0
	global_store_short v[110:111], v86, off offset:96
	v_mul_f32_e32 v86, 0x4b800000, v92
	v_mul_f32_e32 v90, v90, v93
	v_cndmask_b32_e32 v86, v92, v86, vcc
	v_mul_f32_e32 v90, v209, v90
	v_rsq_f32_e32 v86, v86
	v_mul_f32_e32 v90, v117, v90
	v_cvt_pk_bf16_f32 v90, v90, s0
	global_store_short v[110:111], v90, off
	v_mul_f32_e32 v90, v91, v93
	v_mul_f32_e32 v90, v210, v90
	v_mul_f32_e32 v87, 0x45800000, v86
	v_mul_f32_e32 v90, v118, v90
	v_cndmask_b32_e32 v86, v86, v87, vcc
	v_cvt_pk_bf16_f32 v90, v90, s0
	v_mul_f32_e32 v87, v88, v86
	s_waitcnt vmcnt(14)
	v_lshlrev_b32_e32 v88, 16, v122
	global_store_short v[110:111], v90, off offset:32
	v_mul_f32_e32 v90, 0xbfb8aa3b, v88
	v_exp_f32_e32 v90, v90
	v_mul_f32_e32 v87, v209, v87
	v_mul_f32_e32 v84, v84, v86
	v_mul_f32_e32 v84, v211, v84
	v_add_f32_e32 v90, 1.0, v90
	s_nop 0
	v_rcp_f32_e32 v90, v90
	s_nop 0
	v_mul_f32_e32 v88, v90, v88
	v_mul_f32_e32 v87, v88, v87
	v_cvt_pk_bf16_f32 v87, v87, s0
	s_waitcnt vmcnt(14)
	v_lshlrev_b32_e32 v88, 16, v121
	global_store_short v[100:101], v87, off
	v_mul_f32_e32 v87, v89, v86
	v_mul_f32_e32 v89, 0xbfb8aa3b, v88
	v_exp_f32_e32 v89, v89
	v_mul_f32_e32 v87, v210, v87
	v_add_f32_e32 v89, 1.0, v89
	s_nop 0
	v_rcp_f32_e32 v89, v89
	s_nop 0
	v_mul_f32_e32 v88, v89, v88
	v_mul_f32_e32 v87, v88, v87
	v_cvt_pk_bf16_f32 v87, v87, s0
	global_store_short v[100:101], v87, off offset:32
	s_waitcnt vmcnt(15)
	v_lshlrev_b32_e32 v87, 16, v120
	v_mul_f32_e32 v88, 0xbfb8aa3b, v87
	v_exp_f32_e32 v88, v88
	s_nop 0
	v_add_f32_e32 v88, 1.0, v88
	s_nop 0
	v_rcp_f32_e32 v88, v88
	s_nop 0
	v_mul_f32_e32 v87, v88, v87
	v_mul_f32_e32 v84, v87, v84
	v_cvt_pk_bf16_f32 v84, v84, s0
	global_store_short v[100:101], v84, off offset:64
	v_mul_f32_e32 v84, v85, v86
	s_waitcnt vmcnt(15)
	v_lshlrev_b32_e32 v85, 16, v116
	v_mul_f32_e32 v86, 0xbfb8aa3b, v85
	v_exp_f32_e32 v86, v86
	v_mul_f32_e32 v84, v212, v84
	v_or_b32_e32 v92, 19, v98
	v_ashrrev_i32_e32 v93, 31, v92
	v_add_f32_e32 v86, 1.0, v86
	s_nop 0
	v_rcp_f32_e32 v86, v86
	s_nop 0
	v_mul_f32_e32 v85, v86, v85
	v_mul_f32_e32 v84, v85, v84
	v_cvt_pk_bf16_f32 v84, v84, s0
	global_store_short v[100:101], v84, off offset:96
	v_or_b32_e32 v84, 16, v98
	v_ashrrev_i32_e32 v85, 31, v84
	v_lshlrev_b64 v[86:87], 9, v[84:85]
	v_lshl_add_u64 v[90:91], v[106:107], 0, v[86:87]
	global_load_ushort v94, v[90:91], off
	global_load_ushort v95, v[90:91], off offset:32
	global_load_ushort v114, v[90:91], off offset:64
	global_load_ushort v115, v[90:91], off offset:96
	v_mad_i64_i32 v[110:111], s[0:1], v84, s62, v[108:109]
	v_or_b32_e32 v84, 17, v98
	v_ashrrev_i32_e32 v85, 31, v84
	v_lshlrev_b64 v[86:87], 9, v[84:85]
	v_mad_i64_i32 v[100:101], s[0:1], v84, s62, v[108:109]
	v_or_b32_e32 v84, 18, v98
	v_ashrrev_i32_e32 v85, 31, v84
	v_lshl_add_u64 v[88:89], v[106:107], 0, v[86:87]
	v_lshlrev_b64 v[86:87], 9, v[84:85]
	v_mad_i64_i32 v[96:97], s[0:1], v84, s62, v[108:109]
	v_lshlrev_b64 v[84:85], 9, v[92:93]
	v_lshl_add_u64 v[86:87], v[106:107], 0, v[86:87]
	v_lshl_add_u64 v[84:85], v[106:107], 0, v[84:85]
	v_mov_b32_e32 v98, v70
	global_load_ushort v127, v[88:89], off
	global_load_ushort v128, v[88:89], off offset:32
	global_load_ushort v125, v[88:89], off offset:64
	global_load_ushort v126, v[88:89], off offset:96
	global_load_ushort v122, v[86:87], off
	global_load_ushort v123, v[86:87], off offset:32
	global_load_ushort v120, v[86:87], off offset:64
	global_load_ushort v121, v[86:87], off offset:96
	global_load_ushort v118, v[84:85], off
	global_load_ushort v119, v[84:85], off offset:32
	global_load_ushort v116, v[84:85], off offset:64
	global_load_ushort v117, v[84:85], off offset:96
	v_mad_i64_i32 v[92:93], s[0:1], v92, s62, v[108:109]
	s_waitcnt vmcnt(15)
	v_lshlrev_b32_e32 v94, 16, v94
	s_waitcnt vmcnt(14)
	v_lshlrev_b32_e32 v95, 16, v95
	v_pk_add_f32 v[98:99], v[98:99], v[94:95]
	s_waitcnt vmcnt(12)
	v_lshlrev_b32_e32 v95, 16, v115
	v_mov_b32_e32 v115, v60
	global_load_ushort v60, v[110:111], off offset:2048
	v_lshlrev_b32_e32 v94, 16, v114
	v_mov_b32_e32 v114, v78
	v_pk_mul_f32 v[112:113], v[98:99], v[98:99]
	v_pk_add_f32 v[94:95], v[114:115], v[94:95]
	s_waitcnt vmcnt(0)
	v_lshlrev_b32_e32 v60, 16, v60
	v_mul_f32_e32 v70, 0xbfb8aa3b, v60
	v_exp_f32_e32 v70, v70
	v_pk_mul_f32 v[114:115], v[94:95], v[94:95]
	v_add_f32_e32 v70, 1.0, v70
	s_nop 0
	v_rcp_f32_e32 v70, v70
	s_nop 0
	v_mul_f32_e32 v129, v70, v60
	global_load_ushort v60, v[110:111], off offset:2080
	s_waitcnt vmcnt(0)
; __device__ __forceinline__ bf16_t f2bf(float f) { return (bf16_t)(cvt_pk_bf16(f, 0.f) & 0xffffu); }
; __device__ __forceinline__ float bf2f(bf16_t b) { return __uint_as_float(((unsigned)b) << 16); }
; __device__ __forceinline__ float siluf_(float x) { return x * sigmoidf_(x); }
; template <int MODE>
; __device__ __forceinline__ void hgrn_mfma(const Ctx& C, int l, int z, int b, int hd, int c, f32x4 (&Sacc)[4][4], float& dectot, unsigned char* wl, float lb) {
;     ...
;                 for (int r = 0; r < 4; ++r) { const int st = c * 128 + sc * 32 + 16 * tt + 4 * quad + r; const int tq = z ? 4095 - st : st;
;                     const size_t tok = (size_t)(b * SEQ + tq); const bf16_t* yp = ya + tok * 256 + hd * 64 + fr; const bf16_t* gp = pa + tok * 1280 + 1024 + hd * 64 + fr;
; #pragma unroll
;                     for (int vt = 0; vt < 4; ++vt) { tmpv[r][vt] = yp[16 * vt]; gtv[r][vt] = gp[16 * vt]; } }
; #pragma unroll
;                 for (int r = 0; r < 4; ++r) { const int st = c * 128 + sc * 32 + 16 * tt + 4 * quad + r; const int tq = z ? 4095 - st : st;
;                     bf16_t* yp = ya + (size_t)(b * SEQ + tq) * 256 + hd * 64 + fr;
;                     float o[4]; float ss = 0.f;
; #pragma unroll
;                     for (int vt = 0; vt < 4; ++vt) { o[vt] = Oacc[tt][vt][r] + bf2f(tmpv[r][vt]); ss += o[vt] * o[vt]; }
;                     ss += __shfl_xor(ss, 1); ss += __shfl_xor(ss, 2); ss += __shfl_xor(ss, 4); ss += __shfl_xor(ss, 8);
;                     const float rs = rsqrtf(ss * (1.f / 64.f) + 1e-6f);
; #pragma unroll
;                     for (int vt = 0; vt < 4; ++vt) yp[16 * vt] = f2bf(o[vt] * rs * gnv[vt] * siluf_(bf2f(gtv[r][vt]))); }
	v_lshlrev_b32_e32 v60, 16, v60
	v_mul_f32_e32 v70, 0xbfb8aa3b, v60
	v_exp_f32_e32 v70, v70
	s_nop 0
	v_add_f32_e32 v70, 1.0, v70
	s_nop 0
	v_rcp_f32_e32 v70, v70
	s_nop 0
	v_mul_f32_e32 v78, v70, v60
	global_load_ushort v60, v[110:111], off offset:2112
	s_waitcnt vmcnt(0)
	v_lshlrev_b32_e32 v60, 16, v60
	v_mul_f32_e32 v70, 0xbfb8aa3b, v60
	v_exp_f32_e32 v70, v70
	s_nop 0
	v_add_f32_e32 v70, 1.0, v70
	s_nop 0
	v_rcp_f32_e32 v70, v70
	s_nop 0
	v_mul_f32_e32 v124, v70, v60
	global_load_ushort v60, v[110:111], off offset:2144
	s_waitcnt vmcnt(0)
	v_lshlrev_b32_e32 v60, 16, v60
	v_mul_f32_e32 v70, 0xbfb8aa3b, v60
	v_exp_f32_e32 v70, v70
	s_nop 0
	v_add_f32_e32 v70, 1.0, v70
	s_nop 0
	v_rcp_f32_e32 v70, v70
	v_lshlrev_b32_e32 v131, 16, v128
	v_lshlrev_b32_e32 v130, 16, v127
	v_mov_b32_e32 v74, v71
	v_mul_f32_e32 v110, v70, v60
	v_pk_add_f32 v[70:71], v[74:75], v[130:131]
	v_lshlrev_b32_e32 v127, 16, v126
	v_lshlrev_b32_e32 v126, 16, v125
	v_mov_b32_e32 v60, v79
	v_pk_mul_f32 v[74:75], v[70:71], v[70:71]
	v_pk_add_f32 v[60:61], v[60:61], v[126:127]
	v_mov_b32_e32 v130, v74
	v_pk_mul_f32 v[126:127], v[60:61], v[60:61]
	v_mov_b32_e32 v131, v112
	v_mov_b32_e32 v112, v75
	v_pk_add_f32 v[74:75], v[130:131], v[112:113]
	v_mov_b32_e32 v112, v126
	v_mov_b32_e32 v113, v114
	v_pk_add_f32 v[74:75], v[74:75], v[112:113]
	v_mov_b32_e32 v114, v127
	v_pk_add_f32 v[74:75], v[74:75], v[114:115]
	ds_bpermute_b32 v113, v231, v75
	ds_bpermute_b32 v112, v231, v74
	s_waitcnt lgkmcnt(0)
	v_pk_add_f32 v[74:75], v[74:75], v[112:113]
	ds_bpermute_b32 v113, v230, v75
	ds_bpermute_b32 v112, v230, v74
	s_waitcnt lgkmcnt(0)
	v_pk_add_f32 v[74:75], v[74:75], v[112:113]
	ds_bpermute_b32 v113, v229, v75
	ds_bpermute_b32 v112, v229, v74
	s_waitcnt lgkmcnt(0)
	v_pk_add_f32 v[74:75], v[74:75], v[112:113]
	ds_bpermute_b32 v113, v64, v75
	ds_bpermute_b32 v112, v64, v74
	s_waitcnt lgkmcnt(0)
	v_pk_add_f32 v[74:75], v[74:75], v[112:113]
	s_nop 0
	v_pk_fma_f32 v[74:75], v[74:75], s[2:3], v[82:83] op_sel_hi:[1,0,0]
	s_nop 0
	v_mul_f32_e32 v79, 0x4b800000, v75
	v_cmp_gt_f32_e64 s[0:1], s54, v75
	v_cmp_gt_f32_e32 vcc, s54, v74
	s_nop 0
	v_cndmask_b32_e64 v75, v75, v79, s[0:1]
	v_rsq_f32_e32 v75, v75
	s_nop 0
	v_mul_f32_e32 v79, 0x45800000, v75
	v_cndmask_b32_e64 v75, v75, v79, s[0:1]
	v_mul_f32_e32 v79, v98, v75
	global_load_ushort v111, v[100:101], off offset:2048
	global_load_ushort v112, v[100:101], off offset:2080
	global_load_ushort v113, v[100:101], off offset:2112
	global_load_ushort v114, v[100:101], off offset:2144
	global_load_ushort v115, v[96:97], off offset:2048
	global_load_ushort v125, v[96:97], off offset:2080
	s_nop 0
	global_load_ushort v101, v[96:97], off offset:2112
	global_load_ushort v100, v[96:97], off offset:2144
	global_load_ushort v98, v[92:93], off offset:2048
	s_nop 0
	global_load_ushort v97, v[92:93], off offset:2080
	global_load_ushort v96, v[92:93], off offset:2112
	s_nop 0
	global_load_ushort v92, v[92:93], off offset:2144
	v_mul_f32_e32 v79, v209, v79
	v_mul_f32_e32 v79, v129, v79
	v_cvt_pk_bf16_f32 v79, v79, s0
	global_store_short v[90:91], v79, off
	v_mul_f32_e32 v79, v99, v75
	v_mul_f32_e32 v79, v210, v79
	v_mul_f32_e32 v78, v78, v79
	v_cvt_pk_bf16_f32 v78, v78, s0
	global_store_short v[90:91], v78, off offset:32
	v_mul_f32_e32 v78, v94, v75
	v_mul_f32_e32 v75, v95, v75
	v_mul_f32_e32 v75, v212, v75
	v_mul_f32_e32 v75, v110, v75
	v_cvt_pk_bf16_f32 v75, v75, s0
	global_store_short v[90:91], v75, off offset:96
	v_mul_f32_e32 v75, 0x4b800000, v74
	v_cndmask_b32_e32 v74, v74, v75, vcc
	v_rsq_f32_e32 v74, v74
	v_mul_f32_e32 v78, v211, v78
	v_mul_f32_e32 v78, v124, v78
	v_cvt_pk_bf16_f32 v78, v78, s0
	v_mul_f32_e32 v75, 0x45800000, v74
	v_cndmask_b32_e32 v74, v74, v75, vcc
	global_store_short v[90:91], v78, off offset:64
	v_mul_f32_e32 v70, v70, v74
	v_mul_f32_e32 v70, v209, v70
	v_mul_f32_e32 v60, v60, v74
	v_mul_f32_e32 v60, v211, v60
	s_waitcnt vmcnt(15)
	v_lshlrev_b32_e32 v75, 16, v111
	v_mul_f32_e32 v78, 0xbfb8aa3b, v75
	v_exp_f32_e32 v78, v78
	s_nop 0
	v_add_f32_e32 v78, 1.0, v78
	s_nop 0
	v_rcp_f32_e32 v78, v78
	s_nop 0
	v_mul_f32_e32 v75, v78, v75
	v_mul_f32_e32 v70, v75, v70
	v_cvt_pk_bf16_f32 v70, v70, s0
	global_store_short v[88:89], v70, off
	v_mul_f32_e32 v70, v71, v74
	s_waitcnt vmcnt(15)
	v_lshlrev_b32_e32 v71, 16, v112
	v_mul_f32_e32 v75, 0xbfb8aa3b, v71
	v_exp_f32_e32 v75, v75
	v_mul_f32_e32 v70, v210, v70
	v_add_f32_e32 v75, 1.0, v75
	s_nop 0
	v_rcp_f32_e32 v75, v75
	s_nop 0
	v_mul_f32_e32 v71, v75, v71
	v_mul_f32_e32 v70, v71, v70
	v_cvt_pk_bf16_f32 v70, v70, s0
	global_store_short v[88:89], v70, off offset:32
	s_waitcnt vmcnt(15)
	v_lshlrev_b32_e32 v70, 16, v113
	v_mul_f32_e32 v71, 0xbfb8aa3b, v70
	v_exp_f32_e32 v71, v71
	s_nop 0
	v_add_f32_e32 v71, 1.0, v71
	s_nop 0
	v_rcp_f32_e32 v71, v71
	s_nop 0
	v_mul_f32_e32 v70, v71, v70
	v_mul_f32_e32 v60, v70, v60
	v_cvt_pk_bf16_f32 v60, v60, s0
	global_store_short v[88:89], v60, off offset:64
	v_mul_f32_e32 v60, v61, v74
	s_waitcnt vmcnt(15)
	v_lshlrev_b32_e32 v61, 16, v114
	v_mul_f32_e32 v70, 0xbfb8aa3b, v61
	v_exp_f32_e32 v70, v70
	v_mul_f32_e32 v60, v212, v60
	v_add_f32_e32 v70, 1.0, v70
	s_nop 0
	v_rcp_f32_e32 v70, v70
	v_mov_b32_e32 v75, v62
	s_waitcnt vmcnt(14)
; __device__ __forceinline__ bf16_t f2bf(float f) { return (bf16_t)(cvt_pk_bf16(f, 0.f) & 0xffffu); }
; __device__ __forceinline__ float bf2f(bf16_t b) { return __uint_as_float(((unsigned)b) << 16); }
; __device__ __forceinline__ float siluf_(float x) { return x * sigmoidf_(x); }
; __device__ __forceinline__ void wave_lds_fence() { asm volatile("s_waitcnt lgkmcnt(0)" ::: "memory"); __builtin_amdgcn_wave_barrier(); }
; template <int MODE>
; __device__ __forceinline__ void hgrn_mfma(const Ctx& C, int l, int z, int b, int hd, int c, f32x4 (&Sacc)[4][4], float& dectot, unsigned char* wl, float lb) {
;     ...
;         if (MODE == 2) {
; #pragma unroll
;             for (int tt = 0; tt < 2; ++tt) {
;                 bf16_t tmpv[4][4], gtv[4][4];
; #pragma unroll
;                 for (int r = 0; r < 4; ++r) { const int st = c * 128 + sc * 32 + 16 * tt + 4 * quad + r; const int tq = z ? 4095 - st : st;
;                     const size_t tok = (size_t)(b * SEQ + tq); const bf16_t* yp = ya + tok * 256 + hd * 64 + fr; const bf16_t* gp = pa + tok * 1280 + 1024 + hd * 64 + fr;
; #pragma unroll
;                     for (int vt = 0; vt < 4; ++vt) { tmpv[r][vt] = yp[16 * vt]; gtv[r][vt] = gp[16 * vt]; } }
; #pragma unroll
;                 for (int r = 0; r < 4; ++r) { const int st = c * 128 + sc * 32 + 16 * tt + 4 * quad + r; const int tq = z ? 4095 - st : st;
;                     bf16_t* yp = ya + (size_t)(b * SEQ + tq) * 256 + hd * 64 + fr;
;                     float o[4]; float ss = 0.f;
; #pragma unroll
;                     for (int vt = 0; vt < 4; ++vt) { o[vt] = Oacc[tt][vt][r] + bf2f(tmpv[r][vt]); ss += o[vt] * o[vt]; }
;                     ss += __shfl_xor(ss, 1); ss += __shfl_xor(ss, 2); ss += __shfl_xor(ss, 4); ss += __shfl_xor(ss, 8);
;                     const float rs = rsqrtf(ss * (1.f / 64.f) + 1e-6f);
; #pragma unroll
;                     for (int vt = 0; vt < 4; ++vt) yp[16 * vt] = f2bf(o[vt] * rs * gnv[vt] * siluf_(bf2f(gtv[r][vt]))); }
;                 asm volatile("" ::: "memory");
;             }
;         }
;         wave_lds_fence();
;     }
	v_lshlrev_b32_e32 v62, 16, v115
	v_mul_f32_e32 v61, v70, v61
	v_mov_b32_e32 v70, v72
	v_mul_f32_e32 v72, 0xbfb8aa3b, v62
	v_exp_f32_e32 v72, v72
	v_mul_f32_e32 v60, v61, v60
	v_cvt_pk_bf16_f32 v60, v60, s0
	v_mov_b32_e32 v71, v76
	v_add_f32_e32 v72, 1.0, v72
	v_mov_b32_e32 v74, v80
	global_store_short v[88:89], v60, off offset:96
	v_lshlrev_b32_e32 v61, 16, v123
	v_lshlrev_b32_e32 v60, 16, v122
	v_rcp_f32_e32 v72, v72
	s_nop 0
	v_mul_f32_e32 v90, v72, v62
	s_waitcnt vmcnt(14)
	v_lshlrev_b32_e32 v62, 16, v125
	v_mul_f32_e32 v72, 0xbfb8aa3b, v62
	v_exp_f32_e32 v72, v72
	v_pk_add_f32 v[70:71], v[70:71], v[60:61]
	v_lshlrev_b32_e32 v61, 16, v121
	v_lshlrev_b32_e32 v60, 16, v120
	v_add_f32_e32 v72, 1.0, v72
	v_pk_mul_f32 v[78:79], v[70:71], v[70:71]
	v_pk_add_f32 v[60:61], v[74:75], v[60:61]
	v_rcp_f32_e32 v72, v72
	s_nop 0
	v_mul_f32_e32 v91, v72, v62
	s_waitcnt vmcnt(13)
	v_lshlrev_b32_e32 v62, 16, v101
	v_mul_f32_e32 v72, 0xbfb8aa3b, v62
	v_exp_f32_e32 v72, v72
	v_pk_mul_f32 v[74:75], v[60:61], v[60:61]
	v_add_f32_e32 v72, 1.0, v72
	s_nop 0
	v_rcp_f32_e32 v72, v72
	s_nop 0
	v_mul_f32_e32 v93, v72, v62
	s_waitcnt vmcnt(12)
	v_lshlrev_b32_e32 v62, 16, v100
	v_mul_f32_e32 v72, 0xbfb8aa3b, v62
	v_exp_f32_e32 v72, v72
	s_nop 0
	v_add_f32_e32 v72, 1.0, v72
	s_nop 0
	v_rcp_f32_e32 v72, v72
	v_lshlrev_b32_e32 v89, 16, v119
	v_lshlrev_b32_e32 v88, 16, v118
	v_mov_b32_e32 v76, v73
	v_mul_f32_e32 v94, v72, v62
	v_pk_add_f32 v[72:73], v[76:77], v[88:89]
	v_lshlrev_b32_e32 v89, 16, v117
	v_lshlrev_b32_e32 v88, 16, v116
	v_mov_b32_e32 v62, v81
	v_pk_mul_f32 v[76:77], v[72:73], v[72:73]
	v_pk_add_f32 v[62:63], v[62:63], v[88:89]
	v_mov_b32_e32 v88, v76
	v_pk_mul_f32 v[80:81], v[62:63], v[62:63]
	v_mov_b32_e32 v89, v78
	v_mov_b32_e32 v78, v77
	v_pk_add_f32 v[76:77], v[88:89], v[78:79]
	v_mov_b32_e32 v78, v80
	v_mov_b32_e32 v79, v74
	v_pk_add_f32 v[76:77], v[76:77], v[78:79]
	v_mov_b32_e32 v74, v81
	v_pk_add_f32 v[74:75], v[76:77], v[74:75]
	ds_bpermute_b32 v77, v231, v75
	ds_bpermute_b32 v76, v231, v74
	s_waitcnt lgkmcnt(0)
	v_pk_add_f32 v[74:75], v[74:75], v[76:77]
	ds_bpermute_b32 v77, v230, v75
	ds_bpermute_b32 v76, v230, v74
	s_waitcnt lgkmcnt(0)
	v_pk_add_f32 v[74:75], v[74:75], v[76:77]
	ds_bpermute_b32 v77, v229, v75
	ds_bpermute_b32 v76, v229, v74
	s_waitcnt lgkmcnt(0)
	v_pk_add_f32 v[74:75], v[74:75], v[76:77]
	ds_bpermute_b32 v77, v64, v75
	ds_bpermute_b32 v76, v64, v74
	s_waitcnt lgkmcnt(0)
	v_pk_add_f32 v[74:75], v[74:75], v[76:77]
	s_nop 0
	v_pk_fma_f32 v[74:75], v[74:75], s[2:3], v[82:83] op_sel_hi:[1,0,0]
	s_nop 0
	v_mul_f32_e32 v64, 0x4b800000, v75
	v_cmp_gt_f32_e64 s[0:1], s54, v75
	v_cmp_gt_f32_e32 vcc, s54, v74
	s_nop 0
	v_cndmask_b32_e64 v64, v75, v64, s[0:1]
	v_rsq_f32_e32 v64, v64
	s_nop 0
	v_mul_f32_e32 v75, 0x45800000, v64
	v_cndmask_b32_e64 v64, v64, v75, s[0:1]
	v_mul_f32_e32 v60, v60, v64
	v_mul_f32_e32 v70, v70, v64
	v_mul_f32_e32 v60, v211, v60
	v_mul_f32_e32 v70, v209, v70
	v_mul_f32_e32 v60, v93, v60
	v_mul_f32_e32 v70, v90, v70
	v_cvt_pk_bf16_f32 v60, v60, s0
	v_cvt_pk_bf16_f32 v70, v70, s0
	global_store_short v[86:87], v60, off offset:64
	v_mul_f32_e32 v60, v61, v64
	global_store_short v[86:87], v70, off
	v_mul_f32_e32 v70, v71, v64
	v_mul_f32_e32 v60, v212, v60
	v_mul_f32_e32 v70, v210, v70
	v_mul_f32_e32 v60, v94, v60
	v_mul_f32_e32 v70, v91, v70
	v_cvt_pk_bf16_f32 v60, v60, s0
	v_cvt_pk_bf16_f32 v70, v70, s0
	global_store_short v[86:87], v60, off offset:96
	v_mul_f32_e32 v60, 0x4b800000, v74
	s_waitcnt vmcnt(14)
	v_lshlrev_b32_e32 v64, 16, v98
	global_store_short v[86:87], v70, off offset:32
	v_cndmask_b32_e32 v60, v74, v60, vcc
	v_mul_f32_e32 v70, 0xbfb8aa3b, v64
	v_rsq_f32_e32 v60, v60
	v_exp_f32_e32 v70, v70
	v_mul_f32_e32 v61, 0x45800000, v60
	v_add_f32_e32 v70, 1.0, v70
	v_cndmask_b32_e32 v60, v60, v61, vcc
	v_mul_f32_e32 v61, v72, v60
	v_mul_f32_e32 v61, v209, v61
	v_rcp_f32_e32 v70, v70
	s_nop 0
	v_mul_f32_e32 v64, v70, v64
	v_mul_f32_e32 v61, v64, v61
	s_waitcnt vmcnt(14)
	v_lshlrev_b32_e32 v64, 16, v97
	v_mul_f32_e32 v70, 0xbfb8aa3b, v64
	v_exp_f32_e32 v70, v70
	v_cvt_pk_bf16_f32 v61, v61, s0
	global_store_short v[84:85], v61, off
	v_mul_f32_e32 v61, v73, v60
	v_add_f32_e32 v70, 1.0, v70
	v_mul_f32_e32 v61, v210, v61
	v_rcp_f32_e32 v70, v70
	s_nop 0
	v_mul_f32_e32 v64, v70, v64
	v_mul_f32_e32 v61, v64, v61
	v_cvt_pk_bf16_f32 v61, v61, s0
	global_store_short v[84:85], v61, off offset:32
	v_mul_f32_e32 v61, v62, v60
	s_waitcnt vmcnt(15)
	v_lshlrev_b32_e32 v62, 16, v96
	v_mul_f32_e32 v64, 0xbfb8aa3b, v62
	v_exp_f32_e32 v64, v64
	v_mul_f32_e32 v61, v211, v61
	v_mul_f32_e32 v60, v63, v60
	v_mul_f32_e32 v60, v212, v60
	v_add_f32_e32 v64, 1.0, v64
	s_nop 0
	v_rcp_f32_e32 v64, v64
	s_nop 0
	v_mul_f32_e32 v62, v64, v62
	v_mul_f32_e32 v61, v62, v61
	v_cvt_pk_bf16_f32 v61, v61, s0
	global_store_short v[84:85], v61, off offset:64
	s_waitcnt vmcnt(15)
	v_lshlrev_b32_e32 v61, 16, v92
	v_mul_f32_e32 v62, 0xbfb8aa3b, v61
	v_exp_f32_e32 v62, v62
	s_nop 0
	v_add_f32_e32 v62, 1.0, v62
	s_nop 0
	v_rcp_f32_e32 v62, v62
	s_nop 0
	v_mul_f32_e32 v61, v62, v61
	v_mul_f32_e32 v60, v61, v60
	v_cvt_pk_bf16_f32 v60, v60, s0
	global_store_short v[84:85], v60, off offset:96
	s_waitcnt lgkmcnt(0)
	s_cbranch_scc0 .LBB0_742
	v_readlane_b32 s0, v254, 20
	s_add_i32 s73, s73, s0
	s_cmpk_gt_i32 s73, 0x3ff
	v_readlane_b32 s1, v254, 21
	s_cbranch_scc0 .LBB0_739
